# P1 and gates epilogues rewritten: per-wave LDS transpose to full-row 16B stores, batched rope table loads; gates sigmoid uses f32 v_exp+v_rcp; scal_unit loop prefetch
# speedup vs baseline: 1.1273x; 1.0303x over previous
; DI int otid() { int t = threadIdx.x & 255; asm volatile("" : "+v"(t)); return t; }
; DI void scal_unit(const Params& p, int l, int unit, float* lds) {
;     ...
;   const int t = otid(), lane = t & 63, w = t >> 6, r = lane & 15, q = lane >> 4;
;   f4v acc[2];
;   acc[0] = (f4v){0.f, 0.f, 0.f, 0.f}; acc[1] = (f4v){0.f, 0.f, 0.f, 0.f};
;   const int t0 = unit * 64;
;   for (int k0 = 0; k0 < 1024; k0 += 64) {
;     __syncthreads();
; #pragma unroll
;     for (int i = 0; i < 4; ++i) { int e = t + 256 * i; int rr = e >> 4, c4 = (e & 15) * 4; *(f4v*)&xt[rr * 68 + c4] = *(const f4v*)&xs[(size_t)(t0 + rr) * DM + k0 + c4]; }
; #pragma unroll
;     for (int i = 0; i < 8; ++i) { int e = t + 256 * i; int kk = e >> 5, c = e & 31; int col = (c < 16) ? (5120 + c) : (8464 + (c - 16)); wt[kk * 32 + c] = win[(size_t)(k0 + kk) * NIN + col]; }
;     __syncthreads();
.LBB0_95:
	v_mov_b32_e32 v2, v182
	s_movk_i32 s8, 0x110
	v_ashrrev_i32_e32 v6, 2, v2
	v_bfe_u32 v11, v2, 4, 2
	v_and_b32_e32 v39, -16, v6
	v_bfi_b32 v6, -16, v6, v2
	v_mul_lo_u32 v6, v6, s8
	v_lshlrev_b32_e32 v7, 2, v11
	v_add3_u32 v40, v183, v6, v7
	v_ashrrev_i32_e32 v6, 4, v2
	v_lshlrev_b32_e32 v8, 4, v2
	v_mul_lo_u32 v7, v6, s8
	v_and_b32_e32 v8, 0xf0, v8
	v_add3_u32 v41, v183, v7, v8
	v_add_u32_e32 v7, 0x100, v2
	v_ashrrev_i32_e32 v9, 4, v7
	v_mul_lo_u32 v10, v9, s8
	v_add3_u32 v42, v183, v10, v8
	v_add_u32_e32 v10, 0x200, v2
	v_ashrrev_i32_e32 v34, 4, v10
	v_mul_lo_u32 v12, v34, s8
	v_add3_u32 v43, v183, v12, v8
	v_add_u32_e32 v12, 0x300, v2
	v_ashrrev_i32_e32 v36, 4, v12
	v_ashrrev_i32_e32 v24, 5, v10
	v_add_u32_e32 v10, 0x400, v2
	v_and_b32_e32 v3, 31, v2
	v_mul_lo_u32 v13, v36, s8
	v_ashrrev_i32_e32 v20, 5, v10
	v_add_u32_e32 v10, 0x500, v2
	v_and_b32_e32 v4, 15, v2
	v_cmp_gt_u32_e32 vcc, 16, v3
	v_add3_u32 v44, v183, v13, v8
	v_ashrrev_i32_e32 v8, 5, v2
	v_lshl_add_u32 v45, v2, 2, v183
	v_ashrrev_i32_e32 v18, 5, v10
	v_add_u32_e32 v10, 0x600, v2
	v_add_u32_e32 v2, 0x700, v2
	v_cndmask_b32_e32 v5, v190, v191, vcc
	v_ashrrev_i32_e32 v16, 5, v10
	v_ashrrev_i32_e32 v14, 5, v2
	v_lshlrev_b32_e32 v2, 7, v11
	v_lshlrev_b32_e32 v10, 2, v4
	v_readlane_b32 s8, v255, 28
	v_add3_u32 v46, v183, v2, v10
	v_or_b32_e32 v2, v5, v3
	v_readlane_b32 s9, v255, 29
	v_ashrrev_i32_e32 v7, 5, v7
	v_ashrrev_i32_e32 v22, 5, v12
	v_lshlrev_b32_e32 v12, 2, v2
	v_mov_b64_e32 v[2:3], s[8:9]
	s_mov_b32 s16, 0x9080
	v_mad_i64_i32 v[14:15], s[8:9], v14, s16, v[2:3]
	v_mad_i64_i32 v[16:17], s[8:9], v16, s16, v[2:3]
	v_mad_i64_i32 v[18:19], s[8:9], v18, s16, v[2:3]
	v_mad_i64_i32 v[20:21], s[8:9], v20, s16, v[2:3]
	v_mad_i64_i32 v[22:23], s[8:9], v22, s16, v[2:3]
	v_mad_i64_i32 v[24:25], s[8:9], v24, s16, v[2:3]
	v_mad_i64_i32 v[26:27], s[8:9], v7, s16, v[2:3]
	v_mad_i64_i32 v[28:29], s[8:9], v8, s16, v[2:3]
	v_add_u32_e32 v2, v6, v38
	v_ashrrev_i32_e32 v3, 31, v2
	v_lshlrev_b64 v[2:3], 12, v[2:3]
	v_lshlrev_b32_e32 v4, 4, v4
	v_or_b32_e32 v2, v2, v4
	v_lshl_add_u64 v[30:31], s[4:5], 0, v[2:3]
	v_add_u32_e32 v2, v9, v38
	v_ashrrev_i32_e32 v3, 31, v2
	v_lshlrev_b64 v[2:3], 12, v[2:3]
	v_or_b32_e32 v2, v2, v4
	v_lshl_add_u64 v[32:33], s[4:5], 0, v[2:3]
	v_add_u32_e32 v2, v34, v38
	v_ashrrev_i32_e32 v3, 31, v2
	v_lshlrev_b64 v[2:3], 12, v[2:3]
	v_or_b32_e32 v2, v2, v4
	v_lshl_add_u64 v[34:35], s[4:5], 0, v[2:3]
	v_add_u32_e32 v2, v36, v38
	v_ashrrev_i32_e32 v3, 31, v2
	v_lshlrev_b64 v[2:3], 12, v[2:3]
	v_or_b32_e32 v2, v2, v4
	v_lshl_add_u64 v[36:37], s[4:5], 0, v[2:3]
	v_mov_b32_e32 v2, 0
	v_mov_b32_e32 v13, v0
	s_movk_i32 s8, 0xffc0
	v_mov_b32_e32 v3, v2
	v_mov_b32_e32 v4, v2
	v_mov_b32_e32 v5, v2
	v_mov_b32_e32 v6, v2
	v_mov_b32_e32 v7, v2
	v_mov_b32_e32 v8, v2
	v_mov_b32_e32 v9, v2
	v_lshl_add_u64 v[64:65], v[28:29], 0, v[12:13]
	v_lshl_add_u64 v[66:67], v[26:27], 0, v[12:13]
	v_lshl_add_u64 v[68:69], v[24:25], 0, v[12:13]
	v_lshl_add_u64 v[70:71], v[22:23], 0, v[12:13]
	global_load_dwordx4 v[48:51], v[30:31], off
	global_load_dwordx4 v[52:55], v[32:33], off
	global_load_dwordx4 v[56:59], v[34:35], off
	global_load_dwordx4 v[60:63], v[36:37], off
	v_lshl_add_u64 v[72:73], v[20:21], 0, v[12:13]
	v_lshl_add_u64 v[74:75], v[18:19], 0, v[12:13]
	v_lshl_add_u64 v[76:77], v[16:17], 0, v[12:13]
	v_lshl_add_u64 v[78:79], v[14:15], 0, v[12:13]
	global_load_dword v64, v[64:65], off
	s_nop 0
	global_load_dword v65, v[66:67], off
	s_nop 0
	global_load_dword v66, v[68:69], off
	global_load_dword v67, v[70:71], off
	s_nop 0
	global_load_dword v68, v[72:73], off
	global_load_dword v69, v[74:75], off
	global_load_dword v70, v[76:77], off
	global_load_dword v71, v[78:79], off
	v_lshl_add_u64 v[14:15], v[14:15], 0, s[14:15]
	v_lshl_add_u64 v[16:17], v[16:17], 0, s[14:15]
	v_lshl_add_u64 v[18:19], v[18:19], 0, s[14:15]
	v_lshl_add_u64 v[20:21], v[20:21], 0, s[14:15]
	v_lshl_add_u64 v[22:23], v[22:23], 0, s[14:15]
	v_lshl_add_u64 v[24:25], v[24:25], 0, s[14:15]
	v_lshl_add_u64 v[26:27], v[26:27], 0, s[14:15]
	v_lshl_add_u64 v[28:29], v[28:29], 0, s[14:15]
	v_lshl_add_u64 v[30:31], v[30:31], 0, s[26:27]
	v_lshl_add_u64 v[32:33], v[32:33], 0, s[26:27]
	v_lshl_add_u64 v[34:35], v[34:35], 0, s[26:27]
	v_lshl_add_u64 v[36:37], v[36:37], 0, s[26:27]
.LBB0_96:
	s_barrier
	s_waitcnt vmcnt(11)
	ds_write_b128 v41, v[48:51]
	s_waitcnt vmcnt(10)
	ds_write_b128 v42, v[52:55]
	s_waitcnt vmcnt(9)
	ds_write_b128 v43, v[56:59]
	s_waitcnt vmcnt(8)
	ds_write_b128 v44, v[60:63]
	s_waitcnt vmcnt(6)
	ds_write2st64_b32 v45, v64, v65 offset0:68 offset1:72
	s_waitcnt vmcnt(4)
	ds_write2st64_b32 v45, v66, v67 offset0:76 offset1:80
	s_waitcnt vmcnt(2)
	ds_write2st64_b32 v45, v68, v69 offset0:84 offset1:88
	s_waitcnt vmcnt(0)
	ds_write2st64_b32 v45, v70, v71 offset0:92 offset1:96
	s_waitcnt lgkmcnt(0)
	s_add_i32 s8, s8, 64
	s_cmpk_lt_u32 s8, 0x3c0
	s_cbranch_scc0 .Lscal_nopf
	v_lshl_add_u64 v[64:65], v[28:29], 0, v[12:13]
	v_lshl_add_u64 v[66:67], v[26:27], 0, v[12:13]
	v_lshl_add_u64 v[68:69], v[24:25], 0, v[12:13]
	v_lshl_add_u64 v[70:71], v[22:23], 0, v[12:13]
	global_load_dwordx4 v[48:51], v[30:31], off
	global_load_dwordx4 v[52:55], v[32:33], off
	global_load_dwordx4 v[56:59], v[34:35], off
	global_load_dwordx4 v[60:63], v[36:37], off
	v_lshl_add_u64 v[72:73], v[20:21], 0, v[12:13]
	v_lshl_add_u64 v[74:75], v[18:19], 0, v[12:13]
	v_lshl_add_u64 v[76:77], v[16:17], 0, v[12:13]
	v_lshl_add_u64 v[78:79], v[14:15], 0, v[12:13]
	global_load_dword v64, v[64:65], off
	s_nop 0
	global_load_dword v65, v[66:67], off
	s_nop 0
	global_load_dword v66, v[68:69], off
	global_load_dword v67, v[70:71], off
	s_nop 0
	global_load_dword v68, v[72:73], off
	global_load_dword v69, v[74:75], off
	global_load_dword v70, v[76:77], off
	global_load_dword v71, v[78:79], off
	v_lshl_add_u64 v[14:15], v[14:15], 0, s[14:15]
	v_lshl_add_u64 v[16:17], v[16:17], 0, s[14:15]
	v_lshl_add_u64 v[18:19], v[18:19], 0, s[14:15]
	v_lshl_add_u64 v[20:21], v[20:21], 0, s[14:15]
	v_lshl_add_u64 v[22:23], v[22:23], 0, s[14:15]
	v_lshl_add_u64 v[24:25], v[24:25], 0, s[14:15]
	v_lshl_add_u64 v[26:27], v[26:27], 0, s[14:15]
	v_lshl_add_u64 v[28:29], v[28:29], 0, s[14:15]
	v_lshl_add_u64 v[30:31], v[30:31], 0, s[26:27]
	v_lshl_add_u64 v[32:33], v[32:33], 0, s[26:27]
	v_lshl_add_u64 v[34:35], v[34:35], 0, s[26:27]
	v_lshl_add_u64 v[36:37], v[36:37], 0, s[26:27]
; DI void scal_unit(const Params& p, int l, int unit, float* lds) {
;     ...
;   for (int k0 = 0; k0 < 1024; k0 += 64) {
;     __syncthreads();
; #pragma unroll
;     for (int i = 0; i < 4; ++i) { int e = t + 256 * i; int rr = e >> 4, c4 = (e & 15) * 4; *(f4v*)&xt[rr * 68 + c4] = *(const f4v*)&xs[(size_t)(t0 + rr) * DM + k0 + c4]; }
; #pragma unroll
;     for (int i = 0; i < 8; ++i) { int e = t + 256 * i; int kk = e >> 5, c = e & 31; int col = (c < 16) ? (5120 + c) : (8464 + (c - 16)); wt[kk * 32 + c] = win[(size_t)(k0 + kk) * NIN + col]; }
;     __syncthreads();
; #pragma unroll
;     for (int ks = 0; ks < 16; ++ks) {
;       const float a = xt[(16 * w + r) * 68 + ks * 4 + q];
;       const float b0 = wt[(ks * 4 + q) * 32 + r], b1 = wt[(ks * 4 + q) * 32 + 16 + r];
;       acc[0] = __builtin_amdgcn_mfma_f32_16x16x4f32(a, b0, acc[0], 0, 0, 0);
;       acc[1] = __builtin_amdgcn_mfma_f32_16x16x4f32(a, b1, acc[1], 0, 0, 0);
;     }
;   }
; #pragma unroll
;   for (int nt = 0; nt < 2; ++nt)
; #pragma unroll
;     for (int rg = 0; rg < 4; ++rg) ps[(size_t)(t0 + 16 * w + 4 * q + rg) * 32 + 16 * nt + r] = acc[nt][rg];
.Lscal_nopf:
	s_barrier
	v_add_u32_e32 v47, 0x4400, v46
	ds_read2_b32 v[80:81], v40 offset1:4
	ds_read2_b32 v[82:83], v47 offset1:16
	ds_read2_b32 v[84:85], v47 offset0:128 offset1:144
	v_add_u32_e32 v47, 0x4800, v46
	ds_read2_b32 v[86:87], v40 offset0:8 offset1:12
	ds_read2_b32 v[88:89], v47 offset1:16
	ds_read2_b32 v[90:91], v47 offset0:128 offset1:144
	v_add_u32_e32 v47, 0x4c00, v46
	ds_read2_b32 v[92:93], v40 offset0:16 offset1:20
	ds_read2_b32 v[94:95], v47 offset1:16
	ds_read2_b32 v[96:97], v47 offset0:128 offset1:144
	v_add_u32_e32 v47, 0x5000, v46
	ds_read2_b32 v[98:99], v40 offset0:24 offset1:28
	ds_read2_b32 v[100:101], v47 offset1:16
	ds_read2_b32 v[102:103], v47 offset0:128 offset1:144
	s_waitcnt lgkmcnt(10)
	v_mfma_f32_16x16x4_f32 v[2:5], v80, v82, v[2:5]
	v_mfma_f32_16x16x4_f32 v[6:9], v80, v83, v[6:9]
	s_waitcnt lgkmcnt(9)
	v_mfma_f32_16x16x4_f32 v[2:5], v81, v84, v[2:5]
	v_mfma_f32_16x16x4_f32 v[6:9], v81, v85, v[6:9]
	v_add_u32_e32 v47, 0x5400, v46
	ds_read2_b32 v[80:81], v40 offset0:32 offset1:36
	ds_read2_b32 v[82:83], v47 offset1:16
	ds_read2_b32 v[84:85], v47 offset0:128 offset1:144
	s_waitcnt lgkmcnt(10)
	v_mfma_f32_16x16x4_f32 v[2:5], v86, v88, v[2:5]
	v_mfma_f32_16x16x4_f32 v[6:9], v86, v89, v[6:9]
	s_waitcnt lgkmcnt(9)
	v_mfma_f32_16x16x4_f32 v[2:5], v87, v90, v[2:5]
	v_mfma_f32_16x16x4_f32 v[6:9], v87, v91, v[6:9]
	v_add_u32_e32 v47, 0x5800, v46
	ds_read2_b32 v[86:87], v40 offset0:40 offset1:44
	ds_read2_b32 v[88:89], v47 offset1:16
	ds_read2_b32 v[90:91], v47 offset0:128 offset1:144
	s_waitcnt lgkmcnt(10)
	v_mfma_f32_16x16x4_f32 v[2:5], v92, v94, v[2:5]
	v_mfma_f32_16x16x4_f32 v[6:9], v92, v95, v[6:9]
	s_waitcnt lgkmcnt(9)
	v_mfma_f32_16x16x4_f32 v[2:5], v93, v96, v[2:5]
	v_mfma_f32_16x16x4_f32 v[6:9], v93, v97, v[6:9]
	v_add_u32_e32 v47, 0x5c00, v46
	ds_read2_b32 v[92:93], v40 offset0:48 offset1:52
	ds_read2_b32 v[94:95], v47 offset1:16
	ds_read2_b32 v[96:97], v47 offset0:128 offset1:144
	s_waitcnt lgkmcnt(10)
	v_mfma_f32_16x16x4_f32 v[2:5], v98, v100, v[2:5]
	v_mfma_f32_16x16x4_f32 v[6:9], v98, v101, v[6:9]
	s_waitcnt lgkmcnt(9)
	v_mfma_f32_16x16x4_f32 v[2:5], v99, v102, v[2:5]
	v_mfma_f32_16x16x4_f32 v[6:9], v99, v103, v[6:9]
	v_add_u32_e32 v47, 0x6000, v46
	ds_read2_b32 v[98:99], v40 offset0:56 offset1:60
	ds_read2_b32 v[100:101], v47 offset1:16
	ds_read2_b32 v[102:103], v47 offset0:128 offset1:144
	s_waitcnt lgkmcnt(10)
	v_mfma_f32_16x16x4_f32 v[2:5], v80, v82, v[2:5]
	v_mfma_f32_16x16x4_f32 v[6:9], v80, v83, v[6:9]
	s_waitcnt lgkmcnt(9)
	v_mfma_f32_16x16x4_f32 v[2:5], v81, v84, v[2:5]
	v_mfma_f32_16x16x4_f32 v[6:9], v81, v85, v[6:9]
	s_waitcnt lgkmcnt(7)
	v_mfma_f32_16x16x4_f32 v[2:5], v86, v88, v[2:5]
	v_mfma_f32_16x16x4_f32 v[6:9], v86, v89, v[6:9]
	s_waitcnt lgkmcnt(6)
	v_mfma_f32_16x16x4_f32 v[2:5], v87, v90, v[2:5]
	v_mfma_f32_16x16x4_f32 v[6:9], v87, v91, v[6:9]
	s_waitcnt lgkmcnt(4)
	v_mfma_f32_16x16x4_f32 v[2:5], v92, v94, v[2:5]
	v_mfma_f32_16x16x4_f32 v[6:9], v92, v95, v[6:9]
	s_waitcnt lgkmcnt(3)
	v_mfma_f32_16x16x4_f32 v[2:5], v93, v96, v[2:5]
	v_mfma_f32_16x16x4_f32 v[6:9], v93, v97, v[6:9]
	s_waitcnt lgkmcnt(1)
	v_mfma_f32_16x16x4_f32 v[2:5], v98, v100, v[2:5]
	v_mfma_f32_16x16x4_f32 v[6:9], v98, v101, v[6:9]
	s_waitcnt lgkmcnt(0)
	v_mfma_f32_16x16x4_f32 v[2:5], v99, v102, v[2:5]
	v_mfma_f32_16x16x4_f32 v[6:9], v99, v103, v[6:9]
	s_cbranch_scc1 .LBB0_96
	v_lshl_add_u32 v12, v1, 6, v39
	v_lshl_or_b32 v12, v11, 2, v12
	v_readlane_b32 s8, v253, 2
	v_mov_b32_e32 v11, v0
	v_readlane_b32 s9, v253, 3
	v_ashrrev_i32_e32 v13, 31, v12
	v_or_b32_e32 v16, 1, v12
	v_lshl_add_u64 v[10:11], s[8:9], 0, v[10:11]
	v_lshlrev_b64 v[14:15], 7, v[12:13]
	v_ashrrev_i32_e32 v17, 31, v16
	v_lshl_add_u64 v[14:15], v[10:11], 0, v[14:15]
	v_lshlrev_b64 v[16:17], 7, v[16:17]
	global_store_dword v[14:15], v2, off
	v_lshl_add_u64 v[16:17], v[10:11], 0, v[16:17]
	v_or_b32_e32 v2, 2, v12
	v_or_b32_e32 v12, 3, v12
	v_readlane_b32 s8, v252, 59
	global_store_dword v[16:17], v3, off
	v_ashrrev_i32_e32 v3, 31, v2
	v_ashrrev_i32_e32 v13, 31, v12
	v_add_u32_e32 v1, s8, v1
	s_movk_i32 s8, 0xff
	v_lshlrev_b64 v[2:3], 7, v[2:3]
	v_lshlrev_b64 v[12:13], 7, v[12:13]
	v_cmp_lt_i32_e32 vcc, s8, v1
	v_readlane_b32 s8, v255, 8
	v_lshl_add_u64 v[2:3], v[10:11], 0, v[2:3]
	v_lshl_add_u64 v[10:11], v[10:11], 0, v[12:13]
	s_or_b64 s[6:7], vcc, s[6:7]
	v_add_u32_e32 v38, s8, v38
	global_store_dword v[2:3], v4, off
	global_store_dword v[10:11], v5, off
	global_store_dword v[14:15], v6, off offset:64
	global_store_dword v[16:17], v7, off offset:64
	global_store_dword v[2:3], v8, off offset:64
	global_store_dword v[10:11], v9, off offset:64
	s_andn2_b64 exec, exec, s[6:7]
	s_cbranch_execnz .LBB0_95

; template <bool GATHER>
; DI void gemm256_main(const h16* __restrict__ A, int lda, const int* __restrict__ idx, int m0,
;                      const h16* __restrict__ B, int ldb, int n0, int K, h16* lds, f16v (&acc)[4][2]) {
;   const int tid = otid512(), lane = tid & 63, wv = tid >> 6, wm = wv >> 2, wn = wv & 3;
;   const int lr = tid >> 1, lc = (tid & 1) * 32;
;   unsigned ao = (unsigned)(GATHER ? idx[m0 + lr] : (m0 + lr)) * (unsigned)lda + lc;
;   unsigned bo = (unsigned)(n0 + lr) * (unsigned)ldb + lc;
;   const h16* ap = A; const h16* bp = B;
;     ...
;   u4v ra[4], rb[4];
;   const int nk = K >> 6;
;   __syncthreads();
; #pragma unroll
;   for (int i = 0; i < 4; ++i) { ra[i] = *(const u4v*)(AP_ + 8 * i); rb[i] = *(const u4v*)(BP_ + 8 * i); }
;   ao += 64; bo += 64;
; #pragma unroll
;   for (int i = 0; i < 4; ++i) { *(u4v*)&lds[lr * LDH + lc + 8 * i] = ra[i]; *(u4v*)&lds[(256 + lr) * LDH + lc + 8 * i] = rb[i]; }
; #pragma unroll
;   for (int i = 0; i < 4; ++i) { ra[i] = *(const u4v*)(AP_ + 8 * i); rb[i] = *(const u4v*)(BP_ + 8 * i); }
;   ao += 64; bo += 64;
;   __syncthreads();
;   for (int kt = 0; kt < nk; ++kt) {
;     const h16* As = lds + (kt & 1) * (512 * LDH);
;     const h16* Bs = As + 256 * LDH;
;     h16* Wn = lds + ((kt & 1) ^ 1) * (512 * LDH);
;     if (kt + 1 < nk) {
; #pragma unroll
;       for (int i = 0; i < 4; ++i) { *(u4v*)&Wn[lr * LDH + lc + 8 * i] = ra[i]; *(u4v*)&Wn[(256 + lr) * LDH + lc + 8 * i] = rb[i]; }
;     }
;     if (kt + 2 < nk) {
; #pragma unroll
;       for (int i = 0; i < 4; ++i) { ra[i] = *(const u4v*)(AP_ + 8 * i); rb[i] = *(const u4v*)(BP_ + 8 * i); }
;       ao += 64; bo += 64;
;     }
; #pragma unroll
;     for (int ks = 0; ks < 4; ++ks) {
;       h8v af[4], bf[2];
; #pragma unroll
;       for (int i = 0; i < 4; ++i) af[i] = *(const h8v*)&As[(wm * 128 + i * 32 + (lane & 31)) * LDH + ks * 16 + 8 * (lane >> 5)];
; #pragma unroll
;       for (int j = 0; j < 2; ++j) bf[j] = *(const h8v*)&Bs[(wn * 64 + j * 32 + (lane & 31)) * LDH + ks * 16 + 8 * (lane >> 5)];
; #pragma unroll
;       for (int i = 0; i < 4; ++i)
; #pragma unroll
; DI void phase_p1(const Params& p, int l, int bid, int nb, int vb, int vnb, unsigned char* smem, unsigned char* smem_half) {
;     ...
;   for (int u = bid; u < 64 * 20; u += nb) {
;     const int m0 = (u / 20) * 256, n0 = (u % 20) * 256;
;     f16v acc[4][2]; acc256_zero(acc);
.LBB0_101:
	s_mul_hi_i32 s2, s19, 0x66666667
	s_lshr_b32 s3, s2, 31
	s_ashr_i32 s2, s2, 3
	s_add_i32 s2, s2, s3
	v_mov_b32_e32 v1, v180
	s_mul_i32 s6, s2, 0x1400
	v_ashrrev_i32_e32 v66, 1, v1
	v_lshlrev_b32_e32 v2, 5, v1
	v_subrev_u32_e32 v3, s6, v66
	s_lshl_b32 s3, s2, 8
	v_and_b32_e32 v67, 32, v2
	v_add_u32_e32 v3, s18, v3
	v_add_u32_e32 v2, s3, v66
	v_lshl_or_b32 v133, v3, 10, v67
	v_readlane_b32 s8, v253, 0
	v_lshl_or_b32 v2, v2, 10, v67
	v_add_u32_e32 v18, 0x100000, v133
	v_mov_b32_e32 v3, v0
	v_mov_b32_e32 v19, v0
	v_readlane_b32 s9, v253, 1
	v_add_u32_e32 v34, 0x100040, v133
	v_mov_b32_e32 v35, v0
	v_lshl_add_u64 v[130:131], v[2:3], 1, s[40:41]
	v_lshl_add_u64 v[30:31], v[18:19], 1, s[8:9]
	v_lshl_add_u64 v[62:63], v[34:35], 1, s[8:9]
	s_barrier
	s_mulk_i32 s2, 0xec00
	s_add_i32 s2, s18, s2
	s_movk_i32 s4, 0x280
	s_cmpk_lt_u32 s2, 0x600
	v_mov_b32_e32 v248, v30
	v_mov_b32_e32 v249, v31
	v_lshrrev_b32_e32 v192, 1, v180
	v_and_b32_e32 v193, 1, v180
	v_mul_u32_u24_e32 v192, 0x90, v192
	v_lshl_add_u32 v178, v193, 6, v192
	v_add_u32_e32 v178, 16, v178
	v_add_u32_e32 v179, 0x12000, v178
	v_lshrrev_b32_e32 v192, 8, v180
	v_and_b32_e32 v194, 31, v180
	v_lshl_or_b32 v192, v192, 7, v194
	v_mul_u32_u24_e32 v192, 0x90, v192
	v_bfe_u32 v193, v180, 5, 1
	v_lshl_add_u32 v192, v193, 4, v192
	v_add_u32_e32 v215, 16, v192
	v_add_u32_e32 v212, 0x12000, v215
	v_bfe_u32 v192, v180, 6, 2
	v_lshl_or_b32 v192, v192, 6, v194
	v_mul_u32_u24_e32 v192, 0x90, v192
	v_lshl_add_u32 v192, v193, 4, v192
	v_add_u32_e32 v213, 0x9010, v192
	v_add_u32_e32 v214, 0x12000, v213
	global_load_dwordx4 v[134:137], v[130:131], off offset:0
	global_load_dwordx4 v[138:141], v[130:131], off offset:16
	global_load_dwordx4 v[142:145], v[130:131], off offset:32
	global_load_dwordx4 v[146:149], v[130:131], off offset:48
	global_load_dwordx4 v[150:153], v[248:249], off offset:0
	global_load_dwordx4 v[154:157], v[248:249], off offset:16
	global_load_dwordx4 v[158:161], v[248:249], off offset:32
	global_load_dwordx4 v[162:165], v[248:249], off offset:48
	s_waitcnt vmcnt(0)
	ds_write_b128 v178, v[134:137]
	ds_write_b128 v178, v[138:141] offset:16
	ds_write_b128 v178, v[142:145] offset:32
	ds_write_b128 v178, v[146:149] offset:48
	ds_write_b128 v178, v[150:153] offset:36864
	ds_write_b128 v178, v[154:157] offset:36880
	ds_write_b128 v178, v[158:161] offset:36896
	ds_write_b128 v178, v[162:165] offset:36912
	global_load_dwordx4 v[134:137], v[130:131], off offset:128
	global_load_dwordx4 v[138:141], v[130:131], off offset:144
	global_load_dwordx4 v[142:145], v[130:131], off offset:160
	global_load_dwordx4 v[146:149], v[130:131], off offset:176
	global_load_dwordx4 v[150:153], v[248:249], off offset:128
	global_load_dwordx4 v[154:157], v[248:249], off offset:144
	global_load_dwordx4 v[158:161], v[248:249], off offset:160
	global_load_dwordx4 v[162:165], v[248:249], off offset:176
	s_waitcnt lgkmcnt(0)
	s_barrier
	ds_read_b128 v[232:235], v213
	ds_read_b128 v[216:219], v215
	ds_read_b128 v[236:239], v213 offset:4608
	ds_read_b128 v[220:223], v215 offset:4608
	ds_read_b128 v[224:227], v215 offset:9216
	ds_read_b128 v[228:231], v215 offset:13824
	ds_read_b128 v[208:211], v213 offset:32
	ds_read_b128 v[240:243], v215 offset:32
	ds_read_b128 v[174:177], v213 offset:4640
	ds_read_b128 v[244:247], v215 offset:4640
	ds_read_b128 v[200:203], v215 offset:9248
	ds_read_b128 v[204:207], v215 offset:13856
	s_waitcnt vmcnt(4)
	ds_write_b128 v179, v[134:137]
	ds_write_b128 v179, v[138:141] offset:16
	ds_write_b128 v179, v[142:145] offset:32
	ds_write_b128 v179, v[146:149] offset:48
	global_load_dwordx4 v[134:137], v[130:131], off offset:256
	global_load_dwordx4 v[138:141], v[130:131], off offset:272
	global_load_dwordx4 v[142:145], v[130:131], off offset:288
	global_load_dwordx4 v[146:149], v[130:131], off offset:304
	s_waitcnt lgkmcnt(14)
	v_mfma_f32_32x32x16_f16 v[114:129], v[232:235], v[216:219], 0
	s_waitcnt lgkmcnt(13)
	v_mfma_f32_32x32x16_f16 v[98:113], v[236:239], v[216:219], 0
	s_waitcnt lgkmcnt(12)
	v_mfma_f32_32x32x16_f16 v[82:97], v[232:235], v[220:223], 0
	v_mfma_f32_32x32x16_f16 v[66:81], v[236:239], v[220:223], 0
	s_waitcnt lgkmcnt(11)
	v_mfma_f32_32x32x16_f16 v[50:65], v[232:235], v[224:227], 0
	v_mfma_f32_32x32x16_f16 v[34:49], v[236:239], v[224:227], 0
	s_waitcnt lgkmcnt(10)
	v_mfma_f32_32x32x16_f16 v[2:17], v[232:235], v[228:231], 0
	v_mfma_f32_32x32x16_f16 v[18:33], v[236:239], v[228:231], 0
	ds_read_b128 v[232:235], v213 offset:64
	ds_read_b128 v[216:219], v215 offset:64
	ds_read_b128 v[236:239], v213 offset:4672
	ds_read_b128 v[220:223], v215 offset:4672
	ds_read_b128 v[224:227], v215 offset:9280
	ds_read_b128 v[228:231], v215 offset:13888
	s_waitcnt vmcnt(4)
	ds_write_b128 v179, v[150:153] offset:36864
	ds_write_b128 v179, v[154:157] offset:36880
	ds_write_b128 v179, v[158:161] offset:36896
	ds_write_b128 v179, v[162:165] offset:36912
	global_load_dwordx4 v[150:153], v[248:249], off offset:256
	global_load_dwordx4 v[154:157], v[248:249], off offset:272
	global_load_dwordx4 v[158:161], v[248:249], off offset:288
	global_load_dwordx4 v[162:165], v[248:249], off offset:304
	s_waitcnt lgkmcnt(15)
	v_mfma_f32_32x32x16_f16 v[114:129], v[208:211], v[240:243], v[114:129]
	s_waitcnt lgkmcnt(15)
	v_mfma_f32_32x32x16_f16 v[98:113], v[174:177], v[240:243], v[98:113]
	s_waitcnt lgkmcnt(15)
	v_mfma_f32_32x32x16_f16 v[82:97], v[208:211], v[244:247], v[82:97]
	v_mfma_f32_32x32x16_f16 v[66:81], v[174:177], v[244:247], v[66:81]
	s_waitcnt lgkmcnt(15)
	v_mfma_f32_32x32x16_f16 v[50:65], v[208:211], v[200:203], v[50:65]
	v_mfma_f32_32x32x16_f16 v[34:49], v[174:177], v[200:203], v[34:49]
	s_waitcnt lgkmcnt(14)
	v_mfma_f32_32x32x16_f16 v[2:17], v[208:211], v[204:207], v[2:17]
	v_mfma_f32_32x32x16_f16 v[18:33], v[174:177], v[204:207], v[18:33]
	ds_read_b128 v[208:211], v213 offset:96
	ds_read_b128 v[240:243], v215 offset:96
	ds_read_b128 v[174:177], v213 offset:4704
	ds_read_b128 v[244:247], v215 offset:4704
	ds_read_b128 v[200:203], v215 offset:9312
	ds_read_b128 v[204:207], v215 offset:13920
	s_waitcnt lgkmcnt(14)
	v_mfma_f32_32x32x16_f16 v[114:129], v[232:235], v[216:219], v[114:129]
	s_waitcnt lgkmcnt(13)
	v_mfma_f32_32x32x16_f16 v[98:113], v[236:239], v[216:219], v[98:113]
	s_waitcnt lgkmcnt(12)
	v_mfma_f32_32x32x16_f16 v[82:97], v[232:235], v[220:223], v[82:97]
	v_mfma_f32_32x32x16_f16 v[66:81], v[236:239], v[220:223], v[66:81]
	s_waitcnt lgkmcnt(11)
	v_mfma_f32_32x32x16_f16 v[50:65], v[232:235], v[224:227], v[50:65]
	v_mfma_f32_32x32x16_f16 v[34:49], v[236:239], v[224:227], v[34:49]
	s_waitcnt lgkmcnt(10)
	v_mfma_f32_32x32x16_f16 v[2:17], v[232:235], v[228:231], v[2:17]
	v_mfma_f32_32x32x16_f16 v[18:33], v[236:239], v[228:231], v[18:33]
	s_waitcnt lgkmcnt(0)
	s_barrier
; DI f16v mfma32(h8v a, h8v b, f16v c) { return __builtin_amdgcn_mfma_f32_32x32x16_f16(a, b, c, 0, 0, 0); }
; template <bool GATHER>
; DI void gemm256_main(const h16* __restrict__ A, int lda, const int* __restrict__ idx, int m0,
;                      const h16* __restrict__ B, int ldb, int n0, int K, h16* lds, f16v (&acc)[4][2]) {
;     ...
;   for (int kt = 0; kt < nk; ++kt) {
;     const h16* As = lds + (kt & 1) * (512 * LDH);
;     const h16* Bs = As + 256 * LDH;
;     h16* Wn = lds + ((kt & 1) ^ 1) * (512 * LDH);
;     if (kt + 1 < nk) {
; #pragma unroll
;       for (int i = 0; i < 4; ++i) { *(u4v*)&Wn[lr * LDH + lc + 8 * i] = ra[i]; *(u4v*)&Wn[(256 + lr) * LDH + lc + 8 * i] = rb[i]; }
;     }
;     if (kt + 2 < nk) {
; #pragma unroll
;       for (int i = 0; i < 4; ++i) { ra[i] = *(const u4v*)(AP_ + 8 * i); rb[i] = *(const u4v*)(BP_ + 8 * i); }
;       ao += 64; bo += 64;
;     }
; #pragma unroll
;     for (int ks = 0; ks < 4; ++ks) {
;       h8v af[4], bf[2];
; #pragma unroll
;       for (int i = 0; i < 4; ++i) af[i] = *(const h8v*)&As[(wm * 128 + i * 32 + (lane & 31)) * LDH + ks * 16 + 8 * (lane >> 5)];
; #pragma unroll
;       for (int j = 0; j < 2; ++j) bf[j] = *(const h8v*)&Bs[(wn * 64 + j * 32 + (lane & 31)) * LDH + ks * 16 + 8 * (lane >> 5)];
; #pragma unroll
;       for (int i = 0; i < 4; ++i)
; #pragma unroll
;         for (int j = 0; j < 2; ++j) acc[i][j] = mfma32(bf[j], af[i], acc[i][j]);
;     }
;     __syncthreads();
	ds_read_b128 v[232:235], v214
	ds_read_b128 v[216:219], v212
	ds_read_b128 v[236:239], v214 offset:4608
	ds_read_b128 v[220:223], v212 offset:4608
	ds_read_b128 v[224:227], v212 offset:9216
	ds_read_b128 v[228:231], v212 offset:13824
	v_mfma_f32_32x32x16_f16 v[114:129], v[208:211], v[240:243], v[114:129]
	v_mfma_f32_32x32x16_f16 v[98:113], v[174:177], v[240:243], v[98:113]
	v_mfma_f32_32x32x16_f16 v[82:97], v[208:211], v[244:247], v[82:97]
	v_mfma_f32_32x32x16_f16 v[66:81], v[174:177], v[244:247], v[66:81]
	v_mfma_f32_32x32x16_f16 v[50:65], v[208:211], v[200:203], v[50:65]
	v_mfma_f32_32x32x16_f16 v[34:49], v[174:177], v[200:203], v[34:49]
	v_mfma_f32_32x32x16_f16 v[2:17], v[208:211], v[204:207], v[2:17]
	v_mfma_f32_32x32x16_f16 v[18:33], v[174:177], v[204:207], v[18:33]
	ds_read_b128 v[208:211], v214 offset:32
	ds_read_b128 v[240:243], v212 offset:32
	ds_read_b128 v[174:177], v214 offset:4640
	ds_read_b128 v[244:247], v212 offset:4640
	ds_read_b128 v[200:203], v212 offset:9248
	ds_read_b128 v[204:207], v212 offset:13856
	s_waitcnt vmcnt(4)
	ds_write_b128 v178, v[134:137]
	ds_write_b128 v178, v[138:141] offset:16
	ds_write_b128 v178, v[142:145] offset:32
	ds_write_b128 v178, v[146:149] offset:48
	global_load_dwordx4 v[134:137], v[130:131], off offset:384
	global_load_dwordx4 v[138:141], v[130:131], off offset:400
	global_load_dwordx4 v[142:145], v[130:131], off offset:416
	global_load_dwordx4 v[146:149], v[130:131], off offset:432
	s_waitcnt lgkmcnt(14)
	v_mfma_f32_32x32x16_f16 v[114:129], v[232:235], v[216:219], v[114:129]
	s_waitcnt lgkmcnt(13)
	v_mfma_f32_32x32x16_f16 v[98:113], v[236:239], v[216:219], v[98:113]
	s_waitcnt lgkmcnt(12)
	v_mfma_f32_32x32x16_f16 v[82:97], v[232:235], v[220:223], v[82:97]
	v_mfma_f32_32x32x16_f16 v[66:81], v[236:239], v[220:223], v[66:81]
	s_waitcnt lgkmcnt(11)
	v_mfma_f32_32x32x16_f16 v[50:65], v[232:235], v[224:227], v[50:65]
	v_mfma_f32_32x32x16_f16 v[34:49], v[236:239], v[224:227], v[34:49]
	s_waitcnt lgkmcnt(10)
	v_mfma_f32_32x32x16_f16 v[2:17], v[232:235], v[228:231], v[2:17]
	v_mfma_f32_32x32x16_f16 v[18:33], v[236:239], v[228:231], v[18:33]
	ds_read_b128 v[232:235], v214 offset:64
	ds_read_b128 v[216:219], v212 offset:64
	ds_read_b128 v[236:239], v214 offset:4672
	ds_read_b128 v[220:223], v212 offset:4672
	ds_read_b128 v[224:227], v212 offset:9280
	ds_read_b128 v[228:231], v212 offset:13888
	s_waitcnt vmcnt(4)
	ds_write_b128 v178, v[150:153] offset:36864
	ds_write_b128 v178, v[154:157] offset:36880
	ds_write_b128 v178, v[158:161] offset:36896
	ds_write_b128 v178, v[162:165] offset:36912
	global_load_dwordx4 v[150:153], v[248:249], off offset:384
	global_load_dwordx4 v[154:157], v[248:249], off offset:400
	global_load_dwordx4 v[158:161], v[248:249], off offset:416
	global_load_dwordx4 v[162:165], v[248:249], off offset:432
	s_waitcnt lgkmcnt(15)
	v_mfma_f32_32x32x16_f16 v[114:129], v[208:211], v[240:243], v[114:129]
	s_waitcnt lgkmcnt(15)
	v_mfma_f32_32x32x16_f16 v[98:113], v[174:177], v[240:243], v[98:113]
	s_waitcnt lgkmcnt(15)
	v_mfma_f32_32x32x16_f16 v[82:97], v[208:211], v[244:247], v[82:97]
	v_mfma_f32_32x32x16_f16 v[66:81], v[174:177], v[244:247], v[66:81]
	s_waitcnt lgkmcnt(15)
	v_mfma_f32_32x32x16_f16 v[50:65], v[208:211], v[200:203], v[50:65]
	v_mfma_f32_32x32x16_f16 v[34:49], v[174:177], v[200:203], v[34:49]
	s_waitcnt lgkmcnt(14)
	v_mfma_f32_32x32x16_f16 v[2:17], v[208:211], v[204:207], v[2:17]
	v_mfma_f32_32x32x16_f16 v[18:33], v[174:177], v[204:207], v[18:33]
	ds_read_b128 v[208:211], v214 offset:96
	ds_read_b128 v[240:243], v212 offset:96
	ds_read_b128 v[174:177], v214 offset:4704
	ds_read_b128 v[244:247], v212 offset:4704
	ds_read_b128 v[200:203], v212 offset:9312
	ds_read_b128 v[204:207], v212 offset:13920
	s_waitcnt lgkmcnt(14)
	v_mfma_f32_32x32x16_f16 v[114:129], v[232:235], v[216:219], v[114:129]
	s_waitcnt lgkmcnt(13)
	v_mfma_f32_32x32x16_f16 v[98:113], v[236:239], v[216:219], v[98:113]
	s_waitcnt lgkmcnt(12)
	v_mfma_f32_32x32x16_f16 v[82:97], v[232:235], v[220:223], v[82:97]
	v_mfma_f32_32x32x16_f16 v[66:81], v[236:239], v[220:223], v[66:81]
	s_waitcnt lgkmcnt(11)
	v_mfma_f32_32x32x16_f16 v[50:65], v[232:235], v[224:227], v[50:65]
	v_mfma_f32_32x32x16_f16 v[34:49], v[236:239], v[224:227], v[34:49]
	s_waitcnt lgkmcnt(10)
	v_mfma_f32_32x32x16_f16 v[2:17], v[232:235], v[228:231], v[2:17]
	v_mfma_f32_32x32x16_f16 v[18:33], v[236:239], v[228:231], v[18:33]
	s_waitcnt lgkmcnt(0)
	s_barrier
; DI f16v mfma32(h8v a, h8v b, f16v c) { return __builtin_amdgcn_mfma_f32_32x32x16_f16(a, b, c, 0, 0, 0); }
; template <bool GATHER>
; DI void gemm256_main(const h16* __restrict__ A, int lda, const int* __restrict__ idx, int m0,
;                      const h16* __restrict__ B, int ldb, int n0, int K, h16* lds, f16v (&acc)[4][2]) {
;     ...
;   for (int kt = 0; kt < nk; ++kt) {
;     const h16* As = lds + (kt & 1) * (512 * LDH);
;     const h16* Bs = As + 256 * LDH;
;     h16* Wn = lds + ((kt & 1) ^ 1) * (512 * LDH);
;     if (kt + 1 < nk) {
; #pragma unroll
;       for (int i = 0; i < 4; ++i) { *(u4v*)&Wn[lr * LDH + lc + 8 * i] = ra[i]; *(u4v*)&Wn[(256 + lr) * LDH + lc + 8 * i] = rb[i]; }
;     }
;     if (kt + 2 < nk) {
; #pragma unroll
;       for (int i = 0; i < 4; ++i) { ra[i] = *(const u4v*)(AP_ + 8 * i); rb[i] = *(const u4v*)(BP_ + 8 * i); }
;       ao += 64; bo += 64;
;     }
; #pragma unroll
;     for (int ks = 0; ks < 4; ++ks) {
;       h8v af[4], bf[2];
; #pragma unroll
;       for (int i = 0; i < 4; ++i) af[i] = *(const h8v*)&As[(wm * 128 + i * 32 + (lane & 31)) * LDH + ks * 16 + 8 * (lane >> 5)];
; #pragma unroll
;       for (int j = 0; j < 2; ++j) bf[j] = *(const h8v*)&Bs[(wn * 64 + j * 32 + (lane & 31)) * LDH + ks * 16 + 8 * (lane >> 5)];
; #pragma unroll
;       for (int i = 0; i < 4; ++i)
; #pragma unroll
;         for (int j = 0; j < 2; ++j) acc[i][j] = mfma32(bf[j], af[i], acc[i][j]);
;     }
;     __syncthreads();
	ds_read_b128 v[232:235], v213
	ds_read_b128 v[216:219], v215
	ds_read_b128 v[236:239], v213 offset:4608
	ds_read_b128 v[220:223], v215 offset:4608
	ds_read_b128 v[224:227], v215 offset:9216
	ds_read_b128 v[228:231], v215 offset:13824
	v_mfma_f32_32x32x16_f16 v[114:129], v[208:211], v[240:243], v[114:129]
	v_mfma_f32_32x32x16_f16 v[98:113], v[174:177], v[240:243], v[98:113]
	v_mfma_f32_32x32x16_f16 v[82:97], v[208:211], v[244:247], v[82:97]
	v_mfma_f32_32x32x16_f16 v[66:81], v[174:177], v[244:247], v[66:81]
	v_mfma_f32_32x32x16_f16 v[50:65], v[208:211], v[200:203], v[50:65]
	v_mfma_f32_32x32x16_f16 v[34:49], v[174:177], v[200:203], v[34:49]
	v_mfma_f32_32x32x16_f16 v[2:17], v[208:211], v[204:207], v[2:17]
	v_mfma_f32_32x32x16_f16 v[18:33], v[174:177], v[204:207], v[18:33]
	ds_read_b128 v[208:211], v213 offset:32
	ds_read_b128 v[240:243], v215 offset:32
	ds_read_b128 v[174:177], v213 offset:4640
	ds_read_b128 v[244:247], v215 offset:4640
	ds_read_b128 v[200:203], v215 offset:9248
	ds_read_b128 v[204:207], v215 offset:13856
	s_waitcnt vmcnt(4)
	ds_write_b128 v179, v[134:137]
	ds_write_b128 v179, v[138:141] offset:16
	ds_write_b128 v179, v[142:145] offset:32
	ds_write_b128 v179, v[146:149] offset:48
	global_load_dwordx4 v[134:137], v[130:131], off offset:512
	global_load_dwordx4 v[138:141], v[130:131], off offset:528
	global_load_dwordx4 v[142:145], v[130:131], off offset:544
	global_load_dwordx4 v[146:149], v[130:131], off offset:560
	s_waitcnt lgkmcnt(14)
	v_mfma_f32_32x32x16_f16 v[114:129], v[232:235], v[216:219], v[114:129]
	s_waitcnt lgkmcnt(13)
	v_mfma_f32_32x32x16_f16 v[98:113], v[236:239], v[216:219], v[98:113]
	s_waitcnt lgkmcnt(12)
	v_mfma_f32_32x32x16_f16 v[82:97], v[232:235], v[220:223], v[82:97]
	v_mfma_f32_32x32x16_f16 v[66:81], v[236:239], v[220:223], v[66:81]
	s_waitcnt lgkmcnt(11)
	v_mfma_f32_32x32x16_f16 v[50:65], v[232:235], v[224:227], v[50:65]
	v_mfma_f32_32x32x16_f16 v[34:49], v[236:239], v[224:227], v[34:49]
	s_waitcnt lgkmcnt(10)
	v_mfma_f32_32x32x16_f16 v[2:17], v[232:235], v[228:231], v[2:17]
	v_mfma_f32_32x32x16_f16 v[18:33], v[236:239], v[228:231], v[18:33]
	ds_read_b128 v[232:235], v213 offset:64
	ds_read_b128 v[216:219], v215 offset:64
	ds_read_b128 v[236:239], v213 offset:4672
	ds_read_b128 v[220:223], v215 offset:4672
	ds_read_b128 v[224:227], v215 offset:9280
	ds_read_b128 v[228:231], v215 offset:13888
	s_waitcnt vmcnt(4)
	ds_write_b128 v179, v[150:153] offset:36864
	ds_write_b128 v179, v[154:157] offset:36880
	ds_write_b128 v179, v[158:161] offset:36896
	ds_write_b128 v179, v[162:165] offset:36912
	global_load_dwordx4 v[150:153], v[248:249], off offset:512
	global_load_dwordx4 v[154:157], v[248:249], off offset:528
	global_load_dwordx4 v[158:161], v[248:249], off offset:544
	global_load_dwordx4 v[162:165], v[248:249], off offset:560
	s_waitcnt lgkmcnt(15)
	v_mfma_f32_32x32x16_f16 v[114:129], v[208:211], v[240:243], v[114:129]
	s_waitcnt lgkmcnt(15)
	v_mfma_f32_32x32x16_f16 v[98:113], v[174:177], v[240:243], v[98:113]
	s_waitcnt lgkmcnt(15)
	v_mfma_f32_32x32x16_f16 v[82:97], v[208:211], v[244:247], v[82:97]
	v_mfma_f32_32x32x16_f16 v[66:81], v[174:177], v[244:247], v[66:81]
	s_waitcnt lgkmcnt(15)
	v_mfma_f32_32x32x16_f16 v[50:65], v[208:211], v[200:203], v[50:65]
	v_mfma_f32_32x32x16_f16 v[34:49], v[174:177], v[200:203], v[34:49]
	s_waitcnt lgkmcnt(14)
	v_mfma_f32_32x32x16_f16 v[2:17], v[208:211], v[204:207], v[2:17]
	v_mfma_f32_32x32x16_f16 v[18:33], v[174:177], v[204:207], v[18:33]
	ds_read_b128 v[208:211], v213 offset:96
	ds_read_b128 v[240:243], v215 offset:96
	ds_read_b128 v[174:177], v213 offset:4704
	ds_read_b128 v[244:247], v215 offset:4704
	ds_read_b128 v[200:203], v215 offset:9312
	ds_read_b128 v[204:207], v215 offset:13920
	s_waitcnt lgkmcnt(14)
	v_mfma_f32_32x32x16_f16 v[114:129], v[232:235], v[216:219], v[114:129]
	s_waitcnt lgkmcnt(13)
	v_mfma_f32_32x32x16_f16 v[98:113], v[236:239], v[216:219], v[98:113]
	s_waitcnt lgkmcnt(12)
	v_mfma_f32_32x32x16_f16 v[82:97], v[232:235], v[220:223], v[82:97]
	v_mfma_f32_32x32x16_f16 v[66:81], v[236:239], v[220:223], v[66:81]
	s_waitcnt lgkmcnt(11)
	v_mfma_f32_32x32x16_f16 v[50:65], v[232:235], v[224:227], v[50:65]
	v_mfma_f32_32x32x16_f16 v[34:49], v[236:239], v[224:227], v[34:49]
	s_waitcnt lgkmcnt(10)
	v_mfma_f32_32x32x16_f16 v[2:17], v[232:235], v[228:231], v[2:17]
	v_mfma_f32_32x32x16_f16 v[18:33], v[236:239], v[228:231], v[18:33]
	s_waitcnt lgkmcnt(0)
	s_barrier
; DI f16v mfma32(h8v a, h8v b, f16v c) { return __builtin_amdgcn_mfma_f32_32x32x16_f16(a, b, c, 0, 0, 0); }
; template <bool GATHER>
; DI void gemm256_main(const h16* __restrict__ A, int lda, const int* __restrict__ idx, int m0,
;                      const h16* __restrict__ B, int ldb, int n0, int K, h16* lds, f16v (&acc)[4][2]) {
;     ...
;   for (int kt = 0; kt < nk; ++kt) {
;     const h16* As = lds + (kt & 1) * (512 * LDH);
;     const h16* Bs = As + 256 * LDH;
;     h16* Wn = lds + ((kt & 1) ^ 1) * (512 * LDH);
;     if (kt + 1 < nk) {
; #pragma unroll
;       for (int i = 0; i < 4; ++i) { *(u4v*)&Wn[lr * LDH + lc + 8 * i] = ra[i]; *(u4v*)&Wn[(256 + lr) * LDH + lc + 8 * i] = rb[i]; }
;     }
;     if (kt + 2 < nk) {
; #pragma unroll
;       for (int i = 0; i < 4; ++i) { ra[i] = *(const u4v*)(AP_ + 8 * i); rb[i] = *(const u4v*)(BP_ + 8 * i); }
;       ao += 64; bo += 64;
;     }
; #pragma unroll
;     for (int ks = 0; ks < 4; ++ks) {
;       h8v af[4], bf[2];
; #pragma unroll
;       for (int i = 0; i < 4; ++i) af[i] = *(const h8v*)&As[(wm * 128 + i * 32 + (lane & 31)) * LDH + ks * 16 + 8 * (lane >> 5)];
; #pragma unroll
;       for (int j = 0; j < 2; ++j) bf[j] = *(const h8v*)&Bs[(wn * 64 + j * 32 + (lane & 31)) * LDH + ks * 16 + 8 * (lane >> 5)];
; #pragma unroll
;       for (int i = 0; i < 4; ++i)
; #pragma unroll
;         for (int j = 0; j < 2; ++j) acc[i][j] = mfma32(bf[j], af[i], acc[i][j]);
;     }
;     __syncthreads();
	ds_read_b128 v[232:235], v214
	ds_read_b128 v[216:219], v212
	ds_read_b128 v[236:239], v214 offset:4608
	ds_read_b128 v[220:223], v212 offset:4608
	ds_read_b128 v[224:227], v212 offset:9216
	ds_read_b128 v[228:231], v212 offset:13824
	v_mfma_f32_32x32x16_f16 v[114:129], v[208:211], v[240:243], v[114:129]
	v_mfma_f32_32x32x16_f16 v[98:113], v[174:177], v[240:243], v[98:113]
	v_mfma_f32_32x32x16_f16 v[82:97], v[208:211], v[244:247], v[82:97]
	v_mfma_f32_32x32x16_f16 v[66:81], v[174:177], v[244:247], v[66:81]
	v_mfma_f32_32x32x16_f16 v[50:65], v[208:211], v[200:203], v[50:65]
	v_mfma_f32_32x32x16_f16 v[34:49], v[174:177], v[200:203], v[34:49]
	v_mfma_f32_32x32x16_f16 v[2:17], v[208:211], v[204:207], v[2:17]
	v_mfma_f32_32x32x16_f16 v[18:33], v[174:177], v[204:207], v[18:33]
	ds_read_b128 v[208:211], v214 offset:32
	ds_read_b128 v[240:243], v212 offset:32
	ds_read_b128 v[174:177], v214 offset:4640
	ds_read_b128 v[244:247], v212 offset:4640
	ds_read_b128 v[200:203], v212 offset:9248
	ds_read_b128 v[204:207], v212 offset:13856
	s_waitcnt vmcnt(4)
	ds_write_b128 v178, v[134:137]
	ds_write_b128 v178, v[138:141] offset:16
	ds_write_b128 v178, v[142:145] offset:32
	ds_write_b128 v178, v[146:149] offset:48
	global_load_dwordx4 v[134:137], v[130:131], off offset:640
	global_load_dwordx4 v[138:141], v[130:131], off offset:656
	global_load_dwordx4 v[142:145], v[130:131], off offset:672
	global_load_dwordx4 v[146:149], v[130:131], off offset:688
	s_waitcnt lgkmcnt(14)
	v_mfma_f32_32x32x16_f16 v[114:129], v[232:235], v[216:219], v[114:129]
	s_waitcnt lgkmcnt(13)
	v_mfma_f32_32x32x16_f16 v[98:113], v[236:239], v[216:219], v[98:113]
	s_waitcnt lgkmcnt(12)
	v_mfma_f32_32x32x16_f16 v[82:97], v[232:235], v[220:223], v[82:97]
	v_mfma_f32_32x32x16_f16 v[66:81], v[236:239], v[220:223], v[66:81]
	s_waitcnt lgkmcnt(11)
	v_mfma_f32_32x32x16_f16 v[50:65], v[232:235], v[224:227], v[50:65]
	v_mfma_f32_32x32x16_f16 v[34:49], v[236:239], v[224:227], v[34:49]
	s_waitcnt lgkmcnt(10)
	v_mfma_f32_32x32x16_f16 v[2:17], v[232:235], v[228:231], v[2:17]
	v_mfma_f32_32x32x16_f16 v[18:33], v[236:239], v[228:231], v[18:33]
	ds_read_b128 v[232:235], v214 offset:64
	ds_read_b128 v[216:219], v212 offset:64
	ds_read_b128 v[236:239], v214 offset:4672
	ds_read_b128 v[220:223], v212 offset:4672
	ds_read_b128 v[224:227], v212 offset:9280
	ds_read_b128 v[228:231], v212 offset:13888
	s_waitcnt vmcnt(4)
	ds_write_b128 v178, v[150:153] offset:36864
	ds_write_b128 v178, v[154:157] offset:36880
	ds_write_b128 v178, v[158:161] offset:36896
	ds_write_b128 v178, v[162:165] offset:36912
	global_load_dwordx4 v[150:153], v[248:249], off offset:640
	global_load_dwordx4 v[154:157], v[248:249], off offset:656
	global_load_dwordx4 v[158:161], v[248:249], off offset:672
	global_load_dwordx4 v[162:165], v[248:249], off offset:688
	s_waitcnt lgkmcnt(15)
	v_mfma_f32_32x32x16_f16 v[114:129], v[208:211], v[240:243], v[114:129]
	s_waitcnt lgkmcnt(15)
	v_mfma_f32_32x32x16_f16 v[98:113], v[174:177], v[240:243], v[98:113]
	s_waitcnt lgkmcnt(15)
	v_mfma_f32_32x32x16_f16 v[82:97], v[208:211], v[244:247], v[82:97]
	v_mfma_f32_32x32x16_f16 v[66:81], v[174:177], v[244:247], v[66:81]
	s_waitcnt lgkmcnt(15)
	v_mfma_f32_32x32x16_f16 v[50:65], v[208:211], v[200:203], v[50:65]
	v_mfma_f32_32x32x16_f16 v[34:49], v[174:177], v[200:203], v[34:49]
	s_waitcnt lgkmcnt(14)
	v_mfma_f32_32x32x16_f16 v[2:17], v[208:211], v[204:207], v[2:17]
	v_mfma_f32_32x32x16_f16 v[18:33], v[174:177], v[204:207], v[18:33]
	ds_read_b128 v[208:211], v214 offset:96
	ds_read_b128 v[240:243], v212 offset:96
	ds_read_b128 v[174:177], v214 offset:4704
	ds_read_b128 v[244:247], v212 offset:4704
	ds_read_b128 v[200:203], v212 offset:9312
	ds_read_b128 v[204:207], v212 offset:13920
	s_waitcnt lgkmcnt(14)
	v_mfma_f32_32x32x16_f16 v[114:129], v[232:235], v[216:219], v[114:129]
	s_waitcnt lgkmcnt(13)
	v_mfma_f32_32x32x16_f16 v[98:113], v[236:239], v[216:219], v[98:113]
	s_waitcnt lgkmcnt(12)
	v_mfma_f32_32x32x16_f16 v[82:97], v[232:235], v[220:223], v[82:97]
	v_mfma_f32_32x32x16_f16 v[66:81], v[236:239], v[220:223], v[66:81]
	s_waitcnt lgkmcnt(11)
	v_mfma_f32_32x32x16_f16 v[50:65], v[232:235], v[224:227], v[50:65]
	v_mfma_f32_32x32x16_f16 v[34:49], v[236:239], v[224:227], v[34:49]
	s_waitcnt lgkmcnt(10)
	v_mfma_f32_32x32x16_f16 v[2:17], v[232:235], v[228:231], v[2:17]
	v_mfma_f32_32x32x16_f16 v[18:33], v[236:239], v[228:231], v[18:33]
	s_waitcnt lgkmcnt(0)
	s_barrier
; DI f16v mfma32(h8v a, h8v b, f16v c) { return __builtin_amdgcn_mfma_f32_32x32x16_f16(a, b, c, 0, 0, 0); }
; template <bool GATHER>
; DI void gemm256_main(const h16* __restrict__ A, int lda, const int* __restrict__ idx, int m0,
;                      const h16* __restrict__ B, int ldb, int n0, int K, h16* lds, f16v (&acc)[4][2]) {
;     ...
;   for (int kt = 0; kt < nk; ++kt) {
;     const h16* As = lds + (kt & 1) * (512 * LDH);
;     const h16* Bs = As + 256 * LDH;
;     h16* Wn = lds + ((kt & 1) ^ 1) * (512 * LDH);
;     if (kt + 1 < nk) {
; #pragma unroll
;       for (int i = 0; i < 4; ++i) { *(u4v*)&Wn[lr * LDH + lc + 8 * i] = ra[i]; *(u4v*)&Wn[(256 + lr) * LDH + lc + 8 * i] = rb[i]; }
;     }
;     if (kt + 2 < nk) {
; #pragma unroll
;       for (int i = 0; i < 4; ++i) { ra[i] = *(const u4v*)(AP_ + 8 * i); rb[i] = *(const u4v*)(BP_ + 8 * i); }
;       ao += 64; bo += 64;
;     }
; #pragma unroll
;     for (int ks = 0; ks < 4; ++ks) {
;       h8v af[4], bf[2];
; #pragma unroll
;       for (int i = 0; i < 4; ++i) af[i] = *(const h8v*)&As[(wm * 128 + i * 32 + (lane & 31)) * LDH + ks * 16 + 8 * (lane >> 5)];
; #pragma unroll
;       for (int j = 0; j < 2; ++j) bf[j] = *(const h8v*)&Bs[(wn * 64 + j * 32 + (lane & 31)) * LDH + ks * 16 + 8 * (lane >> 5)];
; #pragma unroll
;       for (int i = 0; i < 4; ++i)
; #pragma unroll
;         for (int j = 0; j < 2; ++j) acc[i][j] = mfma32(bf[j], af[i], acc[i][j]);
;     }
;     __syncthreads();
	ds_read_b128 v[232:235], v213
	ds_read_b128 v[216:219], v215
	ds_read_b128 v[236:239], v213 offset:4608
	ds_read_b128 v[220:223], v215 offset:4608
	ds_read_b128 v[224:227], v215 offset:9216
	ds_read_b128 v[228:231], v215 offset:13824
	v_mfma_f32_32x32x16_f16 v[114:129], v[208:211], v[240:243], v[114:129]
	v_mfma_f32_32x32x16_f16 v[98:113], v[174:177], v[240:243], v[98:113]
	v_mfma_f32_32x32x16_f16 v[82:97], v[208:211], v[244:247], v[82:97]
	v_mfma_f32_32x32x16_f16 v[66:81], v[174:177], v[244:247], v[66:81]
	v_mfma_f32_32x32x16_f16 v[50:65], v[208:211], v[200:203], v[50:65]
	v_mfma_f32_32x32x16_f16 v[34:49], v[174:177], v[200:203], v[34:49]
	v_mfma_f32_32x32x16_f16 v[2:17], v[208:211], v[204:207], v[2:17]
	v_mfma_f32_32x32x16_f16 v[18:33], v[174:177], v[204:207], v[18:33]
	ds_read_b128 v[208:211], v213 offset:32
	ds_read_b128 v[240:243], v215 offset:32
	ds_read_b128 v[174:177], v213 offset:4640
	ds_read_b128 v[244:247], v215 offset:4640
	ds_read_b128 v[200:203], v215 offset:9248
	ds_read_b128 v[204:207], v215 offset:13856
	s_waitcnt vmcnt(4)
	ds_write_b128 v179, v[134:137]
	ds_write_b128 v179, v[138:141] offset:16
	ds_write_b128 v179, v[142:145] offset:32
	ds_write_b128 v179, v[146:149] offset:48
	global_load_dwordx4 v[134:137], v[130:131], off offset:768
	global_load_dwordx4 v[138:141], v[130:131], off offset:784
	global_load_dwordx4 v[142:145], v[130:131], off offset:800
	global_load_dwordx4 v[146:149], v[130:131], off offset:816
	s_waitcnt lgkmcnt(14)
	v_mfma_f32_32x32x16_f16 v[114:129], v[232:235], v[216:219], v[114:129]
	s_waitcnt lgkmcnt(13)
	v_mfma_f32_32x32x16_f16 v[98:113], v[236:239], v[216:219], v[98:113]
	s_waitcnt lgkmcnt(12)
	v_mfma_f32_32x32x16_f16 v[82:97], v[232:235], v[220:223], v[82:97]
	v_mfma_f32_32x32x16_f16 v[66:81], v[236:239], v[220:223], v[66:81]
	s_waitcnt lgkmcnt(11)
	v_mfma_f32_32x32x16_f16 v[50:65], v[232:235], v[224:227], v[50:65]
	v_mfma_f32_32x32x16_f16 v[34:49], v[236:239], v[224:227], v[34:49]
	s_waitcnt lgkmcnt(10)
	v_mfma_f32_32x32x16_f16 v[2:17], v[232:235], v[228:231], v[2:17]
	v_mfma_f32_32x32x16_f16 v[18:33], v[236:239], v[228:231], v[18:33]
	ds_read_b128 v[232:235], v213 offset:64
	ds_read_b128 v[216:219], v215 offset:64
	ds_read_b128 v[236:239], v213 offset:4672
	ds_read_b128 v[220:223], v215 offset:4672
	ds_read_b128 v[224:227], v215 offset:9280
	ds_read_b128 v[228:231], v215 offset:13888
	s_waitcnt vmcnt(4)
	ds_write_b128 v179, v[150:153] offset:36864
	ds_write_b128 v179, v[154:157] offset:36880
	ds_write_b128 v179, v[158:161] offset:36896
	ds_write_b128 v179, v[162:165] offset:36912
	global_load_dwordx4 v[150:153], v[248:249], off offset:768
	global_load_dwordx4 v[154:157], v[248:249], off offset:784
	global_load_dwordx4 v[158:161], v[248:249], off offset:800
	global_load_dwordx4 v[162:165], v[248:249], off offset:816
	s_waitcnt lgkmcnt(15)
	v_mfma_f32_32x32x16_f16 v[114:129], v[208:211], v[240:243], v[114:129]
	s_waitcnt lgkmcnt(15)
	v_mfma_f32_32x32x16_f16 v[98:113], v[174:177], v[240:243], v[98:113]
	s_waitcnt lgkmcnt(15)
	v_mfma_f32_32x32x16_f16 v[82:97], v[208:211], v[244:247], v[82:97]
	v_mfma_f32_32x32x16_f16 v[66:81], v[174:177], v[244:247], v[66:81]
	s_waitcnt lgkmcnt(15)
	v_mfma_f32_32x32x16_f16 v[50:65], v[208:211], v[200:203], v[50:65]
	v_mfma_f32_32x32x16_f16 v[34:49], v[174:177], v[200:203], v[34:49]
	s_waitcnt lgkmcnt(14)
	v_mfma_f32_32x32x16_f16 v[2:17], v[208:211], v[204:207], v[2:17]
	v_mfma_f32_32x32x16_f16 v[18:33], v[174:177], v[204:207], v[18:33]
	ds_read_b128 v[208:211], v213 offset:96
	ds_read_b128 v[240:243], v215 offset:96
	ds_read_b128 v[174:177], v213 offset:4704
	ds_read_b128 v[244:247], v215 offset:4704
	ds_read_b128 v[200:203], v215 offset:9312
	ds_read_b128 v[204:207], v215 offset:13920
	s_waitcnt lgkmcnt(14)
	v_mfma_f32_32x32x16_f16 v[114:129], v[232:235], v[216:219], v[114:129]
	s_waitcnt lgkmcnt(13)
	v_mfma_f32_32x32x16_f16 v[98:113], v[236:239], v[216:219], v[98:113]
	s_waitcnt lgkmcnt(12)
	v_mfma_f32_32x32x16_f16 v[82:97], v[232:235], v[220:223], v[82:97]
	v_mfma_f32_32x32x16_f16 v[66:81], v[236:239], v[220:223], v[66:81]
	s_waitcnt lgkmcnt(11)
	v_mfma_f32_32x32x16_f16 v[50:65], v[232:235], v[224:227], v[50:65]
	v_mfma_f32_32x32x16_f16 v[34:49], v[236:239], v[224:227], v[34:49]
	s_waitcnt lgkmcnt(10)
	v_mfma_f32_32x32x16_f16 v[2:17], v[232:235], v[228:231], v[2:17]
	v_mfma_f32_32x32x16_f16 v[18:33], v[236:239], v[228:231], v[18:33]
	s_waitcnt lgkmcnt(0)
	s_barrier
; DI f16v mfma32(h8v a, h8v b, f16v c) { return __builtin_amdgcn_mfma_f32_32x32x16_f16(a, b, c, 0, 0, 0); }
; template <bool GATHER>
; DI void gemm256_main(const h16* __restrict__ A, int lda, const int* __restrict__ idx, int m0,
;                      const h16* __restrict__ B, int ldb, int n0, int K, h16* lds, f16v (&acc)[4][2]) {
;     ...
;   for (int kt = 0; kt < nk; ++kt) {
;     const h16* As = lds + (kt & 1) * (512 * LDH);
;     const h16* Bs = As + 256 * LDH;
;     h16* Wn = lds + ((kt & 1) ^ 1) * (512 * LDH);
;     if (kt + 1 < nk) {
; #pragma unroll
;       for (int i = 0; i < 4; ++i) { *(u4v*)&Wn[lr * LDH + lc + 8 * i] = ra[i]; *(u4v*)&Wn[(256 + lr) * LDH + lc + 8 * i] = rb[i]; }
;     }
;     if (kt + 2 < nk) {
; #pragma unroll
;       for (int i = 0; i < 4; ++i) { ra[i] = *(const u4v*)(AP_ + 8 * i); rb[i] = *(const u4v*)(BP_ + 8 * i); }
;       ao += 64; bo += 64;
;     }
; #pragma unroll
;     for (int ks = 0; ks < 4; ++ks) {
;       h8v af[4], bf[2];
; #pragma unroll
;       for (int i = 0; i < 4; ++i) af[i] = *(const h8v*)&As[(wm * 128 + i * 32 + (lane & 31)) * LDH + ks * 16 + 8 * (lane >> 5)];
; #pragma unroll
;       for (int j = 0; j < 2; ++j) bf[j] = *(const h8v*)&Bs[(wn * 64 + j * 32 + (lane & 31)) * LDH + ks * 16 + 8 * (lane >> 5)];
; #pragma unroll
;       for (int i = 0; i < 4; ++i)
; #pragma unroll
;         for (int j = 0; j < 2; ++j) acc[i][j] = mfma32(bf[j], af[i], acc[i][j]);
;     }
;     __syncthreads();
	ds_read_b128 v[232:235], v214
	ds_read_b128 v[216:219], v212
	ds_read_b128 v[236:239], v214 offset:4608
	ds_read_b128 v[220:223], v212 offset:4608
	ds_read_b128 v[224:227], v212 offset:9216
	ds_read_b128 v[228:231], v212 offset:13824
	v_mfma_f32_32x32x16_f16 v[114:129], v[208:211], v[240:243], v[114:129]
	v_mfma_f32_32x32x16_f16 v[98:113], v[174:177], v[240:243], v[98:113]
	v_mfma_f32_32x32x16_f16 v[82:97], v[208:211], v[244:247], v[82:97]
	v_mfma_f32_32x32x16_f16 v[66:81], v[174:177], v[244:247], v[66:81]
	v_mfma_f32_32x32x16_f16 v[50:65], v[208:211], v[200:203], v[50:65]
	v_mfma_f32_32x32x16_f16 v[34:49], v[174:177], v[200:203], v[34:49]
	v_mfma_f32_32x32x16_f16 v[2:17], v[208:211], v[204:207], v[2:17]
	v_mfma_f32_32x32x16_f16 v[18:33], v[174:177], v[204:207], v[18:33]
	ds_read_b128 v[208:211], v214 offset:32
	ds_read_b128 v[240:243], v212 offset:32
	ds_read_b128 v[174:177], v214 offset:4640
	ds_read_b128 v[244:247], v212 offset:4640
	ds_read_b128 v[200:203], v212 offset:9248
	ds_read_b128 v[204:207], v212 offset:13856
	s_waitcnt vmcnt(4)
	ds_write_b128 v178, v[134:137]
	ds_write_b128 v178, v[138:141] offset:16
	ds_write_b128 v178, v[142:145] offset:32
	ds_write_b128 v178, v[146:149] offset:48
	global_load_dwordx4 v[134:137], v[130:131], off offset:896
	global_load_dwordx4 v[138:141], v[130:131], off offset:912
	global_load_dwordx4 v[142:145], v[130:131], off offset:928
	global_load_dwordx4 v[146:149], v[130:131], off offset:944
	s_waitcnt lgkmcnt(14)
	v_mfma_f32_32x32x16_f16 v[114:129], v[232:235], v[216:219], v[114:129]
	s_waitcnt lgkmcnt(13)
	v_mfma_f32_32x32x16_f16 v[98:113], v[236:239], v[216:219], v[98:113]
	s_waitcnt lgkmcnt(12)
	v_mfma_f32_32x32x16_f16 v[82:97], v[232:235], v[220:223], v[82:97]
	v_mfma_f32_32x32x16_f16 v[66:81], v[236:239], v[220:223], v[66:81]
	s_waitcnt lgkmcnt(11)
	v_mfma_f32_32x32x16_f16 v[50:65], v[232:235], v[224:227], v[50:65]
	v_mfma_f32_32x32x16_f16 v[34:49], v[236:239], v[224:227], v[34:49]
	s_waitcnt lgkmcnt(10)
	v_mfma_f32_32x32x16_f16 v[2:17], v[232:235], v[228:231], v[2:17]
	v_mfma_f32_32x32x16_f16 v[18:33], v[236:239], v[228:231], v[18:33]
	ds_read_b128 v[232:235], v214 offset:64
	ds_read_b128 v[216:219], v212 offset:64
	ds_read_b128 v[236:239], v214 offset:4672
	ds_read_b128 v[220:223], v212 offset:4672
	ds_read_b128 v[224:227], v212 offset:9280
	ds_read_b128 v[228:231], v212 offset:13888
	s_waitcnt vmcnt(4)
	ds_write_b128 v178, v[150:153] offset:36864
	ds_write_b128 v178, v[154:157] offset:36880
	ds_write_b128 v178, v[158:161] offset:36896
	ds_write_b128 v178, v[162:165] offset:36912
	global_load_dwordx4 v[150:153], v[248:249], off offset:896
	global_load_dwordx4 v[154:157], v[248:249], off offset:912
	global_load_dwordx4 v[158:161], v[248:249], off offset:928
	global_load_dwordx4 v[162:165], v[248:249], off offset:944
	s_waitcnt lgkmcnt(15)
	v_mfma_f32_32x32x16_f16 v[114:129], v[208:211], v[240:243], v[114:129]
	s_waitcnt lgkmcnt(15)
	v_mfma_f32_32x32x16_f16 v[98:113], v[174:177], v[240:243], v[98:113]
	s_waitcnt lgkmcnt(15)
	v_mfma_f32_32x32x16_f16 v[82:97], v[208:211], v[244:247], v[82:97]
	v_mfma_f32_32x32x16_f16 v[66:81], v[174:177], v[244:247], v[66:81]
	s_waitcnt lgkmcnt(15)
	v_mfma_f32_32x32x16_f16 v[50:65], v[208:211], v[200:203], v[50:65]
	v_mfma_f32_32x32x16_f16 v[34:49], v[174:177], v[200:203], v[34:49]
	s_waitcnt lgkmcnt(14)
	v_mfma_f32_32x32x16_f16 v[2:17], v[208:211], v[204:207], v[2:17]
	v_mfma_f32_32x32x16_f16 v[18:33], v[174:177], v[204:207], v[18:33]
	ds_read_b128 v[208:211], v214 offset:96
	ds_read_b128 v[240:243], v212 offset:96
	ds_read_b128 v[174:177], v214 offset:4704
	ds_read_b128 v[244:247], v212 offset:4704
	ds_read_b128 v[200:203], v212 offset:9312
	ds_read_b128 v[204:207], v212 offset:13920
	s_waitcnt lgkmcnt(14)
	v_mfma_f32_32x32x16_f16 v[114:129], v[232:235], v[216:219], v[114:129]
	s_waitcnt lgkmcnt(13)
	v_mfma_f32_32x32x16_f16 v[98:113], v[236:239], v[216:219], v[98:113]
	s_waitcnt lgkmcnt(12)
	v_mfma_f32_32x32x16_f16 v[82:97], v[232:235], v[220:223], v[82:97]
	v_mfma_f32_32x32x16_f16 v[66:81], v[236:239], v[220:223], v[66:81]
	s_waitcnt lgkmcnt(11)
	v_mfma_f32_32x32x16_f16 v[50:65], v[232:235], v[224:227], v[50:65]
	v_mfma_f32_32x32x16_f16 v[34:49], v[236:239], v[224:227], v[34:49]
	s_waitcnt lgkmcnt(10)
	v_mfma_f32_32x32x16_f16 v[2:17], v[232:235], v[228:231], v[2:17]
	v_mfma_f32_32x32x16_f16 v[18:33], v[236:239], v[228:231], v[18:33]
	s_waitcnt lgkmcnt(0)
	s_barrier
; DI f16v mfma32(h8v a, h8v b, f16v c) { return __builtin_amdgcn_mfma_f32_32x32x16_f16(a, b, c, 0, 0, 0); }
; template <bool GATHER>
; DI void gemm256_main(const h16* __restrict__ A, int lda, const int* __restrict__ idx, int m0,
;                      const h16* __restrict__ B, int ldb, int n0, int K, h16* lds, f16v (&acc)[4][2]) {
;     ...
;   for (int kt = 0; kt < nk; ++kt) {
;     const h16* As = lds + (kt & 1) * (512 * LDH);
;     const h16* Bs = As + 256 * LDH;
;     h16* Wn = lds + ((kt & 1) ^ 1) * (512 * LDH);
;     if (kt + 1 < nk) {
; #pragma unroll
;       for (int i = 0; i < 4; ++i) { *(u4v*)&Wn[lr * LDH + lc + 8 * i] = ra[i]; *(u4v*)&Wn[(256 + lr) * LDH + lc + 8 * i] = rb[i]; }
;     }
;     if (kt + 2 < nk) {
; #pragma unroll
;       for (int i = 0; i < 4; ++i) { ra[i] = *(const u4v*)(AP_ + 8 * i); rb[i] = *(const u4v*)(BP_ + 8 * i); }
;       ao += 64; bo += 64;
;     }
; #pragma unroll
;     for (int ks = 0; ks < 4; ++ks) {
;       h8v af[4], bf[2];
; #pragma unroll
;       for (int i = 0; i < 4; ++i) af[i] = *(const h8v*)&As[(wm * 128 + i * 32 + (lane & 31)) * LDH + ks * 16 + 8 * (lane >> 5)];
; #pragma unroll
;       for (int j = 0; j < 2; ++j) bf[j] = *(const h8v*)&Bs[(wn * 64 + j * 32 + (lane & 31)) * LDH + ks * 16 + 8 * (lane >> 5)];
; #pragma unroll
;       for (int i = 0; i < 4; ++i)
; #pragma unroll
;         for (int j = 0; j < 2; ++j) acc[i][j] = mfma32(bf[j], af[i], acc[i][j]);
;     }
;     __syncthreads();
	ds_read_b128 v[232:235], v213
	ds_read_b128 v[216:219], v215
	ds_read_b128 v[236:239], v213 offset:4608
	ds_read_b128 v[220:223], v215 offset:4608
	ds_read_b128 v[224:227], v215 offset:9216
	ds_read_b128 v[228:231], v215 offset:13824
	v_mfma_f32_32x32x16_f16 v[114:129], v[208:211], v[240:243], v[114:129]
	v_mfma_f32_32x32x16_f16 v[98:113], v[174:177], v[240:243], v[98:113]
	v_mfma_f32_32x32x16_f16 v[82:97], v[208:211], v[244:247], v[82:97]
	v_mfma_f32_32x32x16_f16 v[66:81], v[174:177], v[244:247], v[66:81]
	v_mfma_f32_32x32x16_f16 v[50:65], v[208:211], v[200:203], v[50:65]
	v_mfma_f32_32x32x16_f16 v[34:49], v[174:177], v[200:203], v[34:49]
	v_mfma_f32_32x32x16_f16 v[2:17], v[208:211], v[204:207], v[2:17]
	v_mfma_f32_32x32x16_f16 v[18:33], v[174:177], v[204:207], v[18:33]
	ds_read_b128 v[208:211], v213 offset:32
	ds_read_b128 v[240:243], v215 offset:32
	ds_read_b128 v[174:177], v213 offset:4640
	ds_read_b128 v[244:247], v215 offset:4640
	ds_read_b128 v[200:203], v215 offset:9248
	ds_read_b128 v[204:207], v215 offset:13856
	s_waitcnt vmcnt(4)
	ds_write_b128 v179, v[134:137]
	ds_write_b128 v179, v[138:141] offset:16
	ds_write_b128 v179, v[142:145] offset:32
	ds_write_b128 v179, v[146:149] offset:48
	global_load_dwordx4 v[134:137], v[130:131], off offset:1024
	global_load_dwordx4 v[138:141], v[130:131], off offset:1040
	global_load_dwordx4 v[142:145], v[130:131], off offset:1056
	global_load_dwordx4 v[146:149], v[130:131], off offset:1072
	s_waitcnt lgkmcnt(14)
	v_mfma_f32_32x32x16_f16 v[114:129], v[232:235], v[216:219], v[114:129]
	s_waitcnt lgkmcnt(13)
	v_mfma_f32_32x32x16_f16 v[98:113], v[236:239], v[216:219], v[98:113]
	s_waitcnt lgkmcnt(12)
	v_mfma_f32_32x32x16_f16 v[82:97], v[232:235], v[220:223], v[82:97]
	v_mfma_f32_32x32x16_f16 v[66:81], v[236:239], v[220:223], v[66:81]
	s_waitcnt lgkmcnt(11)
	v_mfma_f32_32x32x16_f16 v[50:65], v[232:235], v[224:227], v[50:65]
	v_mfma_f32_32x32x16_f16 v[34:49], v[236:239], v[224:227], v[34:49]
	s_waitcnt lgkmcnt(10)
	v_mfma_f32_32x32x16_f16 v[2:17], v[232:235], v[228:231], v[2:17]
	v_mfma_f32_32x32x16_f16 v[18:33], v[236:239], v[228:231], v[18:33]
	ds_read_b128 v[232:235], v213 offset:64
	ds_read_b128 v[216:219], v215 offset:64
	ds_read_b128 v[236:239], v213 offset:4672
	ds_read_b128 v[220:223], v215 offset:4672
	ds_read_b128 v[224:227], v215 offset:9280
	ds_read_b128 v[228:231], v215 offset:13888
	s_waitcnt vmcnt(4)
	ds_write_b128 v179, v[150:153] offset:36864
	ds_write_b128 v179, v[154:157] offset:36880
	ds_write_b128 v179, v[158:161] offset:36896
	ds_write_b128 v179, v[162:165] offset:36912
	global_load_dwordx4 v[150:153], v[248:249], off offset:1024
	global_load_dwordx4 v[154:157], v[248:249], off offset:1040
	global_load_dwordx4 v[158:161], v[248:249], off offset:1056
	global_load_dwordx4 v[162:165], v[248:249], off offset:1072
	s_waitcnt lgkmcnt(15)
	v_mfma_f32_32x32x16_f16 v[114:129], v[208:211], v[240:243], v[114:129]
	s_waitcnt lgkmcnt(15)
	v_mfma_f32_32x32x16_f16 v[98:113], v[174:177], v[240:243], v[98:113]
	s_waitcnt lgkmcnt(15)
	v_mfma_f32_32x32x16_f16 v[82:97], v[208:211], v[244:247], v[82:97]
	v_mfma_f32_32x32x16_f16 v[66:81], v[174:177], v[244:247], v[66:81]
	s_waitcnt lgkmcnt(15)
	v_mfma_f32_32x32x16_f16 v[50:65], v[208:211], v[200:203], v[50:65]
	v_mfma_f32_32x32x16_f16 v[34:49], v[174:177], v[200:203], v[34:49]
	s_waitcnt lgkmcnt(14)
	v_mfma_f32_32x32x16_f16 v[2:17], v[208:211], v[204:207], v[2:17]
	v_mfma_f32_32x32x16_f16 v[18:33], v[174:177], v[204:207], v[18:33]
	ds_read_b128 v[208:211], v213 offset:96
	ds_read_b128 v[240:243], v215 offset:96
	ds_read_b128 v[174:177], v213 offset:4704
	ds_read_b128 v[244:247], v215 offset:4704
	ds_read_b128 v[200:203], v215 offset:9312
	ds_read_b128 v[204:207], v215 offset:13920
	s_waitcnt lgkmcnt(14)
	v_mfma_f32_32x32x16_f16 v[114:129], v[232:235], v[216:219], v[114:129]
	s_waitcnt lgkmcnt(13)
	v_mfma_f32_32x32x16_f16 v[98:113], v[236:239], v[216:219], v[98:113]
	s_waitcnt lgkmcnt(12)
	v_mfma_f32_32x32x16_f16 v[82:97], v[232:235], v[220:223], v[82:97]
	v_mfma_f32_32x32x16_f16 v[66:81], v[236:239], v[220:223], v[66:81]
	s_waitcnt lgkmcnt(11)
	v_mfma_f32_32x32x16_f16 v[50:65], v[232:235], v[224:227], v[50:65]
	v_mfma_f32_32x32x16_f16 v[34:49], v[236:239], v[224:227], v[34:49]
	s_waitcnt lgkmcnt(10)
	v_mfma_f32_32x32x16_f16 v[2:17], v[232:235], v[228:231], v[2:17]
	v_mfma_f32_32x32x16_f16 v[18:33], v[236:239], v[228:231], v[18:33]
	s_waitcnt lgkmcnt(0)
	s_barrier
; DI f16v mfma32(h8v a, h8v b, f16v c) { return __builtin_amdgcn_mfma_f32_32x32x16_f16(a, b, c, 0, 0, 0); }
; template <bool GATHER>
; DI void gemm256_main(const h16* __restrict__ A, int lda, const int* __restrict__ idx, int m0,
;                      const h16* __restrict__ B, int ldb, int n0, int K, h16* lds, f16v (&acc)[4][2]) {
;     ...
;   for (int kt = 0; kt < nk; ++kt) {
;     const h16* As = lds + (kt & 1) * (512 * LDH);
;     const h16* Bs = As + 256 * LDH;
;     h16* Wn = lds + ((kt & 1) ^ 1) * (512 * LDH);
;     if (kt + 1 < nk) {
; #pragma unroll
;       for (int i = 0; i < 4; ++i) { *(u4v*)&Wn[lr * LDH + lc + 8 * i] = ra[i]; *(u4v*)&Wn[(256 + lr) * LDH + lc + 8 * i] = rb[i]; }
;     }
;     if (kt + 2 < nk) {
; #pragma unroll
;       for (int i = 0; i < 4; ++i) { ra[i] = *(const u4v*)(AP_ + 8 * i); rb[i] = *(const u4v*)(BP_ + 8 * i); }
;       ao += 64; bo += 64;
;     }
; #pragma unroll
;     for (int ks = 0; ks < 4; ++ks) {
;       h8v af[4], bf[2];
; #pragma unroll
;       for (int i = 0; i < 4; ++i) af[i] = *(const h8v*)&As[(wm * 128 + i * 32 + (lane & 31)) * LDH + ks * 16 + 8 * (lane >> 5)];
; #pragma unroll
;       for (int j = 0; j < 2; ++j) bf[j] = *(const h8v*)&Bs[(wn * 64 + j * 32 + (lane & 31)) * LDH + ks * 16 + 8 * (lane >> 5)];
; #pragma unroll
;       for (int i = 0; i < 4; ++i)
; #pragma unroll
;         for (int j = 0; j < 2; ++j) acc[i][j] = mfma32(bf[j], af[i], acc[i][j]);
;     }
;     __syncthreads();
	ds_read_b128 v[232:235], v214
	ds_read_b128 v[216:219], v212
	ds_read_b128 v[236:239], v214 offset:4608
	ds_read_b128 v[220:223], v212 offset:4608
	ds_read_b128 v[224:227], v212 offset:9216
	ds_read_b128 v[228:231], v212 offset:13824
	v_mfma_f32_32x32x16_f16 v[114:129], v[208:211], v[240:243], v[114:129]
	v_mfma_f32_32x32x16_f16 v[98:113], v[174:177], v[240:243], v[98:113]
	v_mfma_f32_32x32x16_f16 v[82:97], v[208:211], v[244:247], v[82:97]
	v_mfma_f32_32x32x16_f16 v[66:81], v[174:177], v[244:247], v[66:81]
	v_mfma_f32_32x32x16_f16 v[50:65], v[208:211], v[200:203], v[50:65]
	v_mfma_f32_32x32x16_f16 v[34:49], v[174:177], v[200:203], v[34:49]
	v_mfma_f32_32x32x16_f16 v[2:17], v[208:211], v[204:207], v[2:17]
	v_mfma_f32_32x32x16_f16 v[18:33], v[174:177], v[204:207], v[18:33]
	ds_read_b128 v[208:211], v214 offset:32
	ds_read_b128 v[240:243], v212 offset:32
	ds_read_b128 v[174:177], v214 offset:4640
	ds_read_b128 v[244:247], v212 offset:4640
	ds_read_b128 v[200:203], v212 offset:9248
	ds_read_b128 v[204:207], v212 offset:13856
	s_waitcnt vmcnt(4)
	ds_write_b128 v178, v[134:137]
	ds_write_b128 v178, v[138:141] offset:16
	ds_write_b128 v178, v[142:145] offset:32
	ds_write_b128 v178, v[146:149] offset:48
	global_load_dwordx4 v[134:137], v[130:131], off offset:1152
	global_load_dwordx4 v[138:141], v[130:131], off offset:1168
	global_load_dwordx4 v[142:145], v[130:131], off offset:1184
	global_load_dwordx4 v[146:149], v[130:131], off offset:1200
	s_waitcnt lgkmcnt(14)
	v_mfma_f32_32x32x16_f16 v[114:129], v[232:235], v[216:219], v[114:129]
	s_waitcnt lgkmcnt(13)
	v_mfma_f32_32x32x16_f16 v[98:113], v[236:239], v[216:219], v[98:113]
	s_waitcnt lgkmcnt(12)
	v_mfma_f32_32x32x16_f16 v[82:97], v[232:235], v[220:223], v[82:97]
	v_mfma_f32_32x32x16_f16 v[66:81], v[236:239], v[220:223], v[66:81]
	s_waitcnt lgkmcnt(11)
	v_mfma_f32_32x32x16_f16 v[50:65], v[232:235], v[224:227], v[50:65]
	v_mfma_f32_32x32x16_f16 v[34:49], v[236:239], v[224:227], v[34:49]
	s_waitcnt lgkmcnt(10)
	v_mfma_f32_32x32x16_f16 v[2:17], v[232:235], v[228:231], v[2:17]
	v_mfma_f32_32x32x16_f16 v[18:33], v[236:239], v[228:231], v[18:33]
	ds_read_b128 v[232:235], v214 offset:64
	ds_read_b128 v[216:219], v212 offset:64
	ds_read_b128 v[236:239], v214 offset:4672
	ds_read_b128 v[220:223], v212 offset:4672
	ds_read_b128 v[224:227], v212 offset:9280
	ds_read_b128 v[228:231], v212 offset:13888
	s_waitcnt vmcnt(4)
	ds_write_b128 v178, v[150:153] offset:36864
	ds_write_b128 v178, v[154:157] offset:36880
	ds_write_b128 v178, v[158:161] offset:36896
	ds_write_b128 v178, v[162:165] offset:36912
	global_load_dwordx4 v[150:153], v[248:249], off offset:1152
	global_load_dwordx4 v[154:157], v[248:249], off offset:1168
	global_load_dwordx4 v[158:161], v[248:249], off offset:1184
	global_load_dwordx4 v[162:165], v[248:249], off offset:1200
	s_waitcnt lgkmcnt(15)
	v_mfma_f32_32x32x16_f16 v[114:129], v[208:211], v[240:243], v[114:129]
	s_waitcnt lgkmcnt(15)
	v_mfma_f32_32x32x16_f16 v[98:113], v[174:177], v[240:243], v[98:113]
	s_waitcnt lgkmcnt(15)
	v_mfma_f32_32x32x16_f16 v[82:97], v[208:211], v[244:247], v[82:97]
	v_mfma_f32_32x32x16_f16 v[66:81], v[174:177], v[244:247], v[66:81]
	s_waitcnt lgkmcnt(15)
	v_mfma_f32_32x32x16_f16 v[50:65], v[208:211], v[200:203], v[50:65]
	v_mfma_f32_32x32x16_f16 v[34:49], v[174:177], v[200:203], v[34:49]
	s_waitcnt lgkmcnt(14)
	v_mfma_f32_32x32x16_f16 v[2:17], v[208:211], v[204:207], v[2:17]
	v_mfma_f32_32x32x16_f16 v[18:33], v[174:177], v[204:207], v[18:33]
	ds_read_b128 v[208:211], v214 offset:96
	ds_read_b128 v[240:243], v212 offset:96
	ds_read_b128 v[174:177], v214 offset:4704
	ds_read_b128 v[244:247], v212 offset:4704
	ds_read_b128 v[200:203], v212 offset:9312
	ds_read_b128 v[204:207], v212 offset:13920
	s_waitcnt lgkmcnt(14)
	v_mfma_f32_32x32x16_f16 v[114:129], v[232:235], v[216:219], v[114:129]
	s_waitcnt lgkmcnt(13)
	v_mfma_f32_32x32x16_f16 v[98:113], v[236:239], v[216:219], v[98:113]
	s_waitcnt lgkmcnt(12)
	v_mfma_f32_32x32x16_f16 v[82:97], v[232:235], v[220:223], v[82:97]
	v_mfma_f32_32x32x16_f16 v[66:81], v[236:239], v[220:223], v[66:81]
	s_waitcnt lgkmcnt(11)
	v_mfma_f32_32x32x16_f16 v[50:65], v[232:235], v[224:227], v[50:65]
	v_mfma_f32_32x32x16_f16 v[34:49], v[236:239], v[224:227], v[34:49]
	s_waitcnt lgkmcnt(10)
	v_mfma_f32_32x32x16_f16 v[2:17], v[232:235], v[228:231], v[2:17]
	v_mfma_f32_32x32x16_f16 v[18:33], v[236:239], v[228:231], v[18:33]
	s_waitcnt lgkmcnt(0)
	s_barrier
; DI f16v mfma32(h8v a, h8v b, f16v c) { return __builtin_amdgcn_mfma_f32_32x32x16_f16(a, b, c, 0, 0, 0); }
; template <bool GATHER>
; DI void gemm256_main(const h16* __restrict__ A, int lda, const int* __restrict__ idx, int m0,
;                      const h16* __restrict__ B, int ldb, int n0, int K, h16* lds, f16v (&acc)[4][2]) {
;     ...
;   for (int kt = 0; kt < nk; ++kt) {
;     const h16* As = lds + (kt & 1) * (512 * LDH);
;     const h16* Bs = As + 256 * LDH;
;     h16* Wn = lds + ((kt & 1) ^ 1) * (512 * LDH);
;     if (kt + 1 < nk) {
; #pragma unroll
;       for (int i = 0; i < 4; ++i) { *(u4v*)&Wn[lr * LDH + lc + 8 * i] = ra[i]; *(u4v*)&Wn[(256 + lr) * LDH + lc + 8 * i] = rb[i]; }
;     }
;     if (kt + 2 < nk) {
; #pragma unroll
;       for (int i = 0; i < 4; ++i) { ra[i] = *(const u4v*)(AP_ + 8 * i); rb[i] = *(const u4v*)(BP_ + 8 * i); }
;       ao += 64; bo += 64;
;     }
; #pragma unroll
;     for (int ks = 0; ks < 4; ++ks) {
;       h8v af[4], bf[2];
; #pragma unroll
;       for (int i = 0; i < 4; ++i) af[i] = *(const h8v*)&As[(wm * 128 + i * 32 + (lane & 31)) * LDH + ks * 16 + 8 * (lane >> 5)];
; #pragma unroll
;       for (int j = 0; j < 2; ++j) bf[j] = *(const h8v*)&Bs[(wn * 64 + j * 32 + (lane & 31)) * LDH + ks * 16 + 8 * (lane >> 5)];
; #pragma unroll
;       for (int i = 0; i < 4; ++i)
; #pragma unroll
;         for (int j = 0; j < 2; ++j) acc[i][j] = mfma32(bf[j], af[i], acc[i][j]);
;     }
;     __syncthreads();
	ds_read_b128 v[232:235], v213
	ds_read_b128 v[216:219], v215
	ds_read_b128 v[236:239], v213 offset:4608
	ds_read_b128 v[220:223], v215 offset:4608
	ds_read_b128 v[224:227], v215 offset:9216
	ds_read_b128 v[228:231], v215 offset:13824
	v_mfma_f32_32x32x16_f16 v[114:129], v[208:211], v[240:243], v[114:129]
	v_mfma_f32_32x32x16_f16 v[98:113], v[174:177], v[240:243], v[98:113]
	v_mfma_f32_32x32x16_f16 v[82:97], v[208:211], v[244:247], v[82:97]
	v_mfma_f32_32x32x16_f16 v[66:81], v[174:177], v[244:247], v[66:81]
	v_mfma_f32_32x32x16_f16 v[50:65], v[208:211], v[200:203], v[50:65]
	v_mfma_f32_32x32x16_f16 v[34:49], v[174:177], v[200:203], v[34:49]
	v_mfma_f32_32x32x16_f16 v[2:17], v[208:211], v[204:207], v[2:17]
	v_mfma_f32_32x32x16_f16 v[18:33], v[174:177], v[204:207], v[18:33]
	ds_read_b128 v[208:211], v213 offset:32
	ds_read_b128 v[240:243], v215 offset:32
	ds_read_b128 v[174:177], v213 offset:4640
	ds_read_b128 v[244:247], v215 offset:4640
	ds_read_b128 v[200:203], v215 offset:9248
	ds_read_b128 v[204:207], v215 offset:13856
	s_waitcnt vmcnt(4)
	ds_write_b128 v179, v[134:137]
	ds_write_b128 v179, v[138:141] offset:16
	ds_write_b128 v179, v[142:145] offset:32
	ds_write_b128 v179, v[146:149] offset:48
	global_load_dwordx4 v[134:137], v[130:131], off offset:1280
	global_load_dwordx4 v[138:141], v[130:131], off offset:1296
	global_load_dwordx4 v[142:145], v[130:131], off offset:1312
	global_load_dwordx4 v[146:149], v[130:131], off offset:1328
	s_waitcnt lgkmcnt(14)
	v_mfma_f32_32x32x16_f16 v[114:129], v[232:235], v[216:219], v[114:129]
	s_waitcnt lgkmcnt(13)
	v_mfma_f32_32x32x16_f16 v[98:113], v[236:239], v[216:219], v[98:113]
	s_waitcnt lgkmcnt(12)
	v_mfma_f32_32x32x16_f16 v[82:97], v[232:235], v[220:223], v[82:97]
	v_mfma_f32_32x32x16_f16 v[66:81], v[236:239], v[220:223], v[66:81]
	s_waitcnt lgkmcnt(11)
	v_mfma_f32_32x32x16_f16 v[50:65], v[232:235], v[224:227], v[50:65]
	v_mfma_f32_32x32x16_f16 v[34:49], v[236:239], v[224:227], v[34:49]
	s_waitcnt lgkmcnt(10)
	v_mfma_f32_32x32x16_f16 v[2:17], v[232:235], v[228:231], v[2:17]
	v_mfma_f32_32x32x16_f16 v[18:33], v[236:239], v[228:231], v[18:33]
	ds_read_b128 v[232:235], v213 offset:64
	ds_read_b128 v[216:219], v215 offset:64
	ds_read_b128 v[236:239], v213 offset:4672
	ds_read_b128 v[220:223], v215 offset:4672
	ds_read_b128 v[224:227], v215 offset:9280
	ds_read_b128 v[228:231], v215 offset:13888
	s_waitcnt vmcnt(4)
	ds_write_b128 v179, v[150:153] offset:36864
	ds_write_b128 v179, v[154:157] offset:36880
	ds_write_b128 v179, v[158:161] offset:36896
	ds_write_b128 v179, v[162:165] offset:36912
	global_load_dwordx4 v[150:153], v[248:249], off offset:1280
	global_load_dwordx4 v[154:157], v[248:249], off offset:1296
	global_load_dwordx4 v[158:161], v[248:249], off offset:1312
	global_load_dwordx4 v[162:165], v[248:249], off offset:1328
	s_waitcnt lgkmcnt(15)
	v_mfma_f32_32x32x16_f16 v[114:129], v[208:211], v[240:243], v[114:129]
	s_waitcnt lgkmcnt(15)
	v_mfma_f32_32x32x16_f16 v[98:113], v[174:177], v[240:243], v[98:113]
	s_waitcnt lgkmcnt(15)
	v_mfma_f32_32x32x16_f16 v[82:97], v[208:211], v[244:247], v[82:97]
	v_mfma_f32_32x32x16_f16 v[66:81], v[174:177], v[244:247], v[66:81]
	s_waitcnt lgkmcnt(15)
	v_mfma_f32_32x32x16_f16 v[50:65], v[208:211], v[200:203], v[50:65]
	v_mfma_f32_32x32x16_f16 v[34:49], v[174:177], v[200:203], v[34:49]
	s_waitcnt lgkmcnt(14)
	v_mfma_f32_32x32x16_f16 v[2:17], v[208:211], v[204:207], v[2:17]
	v_mfma_f32_32x32x16_f16 v[18:33], v[174:177], v[204:207], v[18:33]
	ds_read_b128 v[208:211], v213 offset:96
	ds_read_b128 v[240:243], v215 offset:96
	ds_read_b128 v[174:177], v213 offset:4704
	ds_read_b128 v[244:247], v215 offset:4704
	ds_read_b128 v[200:203], v215 offset:9312
	ds_read_b128 v[204:207], v215 offset:13920
	s_waitcnt lgkmcnt(14)
	v_mfma_f32_32x32x16_f16 v[114:129], v[232:235], v[216:219], v[114:129]
	s_waitcnt lgkmcnt(13)
	v_mfma_f32_32x32x16_f16 v[98:113], v[236:239], v[216:219], v[98:113]
	s_waitcnt lgkmcnt(12)
	v_mfma_f32_32x32x16_f16 v[82:97], v[232:235], v[220:223], v[82:97]
	v_mfma_f32_32x32x16_f16 v[66:81], v[236:239], v[220:223], v[66:81]
	s_waitcnt lgkmcnt(11)
	v_mfma_f32_32x32x16_f16 v[50:65], v[232:235], v[224:227], v[50:65]
	v_mfma_f32_32x32x16_f16 v[34:49], v[236:239], v[224:227], v[34:49]
	s_waitcnt lgkmcnt(10)
	v_mfma_f32_32x32x16_f16 v[2:17], v[232:235], v[228:231], v[2:17]
	v_mfma_f32_32x32x16_f16 v[18:33], v[236:239], v[228:231], v[18:33]
	s_waitcnt lgkmcnt(0)
	s_barrier
; DI f16v mfma32(h8v a, h8v b, f16v c) { return __builtin_amdgcn_mfma_f32_32x32x16_f16(a, b, c, 0, 0, 0); }
; template <bool GATHER>
; DI void gemm256_main(const h16* __restrict__ A, int lda, const int* __restrict__ idx, int m0,
;                      const h16* __restrict__ B, int ldb, int n0, int K, h16* lds, f16v (&acc)[4][2]) {
;     ...
;   for (int kt = 0; kt < nk; ++kt) {
;     const h16* As = lds + (kt & 1) * (512 * LDH);
;     const h16* Bs = As + 256 * LDH;
;     h16* Wn = lds + ((kt & 1) ^ 1) * (512 * LDH);
;     if (kt + 1 < nk) {
; #pragma unroll
;       for (int i = 0; i < 4; ++i) { *(u4v*)&Wn[lr * LDH + lc + 8 * i] = ra[i]; *(u4v*)&Wn[(256 + lr) * LDH + lc + 8 * i] = rb[i]; }
;     }
;     if (kt + 2 < nk) {
; #pragma unroll
;       for (int i = 0; i < 4; ++i) { ra[i] = *(const u4v*)(AP_ + 8 * i); rb[i] = *(const u4v*)(BP_ + 8 * i); }
;       ao += 64; bo += 64;
;     }
; #pragma unroll
;     for (int ks = 0; ks < 4; ++ks) {
;       h8v af[4], bf[2];
; #pragma unroll
;       for (int i = 0; i < 4; ++i) af[i] = *(const h8v*)&As[(wm * 128 + i * 32 + (lane & 31)) * LDH + ks * 16 + 8 * (lane >> 5)];
; #pragma unroll
;       for (int j = 0; j < 2; ++j) bf[j] = *(const h8v*)&Bs[(wn * 64 + j * 32 + (lane & 31)) * LDH + ks * 16 + 8 * (lane >> 5)];
; #pragma unroll
;       for (int i = 0; i < 4; ++i)
; #pragma unroll
;         for (int j = 0; j < 2; ++j) acc[i][j] = mfma32(bf[j], af[i], acc[i][j]);
;     }
;     __syncthreads();
	ds_read_b128 v[232:235], v214
	ds_read_b128 v[216:219], v212
	ds_read_b128 v[236:239], v214 offset:4608
	ds_read_b128 v[220:223], v212 offset:4608
	ds_read_b128 v[224:227], v212 offset:9216
	ds_read_b128 v[228:231], v212 offset:13824
	v_mfma_f32_32x32x16_f16 v[114:129], v[208:211], v[240:243], v[114:129]
	v_mfma_f32_32x32x16_f16 v[98:113], v[174:177], v[240:243], v[98:113]
	v_mfma_f32_32x32x16_f16 v[82:97], v[208:211], v[244:247], v[82:97]
	v_mfma_f32_32x32x16_f16 v[66:81], v[174:177], v[244:247], v[66:81]
	v_mfma_f32_32x32x16_f16 v[50:65], v[208:211], v[200:203], v[50:65]
	v_mfma_f32_32x32x16_f16 v[34:49], v[174:177], v[200:203], v[34:49]
	v_mfma_f32_32x32x16_f16 v[2:17], v[208:211], v[204:207], v[2:17]
	v_mfma_f32_32x32x16_f16 v[18:33], v[174:177], v[204:207], v[18:33]
	ds_read_b128 v[208:211], v214 offset:32
	ds_read_b128 v[240:243], v212 offset:32
	ds_read_b128 v[174:177], v214 offset:4640
	ds_read_b128 v[244:247], v212 offset:4640
	ds_read_b128 v[200:203], v212 offset:9248
	ds_read_b128 v[204:207], v212 offset:13856
	s_waitcnt vmcnt(4)
	ds_write_b128 v178, v[134:137]
	ds_write_b128 v178, v[138:141] offset:16
	ds_write_b128 v178, v[142:145] offset:32
	ds_write_b128 v178, v[146:149] offset:48
	global_load_dwordx4 v[134:137], v[130:131], off offset:1408
	global_load_dwordx4 v[138:141], v[130:131], off offset:1424
	global_load_dwordx4 v[142:145], v[130:131], off offset:1440
	global_load_dwordx4 v[146:149], v[130:131], off offset:1456
	s_waitcnt lgkmcnt(14)
	v_mfma_f32_32x32x16_f16 v[114:129], v[232:235], v[216:219], v[114:129]
	s_waitcnt lgkmcnt(13)
	v_mfma_f32_32x32x16_f16 v[98:113], v[236:239], v[216:219], v[98:113]
	s_waitcnt lgkmcnt(12)
	v_mfma_f32_32x32x16_f16 v[82:97], v[232:235], v[220:223], v[82:97]
	v_mfma_f32_32x32x16_f16 v[66:81], v[236:239], v[220:223], v[66:81]
	s_waitcnt lgkmcnt(11)
	v_mfma_f32_32x32x16_f16 v[50:65], v[232:235], v[224:227], v[50:65]
	v_mfma_f32_32x32x16_f16 v[34:49], v[236:239], v[224:227], v[34:49]
	s_waitcnt lgkmcnt(10)
	v_mfma_f32_32x32x16_f16 v[2:17], v[232:235], v[228:231], v[2:17]
	v_mfma_f32_32x32x16_f16 v[18:33], v[236:239], v[228:231], v[18:33]
	ds_read_b128 v[232:235], v214 offset:64
	ds_read_b128 v[216:219], v212 offset:64
	ds_read_b128 v[236:239], v214 offset:4672
	ds_read_b128 v[220:223], v212 offset:4672
	ds_read_b128 v[224:227], v212 offset:9280
	ds_read_b128 v[228:231], v212 offset:13888
	s_waitcnt vmcnt(4)
	ds_write_b128 v178, v[150:153] offset:36864
	ds_write_b128 v178, v[154:157] offset:36880
	ds_write_b128 v178, v[158:161] offset:36896
	ds_write_b128 v178, v[162:165] offset:36912
	global_load_dwordx4 v[150:153], v[248:249], off offset:1408
	global_load_dwordx4 v[154:157], v[248:249], off offset:1424
	global_load_dwordx4 v[158:161], v[248:249], off offset:1440
	global_load_dwordx4 v[162:165], v[248:249], off offset:1456
	s_waitcnt lgkmcnt(15)
	v_mfma_f32_32x32x16_f16 v[114:129], v[208:211], v[240:243], v[114:129]
	s_waitcnt lgkmcnt(15)
	v_mfma_f32_32x32x16_f16 v[98:113], v[174:177], v[240:243], v[98:113]
	s_waitcnt lgkmcnt(15)
	v_mfma_f32_32x32x16_f16 v[82:97], v[208:211], v[244:247], v[82:97]
	v_mfma_f32_32x32x16_f16 v[66:81], v[174:177], v[244:247], v[66:81]
	s_waitcnt lgkmcnt(15)
	v_mfma_f32_32x32x16_f16 v[50:65], v[208:211], v[200:203], v[50:65]
	v_mfma_f32_32x32x16_f16 v[34:49], v[174:177], v[200:203], v[34:49]
	s_waitcnt lgkmcnt(14)
	v_mfma_f32_32x32x16_f16 v[2:17], v[208:211], v[204:207], v[2:17]
	v_mfma_f32_32x32x16_f16 v[18:33], v[174:177], v[204:207], v[18:33]
	ds_read_b128 v[208:211], v214 offset:96
	ds_read_b128 v[240:243], v212 offset:96
	ds_read_b128 v[174:177], v214 offset:4704
	ds_read_b128 v[244:247], v212 offset:4704
	ds_read_b128 v[200:203], v212 offset:9312
	ds_read_b128 v[204:207], v212 offset:13920
	s_waitcnt lgkmcnt(14)
	v_mfma_f32_32x32x16_f16 v[114:129], v[232:235], v[216:219], v[114:129]
	s_waitcnt lgkmcnt(13)
	v_mfma_f32_32x32x16_f16 v[98:113], v[236:239], v[216:219], v[98:113]
	s_waitcnt lgkmcnt(12)
	v_mfma_f32_32x32x16_f16 v[82:97], v[232:235], v[220:223], v[82:97]
	v_mfma_f32_32x32x16_f16 v[66:81], v[236:239], v[220:223], v[66:81]
	s_waitcnt lgkmcnt(11)
	v_mfma_f32_32x32x16_f16 v[50:65], v[232:235], v[224:227], v[50:65]
	v_mfma_f32_32x32x16_f16 v[34:49], v[236:239], v[224:227], v[34:49]
	s_waitcnt lgkmcnt(10)
	v_mfma_f32_32x32x16_f16 v[2:17], v[232:235], v[228:231], v[2:17]
	v_mfma_f32_32x32x16_f16 v[18:33], v[236:239], v[228:231], v[18:33]
	s_waitcnt lgkmcnt(0)
	s_barrier
; DI f16v mfma32(h8v a, h8v b, f16v c) { return __builtin_amdgcn_mfma_f32_32x32x16_f16(a, b, c, 0, 0, 0); }
; template <bool GATHER>
; DI void gemm256_main(const h16* __restrict__ A, int lda, const int* __restrict__ idx, int m0,
;                      const h16* __restrict__ B, int ldb, int n0, int K, h16* lds, f16v (&acc)[4][2]) {
;     ...
;   for (int kt = 0; kt < nk; ++kt) {
;     const h16* As = lds + (kt & 1) * (512 * LDH);
;     const h16* Bs = As + 256 * LDH;
;     h16* Wn = lds + ((kt & 1) ^ 1) * (512 * LDH);
;     if (kt + 1 < nk) {
; #pragma unroll
;       for (int i = 0; i < 4; ++i) { *(u4v*)&Wn[lr * LDH + lc + 8 * i] = ra[i]; *(u4v*)&Wn[(256 + lr) * LDH + lc + 8 * i] = rb[i]; }
;     }
;     if (kt + 2 < nk) {
; #pragma unroll
;       for (int i = 0; i < 4; ++i) { ra[i] = *(const u4v*)(AP_ + 8 * i); rb[i] = *(const u4v*)(BP_ + 8 * i); }
;       ao += 64; bo += 64;
;     }
; #pragma unroll
;     for (int ks = 0; ks < 4; ++ks) {
;       h8v af[4], bf[2];
; #pragma unroll
;       for (int i = 0; i < 4; ++i) af[i] = *(const h8v*)&As[(wm * 128 + i * 32 + (lane & 31)) * LDH + ks * 16 + 8 * (lane >> 5)];
; #pragma unroll
;       for (int j = 0; j < 2; ++j) bf[j] = *(const h8v*)&Bs[(wn * 64 + j * 32 + (lane & 31)) * LDH + ks * 16 + 8 * (lane >> 5)];
; #pragma unroll
;       for (int i = 0; i < 4; ++i)
; #pragma unroll
;         for (int j = 0; j < 2; ++j) acc[i][j] = mfma32(bf[j], af[i], acc[i][j]);
;     }
;     __syncthreads();
	ds_read_b128 v[232:235], v213
	ds_read_b128 v[216:219], v215
	ds_read_b128 v[236:239], v213 offset:4608
	ds_read_b128 v[220:223], v215 offset:4608
	ds_read_b128 v[224:227], v215 offset:9216
	ds_read_b128 v[228:231], v215 offset:13824
	v_mfma_f32_32x32x16_f16 v[114:129], v[208:211], v[240:243], v[114:129]
	v_mfma_f32_32x32x16_f16 v[98:113], v[174:177], v[240:243], v[98:113]
	v_mfma_f32_32x32x16_f16 v[82:97], v[208:211], v[244:247], v[82:97]
	v_mfma_f32_32x32x16_f16 v[66:81], v[174:177], v[244:247], v[66:81]
	v_mfma_f32_32x32x16_f16 v[50:65], v[208:211], v[200:203], v[50:65]
	v_mfma_f32_32x32x16_f16 v[34:49], v[174:177], v[200:203], v[34:49]
	v_mfma_f32_32x32x16_f16 v[2:17], v[208:211], v[204:207], v[2:17]
	v_mfma_f32_32x32x16_f16 v[18:33], v[174:177], v[204:207], v[18:33]
	ds_read_b128 v[208:211], v213 offset:32
	ds_read_b128 v[240:243], v215 offset:32
	ds_read_b128 v[174:177], v213 offset:4640
	ds_read_b128 v[244:247], v215 offset:4640
	ds_read_b128 v[200:203], v215 offset:9248
	ds_read_b128 v[204:207], v215 offset:13856
	s_waitcnt vmcnt(4)
	ds_write_b128 v179, v[134:137]
	ds_write_b128 v179, v[138:141] offset:16
	ds_write_b128 v179, v[142:145] offset:32
	ds_write_b128 v179, v[146:149] offset:48
	global_load_dwordx4 v[134:137], v[130:131], off offset:1536
	global_load_dwordx4 v[138:141], v[130:131], off offset:1552
	global_load_dwordx4 v[142:145], v[130:131], off offset:1568
	global_load_dwordx4 v[146:149], v[130:131], off offset:1584
	s_waitcnt lgkmcnt(14)
	v_mfma_f32_32x32x16_f16 v[114:129], v[232:235], v[216:219], v[114:129]
	s_waitcnt lgkmcnt(13)
	v_mfma_f32_32x32x16_f16 v[98:113], v[236:239], v[216:219], v[98:113]
	s_waitcnt lgkmcnt(12)
	v_mfma_f32_32x32x16_f16 v[82:97], v[232:235], v[220:223], v[82:97]
	v_mfma_f32_32x32x16_f16 v[66:81], v[236:239], v[220:223], v[66:81]
	s_waitcnt lgkmcnt(11)
	v_mfma_f32_32x32x16_f16 v[50:65], v[232:235], v[224:227], v[50:65]
	v_mfma_f32_32x32x16_f16 v[34:49], v[236:239], v[224:227], v[34:49]
	s_waitcnt lgkmcnt(10)
	v_mfma_f32_32x32x16_f16 v[2:17], v[232:235], v[228:231], v[2:17]
	v_mfma_f32_32x32x16_f16 v[18:33], v[236:239], v[228:231], v[18:33]
	ds_read_b128 v[232:235], v213 offset:64
	ds_read_b128 v[216:219], v215 offset:64
	ds_read_b128 v[236:239], v213 offset:4672
	ds_read_b128 v[220:223], v215 offset:4672
	ds_read_b128 v[224:227], v215 offset:9280
	ds_read_b128 v[228:231], v215 offset:13888
	s_waitcnt vmcnt(4)
	ds_write_b128 v179, v[150:153] offset:36864
	ds_write_b128 v179, v[154:157] offset:36880
	ds_write_b128 v179, v[158:161] offset:36896
	ds_write_b128 v179, v[162:165] offset:36912
	global_load_dwordx4 v[150:153], v[248:249], off offset:1536
	global_load_dwordx4 v[154:157], v[248:249], off offset:1552
	global_load_dwordx4 v[158:161], v[248:249], off offset:1568
	global_load_dwordx4 v[162:165], v[248:249], off offset:1584
	s_waitcnt lgkmcnt(15)
	v_mfma_f32_32x32x16_f16 v[114:129], v[208:211], v[240:243], v[114:129]
	s_waitcnt lgkmcnt(15)
	v_mfma_f32_32x32x16_f16 v[98:113], v[174:177], v[240:243], v[98:113]
	s_waitcnt lgkmcnt(15)
	v_mfma_f32_32x32x16_f16 v[82:97], v[208:211], v[244:247], v[82:97]
	v_mfma_f32_32x32x16_f16 v[66:81], v[174:177], v[244:247], v[66:81]
	s_waitcnt lgkmcnt(15)
	v_mfma_f32_32x32x16_f16 v[50:65], v[208:211], v[200:203], v[50:65]
	v_mfma_f32_32x32x16_f16 v[34:49], v[174:177], v[200:203], v[34:49]
	s_waitcnt lgkmcnt(14)
	v_mfma_f32_32x32x16_f16 v[2:17], v[208:211], v[204:207], v[2:17]
	v_mfma_f32_32x32x16_f16 v[18:33], v[174:177], v[204:207], v[18:33]
	ds_read_b128 v[208:211], v213 offset:96
	ds_read_b128 v[240:243], v215 offset:96
	ds_read_b128 v[174:177], v213 offset:4704
	ds_read_b128 v[244:247], v215 offset:4704
	ds_read_b128 v[200:203], v215 offset:9312
	ds_read_b128 v[204:207], v215 offset:13920
	s_waitcnt lgkmcnt(14)
	v_mfma_f32_32x32x16_f16 v[114:129], v[232:235], v[216:219], v[114:129]
	s_waitcnt lgkmcnt(13)
	v_mfma_f32_32x32x16_f16 v[98:113], v[236:239], v[216:219], v[98:113]
	s_waitcnt lgkmcnt(12)
	v_mfma_f32_32x32x16_f16 v[82:97], v[232:235], v[220:223], v[82:97]
	v_mfma_f32_32x32x16_f16 v[66:81], v[236:239], v[220:223], v[66:81]
	s_waitcnt lgkmcnt(11)
	v_mfma_f32_32x32x16_f16 v[50:65], v[232:235], v[224:227], v[50:65]
	v_mfma_f32_32x32x16_f16 v[34:49], v[236:239], v[224:227], v[34:49]
	s_waitcnt lgkmcnt(10)
	v_mfma_f32_32x32x16_f16 v[2:17], v[232:235], v[228:231], v[2:17]
	v_mfma_f32_32x32x16_f16 v[18:33], v[236:239], v[228:231], v[18:33]
	s_waitcnt lgkmcnt(0)
	s_barrier
; DI f16v mfma32(h8v a, h8v b, f16v c) { return __builtin_amdgcn_mfma_f32_32x32x16_f16(a, b, c, 0, 0, 0); }
; template <bool GATHER>
; DI void gemm256_main(const h16* __restrict__ A, int lda, const int* __restrict__ idx, int m0,
;                      const h16* __restrict__ B, int ldb, int n0, int K, h16* lds, f16v (&acc)[4][2]) {
;     ...
;   for (int kt = 0; kt < nk; ++kt) {
;     const h16* As = lds + (kt & 1) * (512 * LDH);
;     const h16* Bs = As + 256 * LDH;
;     h16* Wn = lds + ((kt & 1) ^ 1) * (512 * LDH);
;     if (kt + 1 < nk) {
; #pragma unroll
;       for (int i = 0; i < 4; ++i) { *(u4v*)&Wn[lr * LDH + lc + 8 * i] = ra[i]; *(u4v*)&Wn[(256 + lr) * LDH + lc + 8 * i] = rb[i]; }
;     }
;     if (kt + 2 < nk) {
; #pragma unroll
;       for (int i = 0; i < 4; ++i) { ra[i] = *(const u4v*)(AP_ + 8 * i); rb[i] = *(const u4v*)(BP_ + 8 * i); }
;       ao += 64; bo += 64;
;     }
; #pragma unroll
;     for (int ks = 0; ks < 4; ++ks) {
;       h8v af[4], bf[2];
; #pragma unroll
;       for (int i = 0; i < 4; ++i) af[i] = *(const h8v*)&As[(wm * 128 + i * 32 + (lane & 31)) * LDH + ks * 16 + 8 * (lane >> 5)];
; #pragma unroll
;       for (int j = 0; j < 2; ++j) bf[j] = *(const h8v*)&Bs[(wn * 64 + j * 32 + (lane & 31)) * LDH + ks * 16 + 8 * (lane >> 5)];
; #pragma unroll
;       for (int i = 0; i < 4; ++i)
; #pragma unroll
;         for (int j = 0; j < 2; ++j) acc[i][j] = mfma32(bf[j], af[i], acc[i][j]);
;     }
;     __syncthreads();
	ds_read_b128 v[232:235], v214
	ds_read_b128 v[216:219], v212
	ds_read_b128 v[236:239], v214 offset:4608
	ds_read_b128 v[220:223], v212 offset:4608
	ds_read_b128 v[224:227], v212 offset:9216
	ds_read_b128 v[228:231], v212 offset:13824
	v_mfma_f32_32x32x16_f16 v[114:129], v[208:211], v[240:243], v[114:129]
	v_mfma_f32_32x32x16_f16 v[98:113], v[174:177], v[240:243], v[98:113]
	v_mfma_f32_32x32x16_f16 v[82:97], v[208:211], v[244:247], v[82:97]
	v_mfma_f32_32x32x16_f16 v[66:81], v[174:177], v[244:247], v[66:81]
	v_mfma_f32_32x32x16_f16 v[50:65], v[208:211], v[200:203], v[50:65]
	v_mfma_f32_32x32x16_f16 v[34:49], v[174:177], v[200:203], v[34:49]
	v_mfma_f32_32x32x16_f16 v[2:17], v[208:211], v[204:207], v[2:17]
	v_mfma_f32_32x32x16_f16 v[18:33], v[174:177], v[204:207], v[18:33]
	ds_read_b128 v[208:211], v214 offset:32
	ds_read_b128 v[240:243], v212 offset:32
	ds_read_b128 v[174:177], v214 offset:4640
	ds_read_b128 v[244:247], v212 offset:4640
	ds_read_b128 v[200:203], v212 offset:9248
	ds_read_b128 v[204:207], v212 offset:13856
	s_waitcnt vmcnt(4)
	ds_write_b128 v178, v[134:137]
	ds_write_b128 v178, v[138:141] offset:16
	ds_write_b128 v178, v[142:145] offset:32
	ds_write_b128 v178, v[146:149] offset:48
	global_load_dwordx4 v[134:137], v[130:131], off offset:1664
	global_load_dwordx4 v[138:141], v[130:131], off offset:1680
	global_load_dwordx4 v[142:145], v[130:131], off offset:1696
	global_load_dwordx4 v[146:149], v[130:131], off offset:1712
	s_waitcnt lgkmcnt(14)
	v_mfma_f32_32x32x16_f16 v[114:129], v[232:235], v[216:219], v[114:129]
	s_waitcnt lgkmcnt(13)
	v_mfma_f32_32x32x16_f16 v[98:113], v[236:239], v[216:219], v[98:113]
	s_waitcnt lgkmcnt(12)
	v_mfma_f32_32x32x16_f16 v[82:97], v[232:235], v[220:223], v[82:97]
	v_mfma_f32_32x32x16_f16 v[66:81], v[236:239], v[220:223], v[66:81]
	s_waitcnt lgkmcnt(11)
	v_mfma_f32_32x32x16_f16 v[50:65], v[232:235], v[224:227], v[50:65]
	v_mfma_f32_32x32x16_f16 v[34:49], v[236:239], v[224:227], v[34:49]
	s_waitcnt lgkmcnt(10)
	v_mfma_f32_32x32x16_f16 v[2:17], v[232:235], v[228:231], v[2:17]
	v_mfma_f32_32x32x16_f16 v[18:33], v[236:239], v[228:231], v[18:33]
	ds_read_b128 v[232:235], v214 offset:64
	ds_read_b128 v[216:219], v212 offset:64
	ds_read_b128 v[236:239], v214 offset:4672
	ds_read_b128 v[220:223], v212 offset:4672
	ds_read_b128 v[224:227], v212 offset:9280
	ds_read_b128 v[228:231], v212 offset:13888
	s_waitcnt vmcnt(4)
	ds_write_b128 v178, v[150:153] offset:36864
	ds_write_b128 v178, v[154:157] offset:36880
	ds_write_b128 v178, v[158:161] offset:36896
	ds_write_b128 v178, v[162:165] offset:36912
	global_load_dwordx4 v[150:153], v[248:249], off offset:1664
	global_load_dwordx4 v[154:157], v[248:249], off offset:1680
	global_load_dwordx4 v[158:161], v[248:249], off offset:1696
	global_load_dwordx4 v[162:165], v[248:249], off offset:1712
	s_waitcnt lgkmcnt(15)
	v_mfma_f32_32x32x16_f16 v[114:129], v[208:211], v[240:243], v[114:129]
	s_waitcnt lgkmcnt(15)
	v_mfma_f32_32x32x16_f16 v[98:113], v[174:177], v[240:243], v[98:113]
	s_waitcnt lgkmcnt(15)
	v_mfma_f32_32x32x16_f16 v[82:97], v[208:211], v[244:247], v[82:97]
	v_mfma_f32_32x32x16_f16 v[66:81], v[174:177], v[244:247], v[66:81]
	s_waitcnt lgkmcnt(15)
	v_mfma_f32_32x32x16_f16 v[50:65], v[208:211], v[200:203], v[50:65]
	v_mfma_f32_32x32x16_f16 v[34:49], v[174:177], v[200:203], v[34:49]
	s_waitcnt lgkmcnt(14)
	v_mfma_f32_32x32x16_f16 v[2:17], v[208:211], v[204:207], v[2:17]
	v_mfma_f32_32x32x16_f16 v[18:33], v[174:177], v[204:207], v[18:33]
	ds_read_b128 v[208:211], v214 offset:96
	ds_read_b128 v[240:243], v212 offset:96
	ds_read_b128 v[174:177], v214 offset:4704
	ds_read_b128 v[244:247], v212 offset:4704
	ds_read_b128 v[200:203], v212 offset:9312
	ds_read_b128 v[204:207], v212 offset:13920
	s_waitcnt lgkmcnt(14)
	v_mfma_f32_32x32x16_f16 v[114:129], v[232:235], v[216:219], v[114:129]
	s_waitcnt lgkmcnt(13)
	v_mfma_f32_32x32x16_f16 v[98:113], v[236:239], v[216:219], v[98:113]
	s_waitcnt lgkmcnt(12)
	v_mfma_f32_32x32x16_f16 v[82:97], v[232:235], v[220:223], v[82:97]
	v_mfma_f32_32x32x16_f16 v[66:81], v[236:239], v[220:223], v[66:81]
	s_waitcnt lgkmcnt(11)
	v_mfma_f32_32x32x16_f16 v[50:65], v[232:235], v[224:227], v[50:65]
	v_mfma_f32_32x32x16_f16 v[34:49], v[236:239], v[224:227], v[34:49]
	s_waitcnt lgkmcnt(10)
	v_mfma_f32_32x32x16_f16 v[2:17], v[232:235], v[228:231], v[2:17]
	v_mfma_f32_32x32x16_f16 v[18:33], v[236:239], v[228:231], v[18:33]
	s_waitcnt lgkmcnt(0)
	s_barrier
; DI f16v mfma32(h8v a, h8v b, f16v c) { return __builtin_amdgcn_mfma_f32_32x32x16_f16(a, b, c, 0, 0, 0); }
; template <bool GATHER>
; DI void gemm256_main(const h16* __restrict__ A, int lda, const int* __restrict__ idx, int m0,
;                      const h16* __restrict__ B, int ldb, int n0, int K, h16* lds, f16v (&acc)[4][2]) {
;     ...
;   for (int kt = 0; kt < nk; ++kt) {
;     const h16* As = lds + (kt & 1) * (512 * LDH);
;     const h16* Bs = As + 256 * LDH;
;     h16* Wn = lds + ((kt & 1) ^ 1) * (512 * LDH);
;     if (kt + 1 < nk) {
; #pragma unroll
;       for (int i = 0; i < 4; ++i) { *(u4v*)&Wn[lr * LDH + lc + 8 * i] = ra[i]; *(u4v*)&Wn[(256 + lr) * LDH + lc + 8 * i] = rb[i]; }
;     }
;     if (kt + 2 < nk) {
; #pragma unroll
;       for (int i = 0; i < 4; ++i) { ra[i] = *(const u4v*)(AP_ + 8 * i); rb[i] = *(const u4v*)(BP_ + 8 * i); }
;       ao += 64; bo += 64;
;     }
; #pragma unroll
;     for (int ks = 0; ks < 4; ++ks) {
;       h8v af[4], bf[2];
; #pragma unroll
;       for (int i = 0; i < 4; ++i) af[i] = *(const h8v*)&As[(wm * 128 + i * 32 + (lane & 31)) * LDH + ks * 16 + 8 * (lane >> 5)];
; #pragma unroll
;       for (int j = 0; j < 2; ++j) bf[j] = *(const h8v*)&Bs[(wn * 64 + j * 32 + (lane & 31)) * LDH + ks * 16 + 8 * (lane >> 5)];
; #pragma unroll
;       for (int i = 0; i < 4; ++i)
; #pragma unroll
;         for (int j = 0; j < 2; ++j) acc[i][j] = mfma32(bf[j], af[i], acc[i][j]);
;     }
;     __syncthreads();
	ds_read_b128 v[232:235], v213
	ds_read_b128 v[216:219], v215
	ds_read_b128 v[236:239], v213 offset:4608
	ds_read_b128 v[220:223], v215 offset:4608
	ds_read_b128 v[224:227], v215 offset:9216
	ds_read_b128 v[228:231], v215 offset:13824
	v_mfma_f32_32x32x16_f16 v[114:129], v[208:211], v[240:243], v[114:129]
	v_mfma_f32_32x32x16_f16 v[98:113], v[174:177], v[240:243], v[98:113]
	v_mfma_f32_32x32x16_f16 v[82:97], v[208:211], v[244:247], v[82:97]
	v_mfma_f32_32x32x16_f16 v[66:81], v[174:177], v[244:247], v[66:81]
	v_mfma_f32_32x32x16_f16 v[50:65], v[208:211], v[200:203], v[50:65]
	v_mfma_f32_32x32x16_f16 v[34:49], v[174:177], v[200:203], v[34:49]
	v_mfma_f32_32x32x16_f16 v[2:17], v[208:211], v[204:207], v[2:17]
	v_mfma_f32_32x32x16_f16 v[18:33], v[174:177], v[204:207], v[18:33]
	ds_read_b128 v[208:211], v213 offset:32
	ds_read_b128 v[240:243], v215 offset:32
	ds_read_b128 v[174:177], v213 offset:4640
	ds_read_b128 v[244:247], v215 offset:4640
	ds_read_b128 v[200:203], v215 offset:9248
	ds_read_b128 v[204:207], v215 offset:13856
	s_waitcnt vmcnt(4)
	ds_write_b128 v179, v[134:137]
	ds_write_b128 v179, v[138:141] offset:16
	ds_write_b128 v179, v[142:145] offset:32
	ds_write_b128 v179, v[146:149] offset:48
	global_load_dwordx4 v[134:137], v[130:131], off offset:1792
	global_load_dwordx4 v[138:141], v[130:131], off offset:1808
	global_load_dwordx4 v[142:145], v[130:131], off offset:1824
	global_load_dwordx4 v[146:149], v[130:131], off offset:1840
	s_waitcnt lgkmcnt(14)
	v_mfma_f32_32x32x16_f16 v[114:129], v[232:235], v[216:219], v[114:129]
	s_waitcnt lgkmcnt(13)
	v_mfma_f32_32x32x16_f16 v[98:113], v[236:239], v[216:219], v[98:113]
	s_waitcnt lgkmcnt(12)
	v_mfma_f32_32x32x16_f16 v[82:97], v[232:235], v[220:223], v[82:97]
	v_mfma_f32_32x32x16_f16 v[66:81], v[236:239], v[220:223], v[66:81]
	s_waitcnt lgkmcnt(11)
	v_mfma_f32_32x32x16_f16 v[50:65], v[232:235], v[224:227], v[50:65]
	v_mfma_f32_32x32x16_f16 v[34:49], v[236:239], v[224:227], v[34:49]
	s_waitcnt lgkmcnt(10)
	v_mfma_f32_32x32x16_f16 v[2:17], v[232:235], v[228:231], v[2:17]
	v_mfma_f32_32x32x16_f16 v[18:33], v[236:239], v[228:231], v[18:33]
	ds_read_b128 v[232:235], v213 offset:64
	ds_read_b128 v[216:219], v215 offset:64
	ds_read_b128 v[236:239], v213 offset:4672
	ds_read_b128 v[220:223], v215 offset:4672
	ds_read_b128 v[224:227], v215 offset:9280
	ds_read_b128 v[228:231], v215 offset:13888
	s_waitcnt vmcnt(4)
	ds_write_b128 v179, v[150:153] offset:36864
	ds_write_b128 v179, v[154:157] offset:36880
	ds_write_b128 v179, v[158:161] offset:36896
	ds_write_b128 v179, v[162:165] offset:36912
	global_load_dwordx4 v[150:153], v[248:249], off offset:1792
	global_load_dwordx4 v[154:157], v[248:249], off offset:1808
	global_load_dwordx4 v[158:161], v[248:249], off offset:1824
	global_load_dwordx4 v[162:165], v[248:249], off offset:1840
	s_waitcnt lgkmcnt(15)
	v_mfma_f32_32x32x16_f16 v[114:129], v[208:211], v[240:243], v[114:129]
	s_waitcnt lgkmcnt(15)
	v_mfma_f32_32x32x16_f16 v[98:113], v[174:177], v[240:243], v[98:113]
	s_waitcnt lgkmcnt(15)
	v_mfma_f32_32x32x16_f16 v[82:97], v[208:211], v[244:247], v[82:97]
	v_mfma_f32_32x32x16_f16 v[66:81], v[174:177], v[244:247], v[66:81]
	s_waitcnt lgkmcnt(15)
	v_mfma_f32_32x32x16_f16 v[50:65], v[208:211], v[200:203], v[50:65]
	v_mfma_f32_32x32x16_f16 v[34:49], v[174:177], v[200:203], v[34:49]
	s_waitcnt lgkmcnt(14)
	v_mfma_f32_32x32x16_f16 v[2:17], v[208:211], v[204:207], v[2:17]
	v_mfma_f32_32x32x16_f16 v[18:33], v[174:177], v[204:207], v[18:33]
	ds_read_b128 v[208:211], v213 offset:96
	ds_read_b128 v[240:243], v215 offset:96
	ds_read_b128 v[174:177], v213 offset:4704
	ds_read_b128 v[244:247], v215 offset:4704
	ds_read_b128 v[200:203], v215 offset:9312
	ds_read_b128 v[204:207], v215 offset:13920
	s_waitcnt lgkmcnt(14)
	v_mfma_f32_32x32x16_f16 v[114:129], v[232:235], v[216:219], v[114:129]
	s_waitcnt lgkmcnt(13)
	v_mfma_f32_32x32x16_f16 v[98:113], v[236:239], v[216:219], v[98:113]
	s_waitcnt lgkmcnt(12)
	v_mfma_f32_32x32x16_f16 v[82:97], v[232:235], v[220:223], v[82:97]
	v_mfma_f32_32x32x16_f16 v[66:81], v[236:239], v[220:223], v[66:81]
	s_waitcnt lgkmcnt(11)
	v_mfma_f32_32x32x16_f16 v[50:65], v[232:235], v[224:227], v[50:65]
	v_mfma_f32_32x32x16_f16 v[34:49], v[236:239], v[224:227], v[34:49]
	s_waitcnt lgkmcnt(10)
	v_mfma_f32_32x32x16_f16 v[2:17], v[232:235], v[228:231], v[2:17]
	v_mfma_f32_32x32x16_f16 v[18:33], v[236:239], v[228:231], v[18:33]
	s_waitcnt lgkmcnt(0)
	s_barrier
; DI f16v mfma32(h8v a, h8v b, f16v c) { return __builtin_amdgcn_mfma_f32_32x32x16_f16(a, b, c, 0, 0, 0); }
; template <bool GATHER>
; DI void gemm256_main(const h16* __restrict__ A, int lda, const int* __restrict__ idx, int m0,
;                      const h16* __restrict__ B, int ldb, int n0, int K, h16* lds, f16v (&acc)[4][2]) {
;     ...
;   for (int kt = 0; kt < nk; ++kt) {
;     const h16* As = lds + (kt & 1) * (512 * LDH);
;     const h16* Bs = As + 256 * LDH;
;     h16* Wn = lds + ((kt & 1) ^ 1) * (512 * LDH);
;     if (kt + 1 < nk) {
; #pragma unroll
;       for (int i = 0; i < 4; ++i) { *(u4v*)&Wn[lr * LDH + lc + 8 * i] = ra[i]; *(u4v*)&Wn[(256 + lr) * LDH + lc + 8 * i] = rb[i]; }
;     }
;     if (kt + 2 < nk) {
; #pragma unroll
;       for (int i = 0; i < 4; ++i) { ra[i] = *(const u4v*)(AP_ + 8 * i); rb[i] = *(const u4v*)(BP_ + 8 * i); }
;       ao += 64; bo += 64;
;     }
; #pragma unroll
;     for (int ks = 0; ks < 4; ++ks) {
;       h8v af[4], bf[2];
; #pragma unroll
;       for (int i = 0; i < 4; ++i) af[i] = *(const h8v*)&As[(wm * 128 + i * 32 + (lane & 31)) * LDH + ks * 16 + 8 * (lane >> 5)];
; #pragma unroll
;       for (int j = 0; j < 2; ++j) bf[j] = *(const h8v*)&Bs[(wn * 64 + j * 32 + (lane & 31)) * LDH + ks * 16 + 8 * (lane >> 5)];
; #pragma unroll
;       for (int i = 0; i < 4; ++i)
; #pragma unroll
;         for (int j = 0; j < 2; ++j) acc[i][j] = mfma32(bf[j], af[i], acc[i][j]);
;     }
;     __syncthreads();
	ds_read_b128 v[232:235], v214
	ds_read_b128 v[216:219], v212
	ds_read_b128 v[236:239], v214 offset:4608
	ds_read_b128 v[220:223], v212 offset:4608
	ds_read_b128 v[224:227], v212 offset:9216
	ds_read_b128 v[228:231], v212 offset:13824
	v_mfma_f32_32x32x16_f16 v[114:129], v[208:211], v[240:243], v[114:129]
	v_mfma_f32_32x32x16_f16 v[98:113], v[174:177], v[240:243], v[98:113]
	v_mfma_f32_32x32x16_f16 v[82:97], v[208:211], v[244:247], v[82:97]
	v_mfma_f32_32x32x16_f16 v[66:81], v[174:177], v[244:247], v[66:81]
	v_mfma_f32_32x32x16_f16 v[50:65], v[208:211], v[200:203], v[50:65]
	v_mfma_f32_32x32x16_f16 v[34:49], v[174:177], v[200:203], v[34:49]
	v_mfma_f32_32x32x16_f16 v[2:17], v[208:211], v[204:207], v[2:17]
	v_mfma_f32_32x32x16_f16 v[18:33], v[174:177], v[204:207], v[18:33]
	ds_read_b128 v[208:211], v214 offset:32
	ds_read_b128 v[240:243], v212 offset:32
	ds_read_b128 v[174:177], v214 offset:4640
	ds_read_b128 v[244:247], v212 offset:4640
	ds_read_b128 v[200:203], v212 offset:9248
	ds_read_b128 v[204:207], v212 offset:13856
	s_waitcnt vmcnt(4)
	ds_write_b128 v178, v[134:137]
	ds_write_b128 v178, v[138:141] offset:16
	ds_write_b128 v178, v[142:145] offset:32
	ds_write_b128 v178, v[146:149] offset:48
	global_load_dwordx4 v[134:137], v[130:131], off offset:1920
	global_load_dwordx4 v[138:141], v[130:131], off offset:1936
	global_load_dwordx4 v[142:145], v[130:131], off offset:1952
	global_load_dwordx4 v[146:149], v[130:131], off offset:1968
	s_waitcnt lgkmcnt(14)
	v_mfma_f32_32x32x16_f16 v[114:129], v[232:235], v[216:219], v[114:129]
	s_waitcnt lgkmcnt(13)
	v_mfma_f32_32x32x16_f16 v[98:113], v[236:239], v[216:219], v[98:113]
	s_waitcnt lgkmcnt(12)
	v_mfma_f32_32x32x16_f16 v[82:97], v[232:235], v[220:223], v[82:97]
	v_mfma_f32_32x32x16_f16 v[66:81], v[236:239], v[220:223], v[66:81]
	s_waitcnt lgkmcnt(11)
	v_mfma_f32_32x32x16_f16 v[50:65], v[232:235], v[224:227], v[50:65]
	v_mfma_f32_32x32x16_f16 v[34:49], v[236:239], v[224:227], v[34:49]
	s_waitcnt lgkmcnt(10)
	v_mfma_f32_32x32x16_f16 v[2:17], v[232:235], v[228:231], v[2:17]
	v_mfma_f32_32x32x16_f16 v[18:33], v[236:239], v[228:231], v[18:33]
	ds_read_b128 v[232:235], v214 offset:64
	ds_read_b128 v[216:219], v212 offset:64
	ds_read_b128 v[236:239], v214 offset:4672
	ds_read_b128 v[220:223], v212 offset:4672
	ds_read_b128 v[224:227], v212 offset:9280
	ds_read_b128 v[228:231], v212 offset:13888
	s_waitcnt vmcnt(4)
	ds_write_b128 v178, v[150:153] offset:36864
	ds_write_b128 v178, v[154:157] offset:36880
	ds_write_b128 v178, v[158:161] offset:36896
	ds_write_b128 v178, v[162:165] offset:36912
	global_load_dwordx4 v[150:153], v[248:249], off offset:1920
	global_load_dwordx4 v[154:157], v[248:249], off offset:1936
	global_load_dwordx4 v[158:161], v[248:249], off offset:1952
	global_load_dwordx4 v[162:165], v[248:249], off offset:1968
	s_waitcnt lgkmcnt(15)
	v_mfma_f32_32x32x16_f16 v[114:129], v[208:211], v[240:243], v[114:129]
	s_waitcnt lgkmcnt(15)
	v_mfma_f32_32x32x16_f16 v[98:113], v[174:177], v[240:243], v[98:113]
	s_waitcnt lgkmcnt(15)
	v_mfma_f32_32x32x16_f16 v[82:97], v[208:211], v[244:247], v[82:97]
	v_mfma_f32_32x32x16_f16 v[66:81], v[174:177], v[244:247], v[66:81]
	s_waitcnt lgkmcnt(15)
	v_mfma_f32_32x32x16_f16 v[50:65], v[208:211], v[200:203], v[50:65]
	v_mfma_f32_32x32x16_f16 v[34:49], v[174:177], v[200:203], v[34:49]
	s_waitcnt lgkmcnt(14)
	v_mfma_f32_32x32x16_f16 v[2:17], v[208:211], v[204:207], v[2:17]
	v_mfma_f32_32x32x16_f16 v[18:33], v[174:177], v[204:207], v[18:33]
	ds_read_b128 v[208:211], v214 offset:96
	ds_read_b128 v[240:243], v212 offset:96
	ds_read_b128 v[174:177], v214 offset:4704
	ds_read_b128 v[244:247], v212 offset:4704
	ds_read_b128 v[200:203], v212 offset:9312
	ds_read_b128 v[204:207], v212 offset:13920
	s_waitcnt lgkmcnt(14)
	v_mfma_f32_32x32x16_f16 v[114:129], v[232:235], v[216:219], v[114:129]
	s_waitcnt lgkmcnt(13)
	v_mfma_f32_32x32x16_f16 v[98:113], v[236:239], v[216:219], v[98:113]
	s_waitcnt lgkmcnt(12)
	v_mfma_f32_32x32x16_f16 v[82:97], v[232:235], v[220:223], v[82:97]
	v_mfma_f32_32x32x16_f16 v[66:81], v[236:239], v[220:223], v[66:81]
	s_waitcnt lgkmcnt(11)
	v_mfma_f32_32x32x16_f16 v[50:65], v[232:235], v[224:227], v[50:65]
	v_mfma_f32_32x32x16_f16 v[34:49], v[236:239], v[224:227], v[34:49]
	s_waitcnt lgkmcnt(10)
	v_mfma_f32_32x32x16_f16 v[2:17], v[232:235], v[228:231], v[2:17]
	v_mfma_f32_32x32x16_f16 v[18:33], v[236:239], v[228:231], v[18:33]
	s_waitcnt lgkmcnt(0)
	s_barrier
; DI f16v mfma32(h8v a, h8v b, f16v c) { return __builtin_amdgcn_mfma_f32_32x32x16_f16(a, b, c, 0, 0, 0); }
; template <bool GATHER>
; DI void gemm256_main(const h16* __restrict__ A, int lda, const int* __restrict__ idx, int m0,
;                      const h16* __restrict__ B, int ldb, int n0, int K, h16* lds, f16v (&acc)[4][2]) {
;     ...
;   for (int kt = 0; kt < nk; ++kt) {
;     const h16* As = lds + (kt & 1) * (512 * LDH);
;     const h16* Bs = As + 256 * LDH;
;     h16* Wn = lds + ((kt & 1) ^ 1) * (512 * LDH);
;     if (kt + 1 < nk) {
; #pragma unroll
;       for (int i = 0; i < 4; ++i) { *(u4v*)&Wn[lr * LDH + lc + 8 * i] = ra[i]; *(u4v*)&Wn[(256 + lr) * LDH + lc + 8 * i] = rb[i]; }
;     }
;     if (kt + 2 < nk) {
; #pragma unroll
;       for (int i = 0; i < 4; ++i) { ra[i] = *(const u4v*)(AP_ + 8 * i); rb[i] = *(const u4v*)(BP_ + 8 * i); }
;       ao += 64; bo += 64;
;     }
; #pragma unroll
;     for (int ks = 0; ks < 4; ++ks) {
;       h8v af[4], bf[2];
; #pragma unroll
;       for (int i = 0; i < 4; ++i) af[i] = *(const h8v*)&As[(wm * 128 + i * 32 + (lane & 31)) * LDH + ks * 16 + 8 * (lane >> 5)];
; #pragma unroll
;       for (int j = 0; j < 2; ++j) bf[j] = *(const h8v*)&Bs[(wn * 64 + j * 32 + (lane & 31)) * LDH + ks * 16 + 8 * (lane >> 5)];
; #pragma unroll
;       for (int i = 0; i < 4; ++i)
; #pragma unroll
;         for (int j = 0; j < 2; ++j) acc[i][j] = mfma32(bf[j], af[i], acc[i][j]);
;     }
;     __syncthreads();
	ds_read_b128 v[232:235], v213
	ds_read_b128 v[216:219], v215
	ds_read_b128 v[236:239], v213 offset:4608
	ds_read_b128 v[220:223], v215 offset:4608
	ds_read_b128 v[224:227], v215 offset:9216
	ds_read_b128 v[228:231], v215 offset:13824
	v_mfma_f32_32x32x16_f16 v[114:129], v[208:211], v[240:243], v[114:129]
	v_mfma_f32_32x32x16_f16 v[98:113], v[174:177], v[240:243], v[98:113]
	v_mfma_f32_32x32x16_f16 v[82:97], v[208:211], v[244:247], v[82:97]
	v_mfma_f32_32x32x16_f16 v[66:81], v[174:177], v[244:247], v[66:81]
	v_mfma_f32_32x32x16_f16 v[50:65], v[208:211], v[200:203], v[50:65]
	v_mfma_f32_32x32x16_f16 v[34:49], v[174:177], v[200:203], v[34:49]
	v_mfma_f32_32x32x16_f16 v[2:17], v[208:211], v[204:207], v[2:17]
	v_mfma_f32_32x32x16_f16 v[18:33], v[174:177], v[204:207], v[18:33]
	ds_read_b128 v[208:211], v213 offset:32
	ds_read_b128 v[240:243], v215 offset:32
	ds_read_b128 v[174:177], v213 offset:4640
	ds_read_b128 v[244:247], v215 offset:4640
	ds_read_b128 v[200:203], v215 offset:9248
	ds_read_b128 v[204:207], v215 offset:13856
	s_waitcnt vmcnt(4)
	ds_write_b128 v179, v[134:137]
	ds_write_b128 v179, v[138:141] offset:16
	ds_write_b128 v179, v[142:145] offset:32
	ds_write_b128 v179, v[146:149] offset:48
	s_waitcnt lgkmcnt(14)
	v_mfma_f32_32x32x16_f16 v[114:129], v[232:235], v[216:219], v[114:129]
	s_waitcnt lgkmcnt(13)
	v_mfma_f32_32x32x16_f16 v[98:113], v[236:239], v[216:219], v[98:113]
	s_waitcnt lgkmcnt(12)
	v_mfma_f32_32x32x16_f16 v[82:97], v[232:235], v[220:223], v[82:97]
	v_mfma_f32_32x32x16_f16 v[66:81], v[236:239], v[220:223], v[66:81]
	s_waitcnt lgkmcnt(11)
	v_mfma_f32_32x32x16_f16 v[50:65], v[232:235], v[224:227], v[50:65]
	v_mfma_f32_32x32x16_f16 v[34:49], v[236:239], v[224:227], v[34:49]
	s_waitcnt lgkmcnt(10)
	v_mfma_f32_32x32x16_f16 v[2:17], v[232:235], v[228:231], v[2:17]
	v_mfma_f32_32x32x16_f16 v[18:33], v[236:239], v[228:231], v[18:33]
	ds_read_b128 v[232:235], v213 offset:64
	ds_read_b128 v[216:219], v215 offset:64
	ds_read_b128 v[236:239], v213 offset:4672
	ds_read_b128 v[220:223], v215 offset:4672
	ds_read_b128 v[224:227], v215 offset:9280
	ds_read_b128 v[228:231], v215 offset:13888
	s_waitcnt vmcnt(0)
	ds_write_b128 v179, v[150:153] offset:36864
	ds_write_b128 v179, v[154:157] offset:36880
	ds_write_b128 v179, v[158:161] offset:36896
	ds_write_b128 v179, v[162:165] offset:36912
	s_waitcnt lgkmcnt(15)
	v_mfma_f32_32x32x16_f16 v[114:129], v[208:211], v[240:243], v[114:129]
	s_waitcnt lgkmcnt(15)
	v_mfma_f32_32x32x16_f16 v[98:113], v[174:177], v[240:243], v[98:113]
	s_waitcnt lgkmcnt(15)
	v_mfma_f32_32x32x16_f16 v[82:97], v[208:211], v[244:247], v[82:97]
	v_mfma_f32_32x32x16_f16 v[66:81], v[174:177], v[244:247], v[66:81]
	s_waitcnt lgkmcnt(15)
	v_mfma_f32_32x32x16_f16 v[50:65], v[208:211], v[200:203], v[50:65]
	v_mfma_f32_32x32x16_f16 v[34:49], v[174:177], v[200:203], v[34:49]
	s_waitcnt lgkmcnt(14)
	v_mfma_f32_32x32x16_f16 v[2:17], v[208:211], v[204:207], v[2:17]
	v_mfma_f32_32x32x16_f16 v[18:33], v[174:177], v[204:207], v[18:33]
	ds_read_b128 v[208:211], v213 offset:96
	ds_read_b128 v[240:243], v215 offset:96
	ds_read_b128 v[174:177], v213 offset:4704
	ds_read_b128 v[244:247], v215 offset:4704
	ds_read_b128 v[200:203], v215 offset:9312
	ds_read_b128 v[204:207], v215 offset:13920
	s_waitcnt lgkmcnt(14)
	v_mfma_f32_32x32x16_f16 v[114:129], v[232:235], v[216:219], v[114:129]
	s_waitcnt lgkmcnt(13)
	v_mfma_f32_32x32x16_f16 v[98:113], v[236:239], v[216:219], v[98:113]
	s_waitcnt lgkmcnt(12)
	v_mfma_f32_32x32x16_f16 v[82:97], v[232:235], v[220:223], v[82:97]
	v_mfma_f32_32x32x16_f16 v[66:81], v[236:239], v[220:223], v[66:81]
	s_waitcnt lgkmcnt(11)
	v_mfma_f32_32x32x16_f16 v[50:65], v[232:235], v[224:227], v[50:65]
	v_mfma_f32_32x32x16_f16 v[34:49], v[236:239], v[224:227], v[34:49]
	s_waitcnt lgkmcnt(10)
	v_mfma_f32_32x32x16_f16 v[2:17], v[232:235], v[228:231], v[2:17]
	v_mfma_f32_32x32x16_f16 v[18:33], v[236:239], v[228:231], v[18:33]
	s_waitcnt lgkmcnt(0)
	s_barrier
	ds_read_b128 v[232:235], v214
	ds_read_b128 v[216:219], v212
	ds_read_b128 v[236:239], v214 offset:4608
	ds_read_b128 v[220:223], v212 offset:4608
	ds_read_b128 v[224:227], v212 offset:9216
	ds_read_b128 v[228:231], v212 offset:13824
	v_mfma_f32_32x32x16_f16 v[114:129], v[208:211], v[240:243], v[114:129]
	v_mfma_f32_32x32x16_f16 v[98:113], v[174:177], v[240:243], v[98:113]
	v_mfma_f32_32x32x16_f16 v[82:97], v[208:211], v[244:247], v[82:97]
	v_mfma_f32_32x32x16_f16 v[66:81], v[174:177], v[244:247], v[66:81]
	v_mfma_f32_32x32x16_f16 v[50:65], v[208:211], v[200:203], v[50:65]
	v_mfma_f32_32x32x16_f16 v[34:49], v[174:177], v[200:203], v[34:49]
	v_mfma_f32_32x32x16_f16 v[2:17], v[208:211], v[204:207], v[2:17]
	v_mfma_f32_32x32x16_f16 v[18:33], v[174:177], v[204:207], v[18:33]
	ds_read_b128 v[208:211], v214 offset:32
	ds_read_b128 v[240:243], v212 offset:32
	ds_read_b128 v[174:177], v214 offset:4640
	ds_read_b128 v[244:247], v212 offset:4640
	ds_read_b128 v[200:203], v212 offset:9248
	ds_read_b128 v[204:207], v212 offset:13856
	s_waitcnt lgkmcnt(10)
	v_mfma_f32_32x32x16_f16 v[114:129], v[232:235], v[216:219], v[114:129]
	s_waitcnt lgkmcnt(9)
	v_mfma_f32_32x32x16_f16 v[98:113], v[236:239], v[216:219], v[98:113]
	s_waitcnt lgkmcnt(8)
	v_mfma_f32_32x32x16_f16 v[82:97], v[232:235], v[220:223], v[82:97]
	v_mfma_f32_32x32x16_f16 v[66:81], v[236:239], v[220:223], v[66:81]
	s_waitcnt lgkmcnt(7)
	v_mfma_f32_32x32x16_f16 v[50:65], v[232:235], v[224:227], v[50:65]
	v_mfma_f32_32x32x16_f16 v[34:49], v[236:239], v[224:227], v[34:49]
	s_waitcnt lgkmcnt(6)
; DI int otid512() { int t = threadIdx.x; asm volatile("" : "+v"(t)); return t; }
; template <class Epi>
; DI void gemm256_epilogue(f16v (&acc)[4][2], int m0, int n0, Epi epi) {
;   const int tid = otid512(), lane = tid & 63, wv = tid >> 6, wm = wv >> 2, wn = wv & 3, h = lane >> 5;
; #pragma unroll
;   for (int i = 0; i < 4; ++i) {
;     const int m = m0 + wm * 128 + i * 32 + (lane & 31);
; #pragma unroll
;     for (int g = 0; g < 4; ++g) {
;       const int n = n0 + wn * 64 + 8 * g + 4 * h;
;       f4v v0 = {acc[i][0][4 * g], acc[i][0][4 * g + 1], acc[i][0][4 * g + 2], acc[i][0][4 * g + 3]};
;       f4v v1 = {acc[i][1][4 * g], acc[i][1][4 * g + 1], acc[i][1][4 * g + 2], acc[i][1][4 * g + 3]};
;       epi(m, n, v0, v1);
; DI void phase_p1(const Params& p, int l, int bid, int nb, int vb, int vnb, unsigned char* smem, unsigned char* smem_half) {
;     ...
;     gemm256_epilogue(acc, m0, n0, [&](int m, int n, f4v v0, f4v v1) {
;       const bool rope = (n >= 1024 && n < 2560) || (n >= 4352 && n < 4992);
;       if (rope) {
;         const int d = n & 31;
;         f4v c = *(const f4v*)&rc[(size_t)m * 32 + d], s = *(const f4v*)&rs[(size_t)m * 32 + d];
;         f4v o0 = v0 * c - v1 * s, o1 = v1 * c + v0 * s;
;         v0 = o0; v1 = o1;
;       }
;       st_h4(&ps[(size_t)m * NSM + n], v0);
;       st_h4(&ps[(size_t)m * NSM + n + 32], v1);
;     });
	v_mfma_f32_32x32x16_f16 v[2:17], v[232:235], v[228:231], v[2:17]
	v_mfma_f32_32x32x16_f16 v[18:33], v[236:239], v[228:231], v[18:33]
	ds_read_b128 v[232:235], v214 offset:64
	ds_read_b128 v[216:219], v212 offset:64
	ds_read_b128 v[236:239], v214 offset:4672
	ds_read_b128 v[220:223], v212 offset:4672
	ds_read_b128 v[224:227], v212 offset:9280
	ds_read_b128 v[228:231], v212 offset:13888
	s_waitcnt lgkmcnt(10)
	v_mfma_f32_32x32x16_f16 v[114:129], v[208:211], v[240:243], v[114:129]
	s_waitcnt lgkmcnt(9)
	v_mfma_f32_32x32x16_f16 v[98:113], v[174:177], v[240:243], v[98:113]
	s_waitcnt lgkmcnt(8)
	v_mfma_f32_32x32x16_f16 v[82:97], v[208:211], v[244:247], v[82:97]
	v_mfma_f32_32x32x16_f16 v[66:81], v[174:177], v[244:247], v[66:81]
	s_waitcnt lgkmcnt(7)
	v_mfma_f32_32x32x16_f16 v[50:65], v[208:211], v[200:203], v[50:65]
	v_mfma_f32_32x32x16_f16 v[34:49], v[174:177], v[200:203], v[34:49]
	s_waitcnt lgkmcnt(6)
	v_mfma_f32_32x32x16_f16 v[2:17], v[208:211], v[204:207], v[2:17]
	v_mfma_f32_32x32x16_f16 v[18:33], v[174:177], v[204:207], v[18:33]
	ds_read_b128 v[208:211], v214 offset:96
	ds_read_b128 v[240:243], v212 offset:96
	ds_read_b128 v[174:177], v214 offset:4704
	ds_read_b128 v[244:247], v212 offset:4704
	ds_read_b128 v[200:203], v212 offset:9312
	ds_read_b128 v[204:207], v212 offset:13920
	s_waitcnt lgkmcnt(10)
	v_mfma_f32_32x32x16_f16 v[114:129], v[232:235], v[216:219], v[114:129]
	s_waitcnt lgkmcnt(9)
	v_mfma_f32_32x32x16_f16 v[98:113], v[236:239], v[216:219], v[98:113]
	s_waitcnt lgkmcnt(8)
	v_mfma_f32_32x32x16_f16 v[82:97], v[232:235], v[220:223], v[82:97]
	v_mfma_f32_32x32x16_f16 v[66:81], v[236:239], v[220:223], v[66:81]
	s_waitcnt lgkmcnt(7)
	v_mfma_f32_32x32x16_f16 v[50:65], v[232:235], v[224:227], v[50:65]
	v_mfma_f32_32x32x16_f16 v[34:49], v[236:239], v[224:227], v[34:49]
	s_waitcnt lgkmcnt(6)
	v_mfma_f32_32x32x16_f16 v[2:17], v[232:235], v[228:231], v[2:17]
	v_mfma_f32_32x32x16_f16 v[18:33], v[236:239], v[228:231], v[18:33]
	s_waitcnt lgkmcnt(0)
	v_mfma_f32_32x32x16_f16 v[114:129], v[208:211], v[240:243], v[114:129]
	v_mfma_f32_32x32x16_f16 v[98:113], v[174:177], v[240:243], v[98:113]
	v_mfma_f32_32x32x16_f16 v[82:97], v[208:211], v[244:247], v[82:97]
	v_mfma_f32_32x32x16_f16 v[66:81], v[174:177], v[244:247], v[66:81]
	v_mfma_f32_32x32x16_f16 v[50:65], v[208:211], v[200:203], v[50:65]
	v_mfma_f32_32x32x16_f16 v[34:49], v[174:177], v[200:203], v[34:49]
	v_mfma_f32_32x32x16_f16 v[2:17], v[208:211], v[204:207], v[2:17]
	v_mfma_f32_32x32x16_f16 v[18:33], v[174:177], v[204:207], v[18:33]
	s_nop 15
	v_mov_b32_e32 v192, 0x7f800000
	v_mov_b32_e32 v193, 0x7fc00000
	v_mov_b32_e32 v194, 0xff800000
	v_mov_b32_e32 v204, 0x7fffec00
	v_mov_b32_e32 v205, 0xff7fc99e
	v_mov_b32_e32 v206, 0x840000
	v_mov_b32_e32 v207, 0xb00000
	v_mov_b32_e32 v208, 0xdc0000
	v_mov_b32_e32 v209, 0x1080000
	v_mov_b32_e32 v210, 0x1340000
	v_mov_b32_e32 v211, 0x420000
	v_mov_b32_e32 v212, 0x580000
	v_mov_b32_e32 v213, 0x6e0000
	v_mov_b32_e32 v214, 0x9a0000
	s_barrier
	v_readfirstlane_b32 s66, v180
	s_add_i32 s69, s18, 0x400
	s_sub_i32 s69, s69, s6
	s_lshr_b32 s66, s66, 6
	s_and_b32 s67, s66, 3
	s_lshr_b32 s68, s66, 2
	s_lshl_b32 s70, s67, 6
	s_add_i32 s70, s70, s69
	s_lshl_b32 s71, s68, 7
	s_add_i32 s71, s71, s3
	s_mul_i32 s72, s66, 0x4800
	s_add_i32 s72, s72, 16
	v_and_b32_e32 v146, 63, v180
	v_and_b32_e32 v148, 31, v146
	v_lshrrev_b32_e32 v147, 5, v146
	v_mul_u32_u24_e32 v130, 0x90, v148
	v_lshl_add_u32 v130, v147, 3, v130
	v_add_u32_e32 v130, s72, v130
	v_lshrrev_b32_e32 v149, 3, v146
	v_and_b32_e32 v138, 7, v146
	v_mul_u32_u24_e32 v131, 0x90, v149
	v_lshl_add_u32 v131, v138, 4, v131
	v_add_u32_e32 v131, s72, v131
	v_add_u32_e32 v140, s71, v149
	v_lshl_add_u32 v138, v138, 3, s70
	v_mov_b64_e32 v[132:133], s[0:1]
	v_mad_u64_u32 v[132:133], s[74:75], v140, s95, v[132:133]
	v_lshlrev_b32_e32 v138, 1, v138
	v_mov_b32_e32 v139, v0
	v_lshl_add_u64 v[132:133], v[132:133], 0, v[138:139]
	s_mov_b32 s76, 0x14000
	s_mov_b32 s77, 0
	s_sub_u32 s78, s70, 0x400
	s_cmp_lt_u32 s78, 0x600
	s_cselect_b32 s79, 1, 0
	s_sub_u32 s78, s70, 0x1100
	s_cmp_lt_u32 s78, 0x280
	s_cselect_b32 s78, 1, 0
	s_or_b32 s79, s79, s78
	s_cmp_eq_u32 s79, 0
	s_cbranch_scc1 .Lp1e_norope
	v_readlane_b32 s80, v252, 60
	v_readlane_b32 s81, v252, 61
	v_readlane_b32 s82, v252, 62
	v_readlane_b32 s83, v252, 63
	v_add_u32_e32 v140, s71, v148
	v_lshlrev_b32_e32 v140, 7, v140
	v_lshl_add_u32 v140, v147, 4, v140
	v_mov_b32_e32 v141, v0
	v_lshl_add_u64 v[134:135], s[80:81], 0, v[140:141]
	v_lshl_add_u64 v[136:137], s[82:83], 0, v[140:141]
	s_mov_b32 s84, 0x1000
	s_mov_b32 s85, 0
	global_load_dwordx4 v[150:153], v[134:135], off
	global_load_dwordx4 v[154:157], v[136:137], off
	global_load_dwordx4 v[158:161], v[134:135], off offset:32
	global_load_dwordx4 v[162:165], v[136:137], off offset:32
	global_load_dwordx4 v[216:219], v[134:135], off offset:64
	global_load_dwordx4 v[220:223], v[136:137], off offset:64
	global_load_dwordx4 v[224:227], v[134:135], off offset:96
	global_load_dwordx4 v[228:231], v[136:137], off offset:96
	v_lshl_add_u64 v[134:135], v[134:135], 0, s[84:85]
	v_lshl_add_u64 v[136:137], v[136:137], 0, s[84:85]
	global_load_dwordx4 v[232:235], v[134:135], off
	global_load_dwordx4 v[236:239], v[136:137], off
	global_load_dwordx4 v[240:243], v[134:135], off offset:32
	global_load_dwordx4 v[244:247], v[136:137], off offset:32
	s_waitcnt vmcnt(10)
; DI void phase_p1(const Params& p, int l, int bid, int nb, int vb, int vnb, unsigned char* smem, unsigned char* smem_half) {
;     ...
;     gemm256_epilogue(acc, m0, n0, [&](int m, int n, f4v v0, f4v v1) {
;       const bool rope = (n >= 1024 && n < 2560) || (n >= 4352 && n < 4992);
;       if (rope) {
;         const int d = n & 31;
;         f4v c = *(const f4v*)&rc[(size_t)m * 32 + d], s = *(const f4v*)&rs[(size_t)m * 32 + d];
;         f4v o0 = v0 * c - v1 * s, o1 = v1 * c + v0 * s;
;         v0 = o0; v1 = o1;
;       }
;       st_h4(&ps[(size_t)m * NSM + n], v0);
;       st_h4(&ps[(size_t)m * NSM + n + 32], v1);
	v_pk_mul_f32 v[146:147], v[98:99], v[154:155]
	v_pk_mul_f32 v[148:149], v[114:115], v[154:155]
	v_pk_fma_f32 v[114:115], v[114:115], v[150:151], v[146:147] neg_lo:[0,0,1] neg_hi:[0,0,1]
	v_pk_fma_f32 v[98:99], v[98:99], v[150:151], v[148:149]
	v_pk_mul_f32 v[146:147], v[100:101], v[156:157]
	v_pk_mul_f32 v[148:149], v[116:117], v[156:157]
	v_pk_fma_f32 v[116:117], v[116:117], v[152:153], v[146:147] neg_lo:[0,0,1] neg_hi:[0,0,1]
	v_pk_fma_f32 v[100:101], v[100:101], v[152:153], v[148:149]
	v_cvt_pk_f16_f32 v138, v114, v115
	v_cvt_pk_f16_f32 v139, v116, v117
	ds_write_b64 v130, v[138:139] offset:0
	v_cvt_pk_f16_f32 v140, v98, v99
	v_cvt_pk_f16_f32 v141, v100, v101
	ds_write_b64 v130, v[140:141] offset:64
	global_load_dwordx4 v[150:153], v[134:135], off offset:64
	global_load_dwordx4 v[154:157], v[136:137], off offset:64
	s_waitcnt vmcnt(10)
	v_pk_mul_f32 v[146:147], v[102:103], v[162:163]
	v_pk_mul_f32 v[148:149], v[118:119], v[162:163]
	v_pk_fma_f32 v[118:119], v[118:119], v[158:159], v[146:147] neg_lo:[0,0,1] neg_hi:[0,0,1]
	v_pk_fma_f32 v[102:103], v[102:103], v[158:159], v[148:149]
	v_pk_mul_f32 v[146:147], v[104:105], v[164:165]
	v_pk_mul_f32 v[148:149], v[120:121], v[164:165]
	v_pk_fma_f32 v[120:121], v[120:121], v[160:161], v[146:147] neg_lo:[0,0,1] neg_hi:[0,0,1]
	v_pk_fma_f32 v[104:105], v[104:105], v[160:161], v[148:149]
	v_cvt_pk_f16_f32 v142, v118, v119
	v_cvt_pk_f16_f32 v143, v120, v121
	ds_write_b64 v130, v[142:143] offset:16
	v_cvt_pk_f16_f32 v144, v102, v103
	v_cvt_pk_f16_f32 v145, v104, v105
	ds_write_b64 v130, v[144:145] offset:80
	global_load_dwordx4 v[158:161], v[134:135], off offset:96
	global_load_dwordx4 v[162:165], v[136:137], off offset:96
	s_waitcnt vmcnt(10)
	v_pk_mul_f32 v[146:147], v[106:107], v[220:221]
	v_pk_mul_f32 v[148:149], v[122:123], v[220:221]
	v_pk_fma_f32 v[122:123], v[122:123], v[216:217], v[146:147] neg_lo:[0,0,1] neg_hi:[0,0,1]
	v_pk_fma_f32 v[106:107], v[106:107], v[216:217], v[148:149]
	v_pk_mul_f32 v[146:147], v[108:109], v[222:223]
	v_pk_mul_f32 v[148:149], v[124:125], v[222:223]
	v_pk_fma_f32 v[124:125], v[124:125], v[218:219], v[146:147] neg_lo:[0,0,1] neg_hi:[0,0,1]
	v_pk_fma_f32 v[108:109], v[108:109], v[218:219], v[148:149]
	v_cvt_pk_f16_f32 v138, v122, v123
	v_cvt_pk_f16_f32 v139, v124, v125
	ds_write_b64 v130, v[138:139] offset:32
	v_cvt_pk_f16_f32 v140, v106, v107
	v_cvt_pk_f16_f32 v141, v108, v109
	ds_write_b64 v130, v[140:141] offset:96
	v_lshl_add_u64 v[134:135], v[134:135], 0, s[84:85]
	v_lshl_add_u64 v[136:137], v[136:137], 0, s[84:85]
	global_load_dwordx4 v[216:219], v[134:135], off
	global_load_dwordx4 v[220:223], v[136:137], off
	s_waitcnt vmcnt(10)
	v_pk_mul_f32 v[146:147], v[110:111], v[228:229]
	v_pk_mul_f32 v[148:149], v[126:127], v[228:229]
	v_pk_fma_f32 v[126:127], v[126:127], v[224:225], v[146:147] neg_lo:[0,0,1] neg_hi:[0,0,1]
	v_pk_fma_f32 v[110:111], v[110:111], v[224:225], v[148:149]
	v_pk_mul_f32 v[146:147], v[112:113], v[230:231]
	v_pk_mul_f32 v[148:149], v[128:129], v[230:231]
	v_pk_fma_f32 v[128:129], v[128:129], v[226:227], v[146:147] neg_lo:[0,0,1] neg_hi:[0,0,1]
	v_pk_fma_f32 v[112:113], v[112:113], v[226:227], v[148:149]
	v_cvt_pk_f16_f32 v142, v126, v127
	v_cvt_pk_f16_f32 v143, v128, v129
	ds_write_b64 v130, v[142:143] offset:48
	v_cvt_pk_f16_f32 v144, v110, v111
	v_cvt_pk_f16_f32 v145, v112, v113
	ds_write_b64 v130, v[144:145] offset:112
	global_load_dwordx4 v[224:227], v[134:135], off offset:32
	global_load_dwordx4 v[228:231], v[136:137], off offset:32
	s_waitcnt vmcnt(10)
	v_pk_mul_f32 v[146:147], v[66:67], v[236:237]
	v_pk_mul_f32 v[148:149], v[82:83], v[236:237]
	v_pk_fma_f32 v[82:83], v[82:83], v[232:233], v[146:147] neg_lo:[0,0,1] neg_hi:[0,0,1]
	v_pk_fma_f32 v[66:67], v[66:67], v[232:233], v[148:149]
	v_pk_mul_f32 v[146:147], v[68:69], v[238:239]
	v_pk_mul_f32 v[148:149], v[84:85], v[238:239]
	v_pk_fma_f32 v[84:85], v[84:85], v[234:235], v[146:147] neg_lo:[0,0,1] neg_hi:[0,0,1]
	v_pk_fma_f32 v[68:69], v[68:69], v[234:235], v[148:149]
	v_cvt_pk_f16_f32 v138, v82, v83
	v_cvt_pk_f16_f32 v139, v84, v85
	ds_write_b64 v130, v[138:139] offset:4608
	v_cvt_pk_f16_f32 v140, v66, v67
	v_cvt_pk_f16_f32 v141, v68, v69
	ds_write_b64 v130, v[140:141] offset:4672
	global_load_dwordx4 v[232:235], v[134:135], off offset:64
	global_load_dwordx4 v[236:239], v[136:137], off offset:64
	s_waitcnt vmcnt(10)
	v_pk_mul_f32 v[146:147], v[70:71], v[244:245]
	v_pk_mul_f32 v[148:149], v[86:87], v[244:245]
	v_pk_fma_f32 v[86:87], v[86:87], v[240:241], v[146:147] neg_lo:[0,0,1] neg_hi:[0,0,1]
	v_pk_fma_f32 v[70:71], v[70:71], v[240:241], v[148:149]
	v_pk_mul_f32 v[146:147], v[72:73], v[246:247]
	v_pk_mul_f32 v[148:149], v[88:89], v[246:247]
	v_pk_fma_f32 v[88:89], v[88:89], v[242:243], v[146:147] neg_lo:[0,0,1] neg_hi:[0,0,1]
	v_pk_fma_f32 v[72:73], v[72:73], v[242:243], v[148:149]
	v_cvt_pk_f16_f32 v142, v86, v87
	v_cvt_pk_f16_f32 v143, v88, v89
	ds_write_b64 v130, v[142:143] offset:4624
	v_cvt_pk_f16_f32 v144, v70, v71
	v_cvt_pk_f16_f32 v145, v72, v73
	ds_write_b64 v130, v[144:145] offset:4688
	global_load_dwordx4 v[240:243], v[134:135], off offset:96
	global_load_dwordx4 v[244:247], v[136:137], off offset:96
	s_waitcnt vmcnt(10)
; DI void phase_p1(const Params& p, int l, int bid, int nb, int vb, int vnb, unsigned char* smem, unsigned char* smem_half) {
;     ...
;     gemm256_epilogue(acc, m0, n0, [&](int m, int n, f4v v0, f4v v1) {
;       const bool rope = (n >= 1024 && n < 2560) || (n >= 4352 && n < 4992);
;       if (rope) {
;         const int d = n & 31;
;         f4v c = *(const f4v*)&rc[(size_t)m * 32 + d], s = *(const f4v*)&rs[(size_t)m * 32 + d];
;         f4v o0 = v0 * c - v1 * s, o1 = v1 * c + v0 * s;
;         v0 = o0; v1 = o1;
;       }
;       st_h4(&ps[(size_t)m * NSM + n], v0);
;       st_h4(&ps[(size_t)m * NSM + n + 32], v1);
	v_pk_mul_f32 v[146:147], v[74:75], v[154:155]
	v_pk_mul_f32 v[148:149], v[90:91], v[154:155]
	v_pk_fma_f32 v[90:91], v[90:91], v[150:151], v[146:147] neg_lo:[0,0,1] neg_hi:[0,0,1]
	v_pk_fma_f32 v[74:75], v[74:75], v[150:151], v[148:149]
	v_pk_mul_f32 v[146:147], v[76:77], v[156:157]
	v_pk_mul_f32 v[148:149], v[92:93], v[156:157]
	v_pk_fma_f32 v[92:93], v[92:93], v[152:153], v[146:147] neg_lo:[0,0,1] neg_hi:[0,0,1]
	v_pk_fma_f32 v[76:77], v[76:77], v[152:153], v[148:149]
	v_cvt_pk_f16_f32 v138, v90, v91
	v_cvt_pk_f16_f32 v139, v92, v93
	ds_write_b64 v130, v[138:139] offset:4640
	v_cvt_pk_f16_f32 v140, v74, v75
	v_cvt_pk_f16_f32 v141, v76, v77
	ds_write_b64 v130, v[140:141] offset:4704
	v_lshl_add_u64 v[134:135], v[134:135], 0, s[84:85]
	v_lshl_add_u64 v[136:137], v[136:137], 0, s[84:85]
	global_load_dwordx4 v[150:153], v[134:135], off
	global_load_dwordx4 v[154:157], v[136:137], off
	s_waitcnt vmcnt(10)
	v_pk_mul_f32 v[146:147], v[78:79], v[162:163]
	v_pk_mul_f32 v[148:149], v[94:95], v[162:163]
	v_pk_fma_f32 v[94:95], v[94:95], v[158:159], v[146:147] neg_lo:[0,0,1] neg_hi:[0,0,1]
	v_pk_fma_f32 v[78:79], v[78:79], v[158:159], v[148:149]
	v_pk_mul_f32 v[146:147], v[80:81], v[164:165]
	v_pk_mul_f32 v[148:149], v[96:97], v[164:165]
	v_pk_fma_f32 v[96:97], v[96:97], v[160:161], v[146:147] neg_lo:[0,0,1] neg_hi:[0,0,1]
	v_pk_fma_f32 v[80:81], v[80:81], v[160:161], v[148:149]
	v_cvt_pk_f16_f32 v142, v94, v95
	v_cvt_pk_f16_f32 v143, v96, v97
	ds_write_b64 v130, v[142:143] offset:4656
	v_cvt_pk_f16_f32 v144, v78, v79
	v_cvt_pk_f16_f32 v145, v80, v81
	ds_write_b64 v130, v[144:145] offset:4720
	global_load_dwordx4 v[158:161], v[134:135], off offset:32
	global_load_dwordx4 v[162:165], v[136:137], off offset:32
	s_waitcnt vmcnt(10)
	v_pk_mul_f32 v[146:147], v[34:35], v[220:221]
	v_pk_mul_f32 v[148:149], v[50:51], v[220:221]
	v_pk_fma_f32 v[50:51], v[50:51], v[216:217], v[146:147] neg_lo:[0,0,1] neg_hi:[0,0,1]
	v_pk_fma_f32 v[34:35], v[34:35], v[216:217], v[148:149]
	v_pk_mul_f32 v[146:147], v[36:37], v[222:223]
	v_pk_mul_f32 v[148:149], v[52:53], v[222:223]
	v_pk_fma_f32 v[52:53], v[52:53], v[218:219], v[146:147] neg_lo:[0,0,1] neg_hi:[0,0,1]
	v_pk_fma_f32 v[36:37], v[36:37], v[218:219], v[148:149]
	v_cvt_pk_f16_f32 v138, v50, v51
	v_cvt_pk_f16_f32 v139, v52, v53
	ds_write_b64 v130, v[138:139] offset:9216
	v_cvt_pk_f16_f32 v140, v34, v35
	v_cvt_pk_f16_f32 v141, v36, v37
	ds_write_b64 v130, v[140:141] offset:9280
	global_load_dwordx4 v[216:219], v[134:135], off offset:64
	global_load_dwordx4 v[220:223], v[136:137], off offset:64
	s_waitcnt vmcnt(10)
	v_pk_mul_f32 v[146:147], v[38:39], v[228:229]
	v_pk_mul_f32 v[148:149], v[54:55], v[228:229]
	v_pk_fma_f32 v[54:55], v[54:55], v[224:225], v[146:147] neg_lo:[0,0,1] neg_hi:[0,0,1]
	v_pk_fma_f32 v[38:39], v[38:39], v[224:225], v[148:149]
	v_pk_mul_f32 v[146:147], v[40:41], v[230:231]
	v_pk_mul_f32 v[148:149], v[56:57], v[230:231]
	v_pk_fma_f32 v[56:57], v[56:57], v[226:227], v[146:147] neg_lo:[0,0,1] neg_hi:[0,0,1]
	v_pk_fma_f32 v[40:41], v[40:41], v[226:227], v[148:149]
	v_cvt_pk_f16_f32 v142, v54, v55
	v_cvt_pk_f16_f32 v143, v56, v57
	ds_write_b64 v130, v[142:143] offset:9232
	v_cvt_pk_f16_f32 v144, v38, v39
	v_cvt_pk_f16_f32 v145, v40, v41
	ds_write_b64 v130, v[144:145] offset:9296
	global_load_dwordx4 v[224:227], v[134:135], off offset:96
	global_load_dwordx4 v[228:231], v[136:137], off offset:96
	s_waitcnt vmcnt(10)
	v_pk_mul_f32 v[146:147], v[42:43], v[236:237]
	v_pk_mul_f32 v[148:149], v[58:59], v[236:237]
	v_pk_fma_f32 v[58:59], v[58:59], v[232:233], v[146:147] neg_lo:[0,0,1] neg_hi:[0,0,1]
	v_pk_fma_f32 v[42:43], v[42:43], v[232:233], v[148:149]
	v_pk_mul_f32 v[146:147], v[44:45], v[238:239]
	v_pk_mul_f32 v[148:149], v[60:61], v[238:239]
	v_pk_fma_f32 v[60:61], v[60:61], v[234:235], v[146:147] neg_lo:[0,0,1] neg_hi:[0,0,1]
	v_pk_fma_f32 v[44:45], v[44:45], v[234:235], v[148:149]
	v_cvt_pk_f16_f32 v138, v58, v59
	v_cvt_pk_f16_f32 v139, v60, v61
	ds_write_b64 v130, v[138:139] offset:9248
	v_cvt_pk_f16_f32 v140, v42, v43
	v_cvt_pk_f16_f32 v141, v44, v45
	ds_write_b64 v130, v[140:141] offset:9312
	s_waitcnt vmcnt(8)
	v_pk_mul_f32 v[146:147], v[46:47], v[244:245]
	v_pk_mul_f32 v[148:149], v[62:63], v[244:245]
	v_pk_fma_f32 v[62:63], v[62:63], v[240:241], v[146:147] neg_lo:[0,0,1] neg_hi:[0,0,1]
	v_pk_fma_f32 v[46:47], v[46:47], v[240:241], v[148:149]
	v_pk_mul_f32 v[146:147], v[48:49], v[246:247]
	v_pk_mul_f32 v[148:149], v[64:65], v[246:247]
	v_pk_fma_f32 v[64:65], v[64:65], v[242:243], v[146:147] neg_lo:[0,0,1] neg_hi:[0,0,1]
	v_pk_fma_f32 v[48:49], v[48:49], v[242:243], v[148:149]
	v_cvt_pk_f16_f32 v142, v62, v63
	v_cvt_pk_f16_f32 v143, v64, v65
	ds_write_b64 v130, v[142:143] offset:9264
	v_cvt_pk_f16_f32 v144, v46, v47
	v_cvt_pk_f16_f32 v145, v48, v49
	ds_write_b64 v130, v[144:145] offset:9328
	s_waitcnt vmcnt(6)
	v_pk_mul_f32 v[146:147], v[18:19], v[154:155]
	v_pk_mul_f32 v[148:149], v[2:3], v[154:155]
	v_pk_fma_f32 v[2:3], v[2:3], v[150:151], v[146:147] neg_lo:[0,0,1] neg_hi:[0,0,1]
	v_pk_fma_f32 v[18:19], v[18:19], v[150:151], v[148:149]
	v_pk_mul_f32 v[146:147], v[20:21], v[156:157]
	v_pk_mul_f32 v[148:149], v[4:5], v[156:157]
	v_pk_fma_f32 v[4:5], v[4:5], v[152:153], v[146:147] neg_lo:[0,0,1] neg_hi:[0,0,1]
	v_pk_fma_f32 v[20:21], v[20:21], v[152:153], v[148:149]
	v_cvt_pk_f16_f32 v138, v2, v3
	v_cvt_pk_f16_f32 v139, v4, v5
	ds_write_b64 v130, v[138:139] offset:13824
	v_cvt_pk_f16_f32 v140, v18, v19
	v_cvt_pk_f16_f32 v141, v20, v21
	ds_write_b64 v130, v[140:141] offset:13888
	s_waitcnt vmcnt(4)
; DI void phase_p1(const Params& p, int l, int bid, int nb, int vb, int vnb, unsigned char* smem, unsigned char* smem_half) {
;     ...
;     gemm256_epilogue(acc, m0, n0, [&](int m, int n, f4v v0, f4v v1) {
;       const bool rope = (n >= 1024 && n < 2560) || (n >= 4352 && n < 4992);
;       if (rope) {
;         const int d = n & 31;
;         f4v c = *(const f4v*)&rc[(size_t)m * 32 + d], s = *(const f4v*)&rs[(size_t)m * 32 + d];
;         f4v o0 = v0 * c - v1 * s, o1 = v1 * c + v0 * s;
;         v0 = o0; v1 = o1;
;       }
;       st_h4(&ps[(size_t)m * NSM + n], v0);
;       st_h4(&ps[(size_t)m * NSM + n + 32], v1);
	v_pk_mul_f32 v[146:147], v[22:23], v[162:163]
	v_pk_mul_f32 v[148:149], v[6:7], v[162:163]
	v_pk_fma_f32 v[6:7], v[6:7], v[158:159], v[146:147] neg_lo:[0,0,1] neg_hi:[0,0,1]
	v_pk_fma_f32 v[22:23], v[22:23], v[158:159], v[148:149]
	v_pk_mul_f32 v[146:147], v[24:25], v[164:165]
	v_pk_mul_f32 v[148:149], v[8:9], v[164:165]
	v_pk_fma_f32 v[8:9], v[8:9], v[160:161], v[146:147] neg_lo:[0,0,1] neg_hi:[0,0,1]
	v_pk_fma_f32 v[24:25], v[24:25], v[160:161], v[148:149]
	v_cvt_pk_f16_f32 v142, v6, v7
	v_cvt_pk_f16_f32 v143, v8, v9
	ds_write_b64 v130, v[142:143] offset:13840
	v_cvt_pk_f16_f32 v144, v22, v23
	v_cvt_pk_f16_f32 v145, v24, v25
	ds_write_b64 v130, v[144:145] offset:13904
	s_waitcnt vmcnt(2)
	v_pk_mul_f32 v[146:147], v[26:27], v[220:221]
	v_pk_mul_f32 v[148:149], v[10:11], v[220:221]
	v_pk_fma_f32 v[10:11], v[10:11], v[216:217], v[146:147] neg_lo:[0,0,1] neg_hi:[0,0,1]
	v_pk_fma_f32 v[26:27], v[26:27], v[216:217], v[148:149]
	v_pk_mul_f32 v[146:147], v[28:29], v[222:223]
	v_pk_mul_f32 v[148:149], v[12:13], v[222:223]
	v_pk_fma_f32 v[12:13], v[12:13], v[218:219], v[146:147] neg_lo:[0,0,1] neg_hi:[0,0,1]
	v_pk_fma_f32 v[28:29], v[28:29], v[218:219], v[148:149]
	v_cvt_pk_f16_f32 v138, v10, v11
	v_cvt_pk_f16_f32 v139, v12, v13
	ds_write_b64 v130, v[138:139] offset:13856
	v_cvt_pk_f16_f32 v140, v26, v27
	v_cvt_pk_f16_f32 v141, v28, v29
	ds_write_b64 v130, v[140:141] offset:13920
	s_waitcnt vmcnt(0)
	v_pk_mul_f32 v[146:147], v[30:31], v[228:229]
	v_pk_mul_f32 v[148:149], v[14:15], v[228:229]
	v_pk_fma_f32 v[14:15], v[14:15], v[224:225], v[146:147] neg_lo:[0,0,1] neg_hi:[0,0,1]
	v_pk_fma_f32 v[30:31], v[30:31], v[224:225], v[148:149]
	v_pk_mul_f32 v[146:147], v[32:33], v[230:231]
	v_pk_mul_f32 v[148:149], v[16:17], v[230:231]
	v_pk_fma_f32 v[16:17], v[16:17], v[226:227], v[146:147] neg_lo:[0,0,1] neg_hi:[0,0,1]
	v_pk_fma_f32 v[32:33], v[32:33], v[226:227], v[148:149]
	v_cvt_pk_f16_f32 v142, v14, v15
	v_cvt_pk_f16_f32 v143, v16, v17
	ds_write_b64 v130, v[142:143] offset:13872
	v_cvt_pk_f16_f32 v144, v30, v31
	v_cvt_pk_f16_f32 v145, v32, v33
	ds_write_b64 v130, v[144:145] offset:13936
	s_branch .Lp1e_store
.Lp1e_norope:
	v_cvt_pk_f16_f32 v138, v114, v115
	v_cvt_pk_f16_f32 v139, v116, v117
	ds_write_b64 v130, v[138:139] offset:0
	v_cvt_pk_f16_f32 v140, v98, v99
	v_cvt_pk_f16_f32 v141, v100, v101
	ds_write_b64 v130, v[140:141] offset:64
	v_cvt_pk_f16_f32 v142, v118, v119
	v_cvt_pk_f16_f32 v143, v120, v121
	ds_write_b64 v130, v[142:143] offset:16
	v_cvt_pk_f16_f32 v144, v102, v103
	v_cvt_pk_f16_f32 v145, v104, v105
	ds_write_b64 v130, v[144:145] offset:80
	v_cvt_pk_f16_f32 v138, v122, v123
	v_cvt_pk_f16_f32 v139, v124, v125
	ds_write_b64 v130, v[138:139] offset:32
	v_cvt_pk_f16_f32 v140, v106, v107
	v_cvt_pk_f16_f32 v141, v108, v109
	ds_write_b64 v130, v[140:141] offset:96
	v_cvt_pk_f16_f32 v142, v126, v127
	v_cvt_pk_f16_f32 v143, v128, v129
	ds_write_b64 v130, v[142:143] offset:48
	v_cvt_pk_f16_f32 v144, v110, v111
	v_cvt_pk_f16_f32 v145, v112, v113
	ds_write_b64 v130, v[144:145] offset:112
	v_cvt_pk_f16_f32 v138, v82, v83
	v_cvt_pk_f16_f32 v139, v84, v85
	ds_write_b64 v130, v[138:139] offset:4608
	v_cvt_pk_f16_f32 v140, v66, v67
	v_cvt_pk_f16_f32 v141, v68, v69
	ds_write_b64 v130, v[140:141] offset:4672
	v_cvt_pk_f16_f32 v142, v86, v87
	v_cvt_pk_f16_f32 v143, v88, v89
	ds_write_b64 v130, v[142:143] offset:4624
	v_cvt_pk_f16_f32 v144, v70, v71
	v_cvt_pk_f16_f32 v145, v72, v73
	ds_write_b64 v130, v[144:145] offset:4688
	v_cvt_pk_f16_f32 v138, v90, v91
	v_cvt_pk_f16_f32 v139, v92, v93
	ds_write_b64 v130, v[138:139] offset:4640
	v_cvt_pk_f16_f32 v140, v74, v75
	v_cvt_pk_f16_f32 v141, v76, v77
	ds_write_b64 v130, v[140:141] offset:4704
	v_cvt_pk_f16_f32 v142, v94, v95
	v_cvt_pk_f16_f32 v143, v96, v97
	ds_write_b64 v130, v[142:143] offset:4656
	v_cvt_pk_f16_f32 v144, v78, v79
	v_cvt_pk_f16_f32 v145, v80, v81
	ds_write_b64 v130, v[144:145] offset:4720
	v_cvt_pk_f16_f32 v138, v50, v51
	v_cvt_pk_f16_f32 v139, v52, v53
	ds_write_b64 v130, v[138:139] offset:9216
	v_cvt_pk_f16_f32 v140, v34, v35
	v_cvt_pk_f16_f32 v141, v36, v37
	ds_write_b64 v130, v[140:141] offset:9280
	v_cvt_pk_f16_f32 v142, v54, v55
	v_cvt_pk_f16_f32 v143, v56, v57
	ds_write_b64 v130, v[142:143] offset:9232
	v_cvt_pk_f16_f32 v144, v38, v39
	v_cvt_pk_f16_f32 v145, v40, v41
	ds_write_b64 v130, v[144:145] offset:9296
	v_cvt_pk_f16_f32 v138, v58, v59
	v_cvt_pk_f16_f32 v139, v60, v61
	ds_write_b64 v130, v[138:139] offset:9248
	v_cvt_pk_f16_f32 v140, v42, v43
	v_cvt_pk_f16_f32 v141, v44, v45
	ds_write_b64 v130, v[140:141] offset:9312
	v_cvt_pk_f16_f32 v142, v62, v63
	v_cvt_pk_f16_f32 v143, v64, v65
	ds_write_b64 v130, v[142:143] offset:9264
	v_cvt_pk_f16_f32 v144, v46, v47
	v_cvt_pk_f16_f32 v145, v48, v49
	ds_write_b64 v130, v[144:145] offset:9328
	v_cvt_pk_f16_f32 v138, v2, v3
	v_cvt_pk_f16_f32 v139, v4, v5
	ds_write_b64 v130, v[138:139] offset:13824
	v_cvt_pk_f16_f32 v140, v18, v19
	v_cvt_pk_f16_f32 v141, v20, v21
	ds_write_b64 v130, v[140:141] offset:13888
	v_cvt_pk_f16_f32 v142, v6, v7
	v_cvt_pk_f16_f32 v143, v8, v9
	ds_write_b64 v130, v[142:143] offset:13840
	v_cvt_pk_f16_f32 v144, v22, v23
	v_cvt_pk_f16_f32 v145, v24, v25
	ds_write_b64 v130, v[144:145] offset:13904
	v_cvt_pk_f16_f32 v138, v10, v11
	v_cvt_pk_f16_f32 v139, v12, v13
	ds_write_b64 v130, v[138:139] offset:13856
	v_cvt_pk_f16_f32 v140, v26, v27
	v_cvt_pk_f16_f32 v141, v28, v29
	ds_write_b64 v130, v[140:141] offset:13920
	v_cvt_pk_f16_f32 v142, v14, v15
	v_cvt_pk_f16_f32 v143, v16, v17
	ds_write_b64 v130, v[142:143] offset:13872
	v_cvt_pk_f16_f32 v144, v30, v31
	v_cvt_pk_f16_f32 v145, v32, v33
	ds_write_b64 v130, v[144:145] offset:13936
; DI void phase_p1(const Params& p, int l, int bid, int nb, int vb, int vnb, unsigned char* smem, unsigned char* smem_half) {
;     ...
;   for (int u = bid; u < 64 * 20; u += nb) {
;     const int m0 = (u / 20) * 256, n0 = (u % 20) * 256;
;     f16v acc[4][2]; acc256_zero(acc);
;     gemm256_main<false>(x16, DM, nullptr, m0, wsm, 1024, n0, 1024, (h16*)smem, acc);
;     gemm256_epilogue(acc, m0, n0, [&](int m, int n, f4v v0, f4v v1) {
;       const bool rope = (n >= 1024 && n < 2560) || (n >= 4352 && n < 4992);
;       if (rope) {
;         const int d = n & 31;
;         f4v c = *(const f4v*)&rc[(size_t)m * 32 + d], s = *(const f4v*)&rs[(size_t)m * 32 + d];
;         f4v o0 = v0 * c - v1 * s, o1 = v1 * c + v0 * s;
;         v0 = o0; v1 = o1;
;       }
;       st_h4(&ps[(size_t)m * NSM + n], v0);
;       st_h4(&ps[(size_t)m * NSM + n + 32], v1);
;     });
.Lp1e_store:
	ds_read_b128 v[150:153], v131 offset:0
	ds_read_b128 v[154:157], v131 offset:1152
	ds_read_b128 v[158:161], v131 offset:2304
	ds_read_b128 v[162:165], v131 offset:3456
	ds_read_b128 v[216:219], v131 offset:4608
	ds_read_b128 v[220:223], v131 offset:5760
	ds_read_b128 v[224:227], v131 offset:6912
	ds_read_b128 v[228:231], v131 offset:8064
	s_waitcnt lgkmcnt(7)
	global_store_dwordx4 v[132:133], v[150:153], off
	v_lshl_add_u64 v[132:133], v[132:133], 0, s[76:77]
	s_waitcnt lgkmcnt(6)
	global_store_dwordx4 v[132:133], v[154:157], off
	v_lshl_add_u64 v[132:133], v[132:133], 0, s[76:77]
	s_waitcnt lgkmcnt(5)
	global_store_dwordx4 v[132:133], v[158:161], off
	v_lshl_add_u64 v[132:133], v[132:133], 0, s[76:77]
	s_waitcnt lgkmcnt(4)
	global_store_dwordx4 v[132:133], v[162:165], off
	v_lshl_add_u64 v[132:133], v[132:133], 0, s[76:77]
	s_waitcnt lgkmcnt(3)
	global_store_dwordx4 v[132:133], v[216:219], off
	v_lshl_add_u64 v[132:133], v[132:133], 0, s[76:77]
	s_waitcnt lgkmcnt(2)
	global_store_dwordx4 v[132:133], v[220:223], off
	v_lshl_add_u64 v[132:133], v[132:133], 0, s[76:77]
	s_waitcnt lgkmcnt(1)
	global_store_dwordx4 v[132:133], v[224:227], off
	v_lshl_add_u64 v[132:133], v[132:133], 0, s[76:77]
	s_waitcnt lgkmcnt(0)
	global_store_dwordx4 v[132:133], v[228:231], off
	v_lshl_add_u64 v[132:133], v[132:133], 0, s[76:77]
	s_nop 1
	ds_read_b128 v[150:153], v131 offset:9216
	ds_read_b128 v[154:157], v131 offset:10368
	ds_read_b128 v[158:161], v131 offset:11520
	ds_read_b128 v[162:165], v131 offset:12672
	ds_read_b128 v[216:219], v131 offset:13824
	ds_read_b128 v[220:223], v131 offset:14976
	ds_read_b128 v[224:227], v131 offset:16128
	ds_read_b128 v[228:231], v131 offset:17280
	s_waitcnt lgkmcnt(7)
	global_store_dwordx4 v[132:133], v[150:153], off
	v_lshl_add_u64 v[132:133], v[132:133], 0, s[76:77]
	s_waitcnt lgkmcnt(6)
	global_store_dwordx4 v[132:133], v[154:157], off
	v_lshl_add_u64 v[132:133], v[132:133], 0, s[76:77]
	s_waitcnt lgkmcnt(5)
	global_store_dwordx4 v[132:133], v[158:161], off
	v_lshl_add_u64 v[132:133], v[132:133], 0, s[76:77]
	s_waitcnt lgkmcnt(4)
	global_store_dwordx4 v[132:133], v[162:165], off
	v_lshl_add_u64 v[132:133], v[132:133], 0, s[76:77]
	s_waitcnt lgkmcnt(3)
	global_store_dwordx4 v[132:133], v[216:219], off
	v_lshl_add_u64 v[132:133], v[132:133], 0, s[76:77]
	s_waitcnt lgkmcnt(2)
	global_store_dwordx4 v[132:133], v[220:223], off
	v_lshl_add_u64 v[132:133], v[132:133], 0, s[76:77]
	s_waitcnt lgkmcnt(1)
	global_store_dwordx4 v[132:133], v[224:227], off
	v_lshl_add_u64 v[132:133], v[132:133], 0, s[76:77]
	s_waitcnt lgkmcnt(0)
	global_store_dwordx4 v[132:133], v[228:231], off
	v_lshl_add_u64 v[132:133], v[132:133], 0, s[76:77]
	v_readlane_b32 s36, v252, 3
	v_readlane_b32 s42, v252, 9
	v_readlane_b32 s2, v255, 11
	s_nop 0
	s_add_i32 s19, s19, s42
	s_add_i32 s18, s18, s2
	v_readlane_b32 s40, v252, 7
	v_readlane_b32 s41, v252, 8
	s_cmpk_lt_i32 s19, 0x500
	v_readlane_b32 s37, v252, 4
	v_readlane_b32 s38, v252, 5
	v_readlane_b32 s39, v252, 6
	v_readlane_b32 s43, v252, 10
	s_cbranch_scc1 .LBB0_101

; template <bool GATHER>
; DI void gemm256_main(const h16* __restrict__ A, int lda, const int* __restrict__ idx, int m0,
;                      const h16* __restrict__ B, int ldb, int n0, int K, h16* lds, f16v (&acc)[4][2]) {
;   const int tid = otid512(), lane = tid & 63, wv = tid >> 6, wm = wv >> 2, wn = wv & 3;
;   const int lr = tid >> 1, lc = (tid & 1) * 32;
;   unsigned ao = (unsigned)(GATHER ? idx[m0 + lr] : (m0 + lr)) * (unsigned)lda + lc;
;   unsigned bo = (unsigned)(n0 + lr) * (unsigned)ldb + lc;
;   const h16* ap = A; const h16* bp = B;
;     ...
;   u4v ra[4], rb[4];
;   const int nk = K >> 6;
;   __syncthreads();
; #pragma unroll
;   for (int i = 0; i < 4; ++i) { ra[i] = *(const u4v*)(AP_ + 8 * i); rb[i] = *(const u4v*)(BP_ + 8 * i); }
;   ao += 64; bo += 64;
; #pragma unroll
;   for (int i = 0; i < 4; ++i) { *(u4v*)&lds[lr * LDH + lc + 8 * i] = ra[i]; *(u4v*)&lds[(256 + lr) * LDH + lc + 8 * i] = rb[i]; }
; #pragma unroll
;   for (int i = 0; i < 4; ++i) { ra[i] = *(const u4v*)(AP_ + 8 * i); rb[i] = *(const u4v*)(BP_ + 8 * i); }
;   ao += 64; bo += 64;
;   __syncthreads();
;   for (int kt = 0; kt < nk; ++kt) {
;     const h16* As = lds + (kt & 1) * (512 * LDH);
;     const h16* Bs = As + 256 * LDH;
;     h16* Wn = lds + ((kt & 1) ^ 1) * (512 * LDH);
;     if (kt + 1 < nk) {
; #pragma unroll
;       for (int i = 0; i < 4; ++i) { *(u4v*)&Wn[lr * LDH + lc + 8 * i] = ra[i]; *(u4v*)&Wn[(256 + lr) * LDH + lc + 8 * i] = rb[i]; }
;     }
;     if (kt + 2 < nk) {
; #pragma unroll
;       for (int i = 0; i < 4; ++i) { ra[i] = *(const u4v*)(AP_ + 8 * i); rb[i] = *(const u4v*)(BP_ + 8 * i); }
;       ao += 64; bo += 64;
;     }
; #pragma unroll
;     for (int ks = 0; ks < 4; ++ks) {
;       h8v af[4], bf[2];
; #pragma unroll
;       for (int i = 0; i < 4; ++i) af[i] = *(const h8v*)&As[(wm * 128 + i * 32 + (lane & 31)) * LDH + ks * 16 + 8 * (lane >> 5)];
; #pragma unroll
;       for (int j = 0; j < 2; ++j) bf[j] = *(const h8v*)&Bs[(wn * 64 + j * 32 + (lane & 31)) * LDH + ks * 16 + 8 * (lane >> 5)];
; #pragma unroll
;       for (int i = 0; i < 4; ++i)
; #pragma unroll
; DI void phase_gates(const Params& p, int bid, int nb, h16* lds) {
;     ...
;   for (int u = bid; u < 64 * 16; u += nb) {
;     const int m0 = (u >> 4) * 256, n0 = (u & 15) * 256;
;     f16v acc[4][2]; acc256_zero(acc);
;     gemm256_main<false>(x16, DM, nullptr, m0, wg, 1024, n0, 1024, lds, acc);
.LBB0_1246:
	v_mov_b32_e32 v1, v180
	s_and_b32 s6, s2, 0xffffff00
	s_and_b32 s5, s3, 0xf00
	v_mov_b32_e32 v177, v0
	v_ashrrev_i32_e32 v34, 1, v1
	v_lshlrev_b32_e32 v2, 5, v1
	v_and_b32_e32 v35, 32, v2
	v_add_u32_e32 v2, s6, v34
	v_add_u32_e32 v3, s5, v34
	v_lshl_or_b32 v2, v2, 10, v35
	v_lshl_or_b32 v176, v3, 10, v35
	v_mov_b32_e32 v3, v0
	v_lshl_add_u64 v[174:175], v[2:3], 1, s[20:21]
	v_lshl_add_u64 v[30:31], v[176:177], 1, s[16:17]
	s_barrier
	global_load_dwordx4 v[2:5], v[174:175], off offset:48
	global_load_dwordx4 v[6:9], v[174:175], off offset:32
	global_load_dwordx4 v[10:13], v[174:175], off offset:16
	global_load_dwordx4 v[14:17], v[174:175], off
	global_load_dwordx4 v[18:21], v[30:31], off offset:48
	global_load_dwordx4 v[22:25], v[30:31], off offset:32
	global_load_dwordx4 v[26:29], v[30:31], off offset:16
	s_nop 0
	global_load_dwordx4 v[30:33], v[30:31], off
	v_mul_lo_u32 v36, v34, s33
	v_lshlrev_b32_e32 v35, 1, v35
	v_add3_u32 v216, 16, v36, v35
	v_add_u32_e32 v177, 0x12000, v216
	v_add_u32_e32 v215, 0x1b000, v216
	v_and_b32_e32 v35, 31, v1
	v_and_or_b32 v34, v34, s18, v35
	v_and_b32_e32 v35, 0xdf, v1
	v_lshrrev_b32_e32 v1, 1, v1
	v_and_b32_e32 v219, 16, v1
	v_mul_lo_u32 v218, v34, s33
	v_add_u32_e32 v1, 16, v219
	v_add_u32_e32 v171, v1, v218
	v_mad_u32_u24 v1, v35, s33, v1
	v_mul_u32_u24_e32 v217, 0x90, v35
	v_or_b32_e32 v178, 0xc0, v176
	v_mov_b32_e32 v179, v0
	s_add_i32 s7, 16, 0x12000
	s_add_i32 s8, 16, 0x1b000
	s_add_i32 s4, s4, s22
	s_add_i32 s3, s3, s9
	s_add_i32 s2, s2, s35
	s_cmpk_lt_i32 s4, 0x400
	s_waitcnt vmcnt(4)
	ds_write_b128 v216, v[14:17]
	s_waitcnt vmcnt(0)
	ds_write_b128 v216, v[30:33] offset:36864
	ds_write_b128 v216, v[10:13] offset:16
	ds_write_b128 v216, v[26:29] offset:36880
	ds_write_b128 v216, v[6:9] offset:32
	ds_write_b128 v216, v[22:25] offset:36896
	ds_write_b128 v216, v[2:5] offset:48
	ds_write_b128 v216, v[18:21] offset:36912
	v_or_b32_e32 v2, 64, v176
	v_mov_b32_e32 v3, v0
	v_lshl_add_u64 v[30:31], v[2:3], 1, s[16:17]
	global_load_dwordx4 v[2:5], v[174:175], off offset:176
	global_load_dwordx4 v[6:9], v[174:175], off offset:160
	global_load_dwordx4 v[10:13], v[174:175], off offset:144
	global_load_dwordx4 v[14:17], v[174:175], off offset:128
	global_load_dwordx4 v[18:21], v[30:31], off offset:48
	global_load_dwordx4 v[22:25], v[30:31], off offset:32
	global_load_dwordx4 v[26:29], v[30:31], off offset:16
	s_nop 0
	global_load_dwordx4 v[30:33], v[30:31], off
	s_waitcnt lgkmcnt(0)
	s_barrier
	s_waitcnt vmcnt(4)
	ds_write_b128 v177, v[14:17]
	s_waitcnt vmcnt(0)
	ds_write_b128 v215, v[30:33]
	ds_write_b128 v177, v[10:13] offset:16
	ds_write_b128 v215, v[26:29] offset:16
	ds_write_b128 v177, v[6:9] offset:32
	ds_write_b128 v215, v[22:25] offset:32
	ds_write_b128 v177, v[2:5] offset:48
	ds_write_b128 v215, v[18:21] offset:48
	v_or_b32_e32 v2, 0x80, v176
	v_mov_b32_e32 v3, v0
	v_lshl_add_u64 v[2:3], v[2:3], 1, s[16:17]
	global_load_dwordx4 v[130:133], v[2:3], off offset:48
	global_load_dwordx4 v[134:137], v[2:3], off offset:32
	global_load_dwordx4 v[142:145], v[2:3], off offset:16
	global_load_dwordx4 v[150:153], v[2:3], off
	global_load_dwordx4 v[138:141], v[174:175], off offset:304
	global_load_dwordx4 v[146:149], v[174:175], off offset:288
	global_load_dwordx4 v[154:157], v[174:175], off offset:272
	global_load_dwordx4 v[158:161], v[174:175], off offset:256
	ds_read_b128 v[2:5], v171 offset:4608
	ds_read_b128 v[6:9], v171 offset:9216
	ds_read_b128 v[10:13], v171 offset:13824
	ds_read_b128 v[14:17], v1 offset:41472
	ds_read_b128 v[18:21], v171
	ds_read_b128 v[162:165], v171 offset:32
	ds_read_b128 v[22:25], v1 offset:36864
	ds_read_b128 v[220:223], v1 offset:36896
	s_waitcnt lgkmcnt(1)
	v_mfma_f32_32x32x16_f16 v[114:129], v[22:25], v[18:21], 0
	ds_read_b128 v[224:227], v171 offset:4640
	ds_read_b128 v[228:231], v171 offset:9248
	ds_read_b128 v[232:235], v171 offset:13856
	ds_read_b128 v[236:239], v1 offset:41504
	v_mfma_f32_32x32x16_f16 v[98:113], v[14:17], v[18:21], 0
	v_mfma_f32_32x32x16_f16 v[82:97], v[22:25], v[2:5], 0
	v_mfma_f32_32x32x16_f16 v[66:81], v[14:17], v[2:5], 0
	v_mfma_f32_32x32x16_f16 v[50:65], v[22:25], v[6:9], 0
	v_mfma_f32_32x32x16_f16 v[34:49], v[14:17], v[6:9], 0
	v_mfma_f32_32x32x16_f16 v[18:33], v[22:25], v[10:13], 0
	v_mfma_f32_32x32x16_f16 v[2:17], v[14:17], v[10:13], 0
	s_waitcnt lgkmcnt(4)
	v_mfma_f32_32x32x16_f16 v[114:129], v[220:223], v[162:165], v[114:129]
	s_waitcnt lgkmcnt(0)
	v_mfma_f32_32x32x16_f16 v[98:113], v[236:239], v[162:165], v[98:113]
	v_mfma_f32_32x32x16_f16 v[82:97], v[220:223], v[224:227], v[82:97]
	v_mfma_f32_32x32x16_f16 v[66:81], v[236:239], v[224:227], v[66:81]
	v_mfma_f32_32x32x16_f16 v[50:65], v[220:223], v[228:231], v[50:65]
	v_mfma_f32_32x32x16_f16 v[34:49], v[236:239], v[228:231], v[34:49]
	v_mfma_f32_32x32x16_f16 v[18:33], v[220:223], v[232:235], v[18:33]
	v_mfma_f32_32x32x16_f16 v[2:17], v[236:239], v[232:235], v[2:17]
	ds_read_b128 v[162:165], v171 offset:64
	ds_read_b128 v[220:223], v171 offset:4672
	ds_read_b128 v[224:227], v171 offset:9280
	ds_read_b128 v[228:231], v171 offset:13888
	ds_read_b128 v[232:235], v1 offset:36928
	ds_read_b128 v[236:239], v1 offset:41536
	s_waitcnt lgkmcnt(1)
	v_mfma_f32_32x32x16_f16 v[114:129], v[232:235], v[162:165], v[114:129]
	s_waitcnt lgkmcnt(0)
	v_mfma_f32_32x32x16_f16 v[98:113], v[236:239], v[162:165], v[98:113]
	v_mfma_f32_32x32x16_f16 v[82:97], v[232:235], v[220:223], v[82:97]
	v_mfma_f32_32x32x16_f16 v[66:81], v[236:239], v[220:223], v[66:81]
	v_mfma_f32_32x32x16_f16 v[50:65], v[232:235], v[224:227], v[50:65]
	v_mfma_f32_32x32x16_f16 v[34:49], v[236:239], v[224:227], v[34:49]
	v_mfma_f32_32x32x16_f16 v[18:33], v[232:235], v[228:231], v[18:33]
	v_mfma_f32_32x32x16_f16 v[2:17], v[236:239], v[228:231], v[2:17]
	ds_read_b128 v[162:165], v171 offset:96
	ds_read_b128 v[220:223], v171 offset:4704
	ds_read_b128 v[224:227], v171 offset:9312
	ds_read_b128 v[228:231], v171 offset:13920
	ds_read_b128 v[232:235], v1 offset:36960
	ds_read_b128 v[236:239], v1 offset:41568
	s_waitcnt lgkmcnt(0)
	s_barrier
; DI f16v mfma32(h8v a, h8v b, f16v c) { return __builtin_amdgcn_mfma_f32_32x32x16_f16(a, b, c, 0, 0, 0); }
; template <bool GATHER>
; DI void gemm256_main(const h16* __restrict__ A, int lda, const int* __restrict__ idx, int m0,
;                      const h16* __restrict__ B, int ldb, int n0, int K, h16* lds, f16v (&acc)[4][2]) {
;     ...
;   for (int kt = 0; kt < nk; ++kt) {
;     const h16* As = lds + (kt & 1) * (512 * LDH);
;     const h16* Bs = As + 256 * LDH;
;     h16* Wn = lds + ((kt & 1) ^ 1) * (512 * LDH);
;     if (kt + 1 < nk) {
; #pragma unroll
;       for (int i = 0; i < 4; ++i) { *(u4v*)&Wn[lr * LDH + lc + 8 * i] = ra[i]; *(u4v*)&Wn[(256 + lr) * LDH + lc + 8 * i] = rb[i]; }
;     }
;     if (kt + 2 < nk) {
; #pragma unroll
;       for (int i = 0; i < 4; ++i) { ra[i] = *(const u4v*)(AP_ + 8 * i); rb[i] = *(const u4v*)(BP_ + 8 * i); }
;       ao += 64; bo += 64;
;     }
; #pragma unroll
;     for (int ks = 0; ks < 4; ++ks) {
;       h8v af[4], bf[2];
; #pragma unroll
;       for (int i = 0; i < 4; ++i) af[i] = *(const h8v*)&As[(wm * 128 + i * 32 + (lane & 31)) * LDH + ks * 16 + 8 * (lane >> 5)];
; #pragma unroll
;       for (int j = 0; j < 2; ++j) bf[j] = *(const h8v*)&Bs[(wn * 64 + j * 32 + (lane & 31)) * LDH + ks * 16 + 8 * (lane >> 5)];
; #pragma unroll
;       for (int i = 0; i < 4; ++i)
; #pragma unroll
;         for (int j = 0; j < 2; ++j) acc[i][j] = mfma32(bf[j], af[i], acc[i][j]);
;     }
;     __syncthreads();
	s_waitcnt vmcnt(0)
	ds_write_b128 v216, v[158:161]
	ds_write_b128 v216, v[150:153] offset:36864
	ds_write_b128 v216, v[154:157] offset:16
	ds_write_b128 v216, v[142:145] offset:36880
	ds_write_b128 v216, v[146:149] offset:32
	ds_write_b128 v216, v[134:137] offset:36896
	ds_write_b128 v216, v[138:141] offset:48
	ds_write_b128 v216, v[130:133] offset:36912
	v_lshl_add_u64 v[138:139], v[178:179], 1, s[16:17]
	global_load_dwordx4 v[130:133], v[138:139], off offset:48
	global_load_dwordx4 v[134:137], v[138:139], off offset:32
	global_load_dwordx4 v[142:145], v[138:139], off offset:16
	global_load_dwordx4 v[150:153], v[138:139], off
	s_nop 0
	global_load_dwordx4 v[138:141], v[174:175], off offset:432
	global_load_dwordx4 v[146:149], v[174:175], off offset:416
	global_load_dwordx4 v[154:157], v[174:175], off offset:400
	global_load_dwordx4 v[158:161], v[174:175], off offset:384
	v_mfma_f32_32x32x16_f16 v[114:129], v[232:235], v[162:165], v[114:129]
	v_add3_u32 v179, s7, v219, v218
	v_add3_u32 v178, s8, v219, v217
	v_mfma_f32_32x32x16_f16 v[98:113], v[236:239], v[162:165], v[98:113]
	v_or_b32_e32 v162, 0x100, v176
	v_mov_b32_e32 v163, v0
	v_or_b32_e32 v164, 0x140, v176
	v_mov_b32_e32 v165, v0
	v_mfma_f32_32x32x16_f16 v[82:97], v[232:235], v[220:223], v[82:97]
	v_mfma_f32_32x32x16_f16 v[66:81], v[236:239], v[220:223], v[66:81]
	v_mfma_f32_32x32x16_f16 v[50:65], v[232:235], v[224:227], v[50:65]
	v_mfma_f32_32x32x16_f16 v[34:49], v[236:239], v[224:227], v[34:49]
	v_mfma_f32_32x32x16_f16 v[18:33], v[232:235], v[228:231], v[18:33]
	v_mfma_f32_32x32x16_f16 v[2:17], v[236:239], v[228:231], v[2:17]
	ds_read_b128 v[220:223], v179 offset:4608
	ds_read_b128 v[224:227], v179 offset:9216
	ds_read_b128 v[228:231], v179 offset:13824
	ds_read_b128 v[232:235], v178 offset:4608
	ds_read_b128 v[236:239], v179
	ds_read_b128 v[240:243], v179 offset:32
	ds_read_b128 v[244:247], v178
	ds_read_b128 v[248:251], v178 offset:32
	s_waitcnt lgkmcnt(1)
	v_mfma_f32_32x32x16_f16 v[114:129], v[244:247], v[236:239], v[114:129]
	v_mfma_f32_32x32x16_f16 v[98:113], v[232:235], v[236:239], v[98:113]
	v_mfma_f32_32x32x16_f16 v[82:97], v[244:247], v[220:223], v[82:97]
	v_mfma_f32_32x32x16_f16 v[66:81], v[232:235], v[220:223], v[66:81]
	v_mfma_f32_32x32x16_f16 v[50:65], v[244:247], v[224:227], v[50:65]
	v_mfma_f32_32x32x16_f16 v[34:49], v[232:235], v[224:227], v[34:49]
	v_mfma_f32_32x32x16_f16 v[18:33], v[244:247], v[228:231], v[18:33]
	v_mfma_f32_32x32x16_f16 v[2:17], v[232:235], v[228:231], v[2:17]
	ds_read_b128 v[218:221], v179 offset:4640
	ds_read_b128 v[222:225], v179 offset:9248
	ds_read_b128 v[226:229], v179 offset:13856
	ds_read_b128 v[230:233], v178 offset:4640
	s_waitcnt lgkmcnt(4)
	v_mfma_f32_32x32x16_f16 v[114:129], v[248:251], v[240:243], v[114:129]
	s_waitcnt lgkmcnt(0)
	v_mfma_f32_32x32x16_f16 v[98:113], v[230:233], v[240:243], v[98:113]
	v_mfma_f32_32x32x16_f16 v[82:97], v[248:251], v[218:221], v[82:97]
	v_mfma_f32_32x32x16_f16 v[66:81], v[230:233], v[218:221], v[66:81]
	v_mfma_f32_32x32x16_f16 v[50:65], v[248:251], v[222:225], v[50:65]
	v_mfma_f32_32x32x16_f16 v[34:49], v[230:233], v[222:225], v[34:49]
	v_mfma_f32_32x32x16_f16 v[18:33], v[248:251], v[226:229], v[18:33]
	v_mfma_f32_32x32x16_f16 v[2:17], v[230:233], v[226:229], v[2:17]
	ds_read_b128 v[218:221], v179 offset:64
	ds_read_b128 v[222:225], v179 offset:4672
	ds_read_b128 v[226:229], v179 offset:9280
	ds_read_b128 v[230:233], v179 offset:13888
	ds_read_b128 v[234:237], v178 offset:64
	ds_read_b128 v[238:241], v178 offset:4672
	s_waitcnt lgkmcnt(1)
	v_mfma_f32_32x32x16_f16 v[114:129], v[234:237], v[218:221], v[114:129]
	s_waitcnt lgkmcnt(0)
	v_mfma_f32_32x32x16_f16 v[98:113], v[238:241], v[218:221], v[98:113]
	v_mfma_f32_32x32x16_f16 v[82:97], v[234:237], v[222:225], v[82:97]
	v_mfma_f32_32x32x16_f16 v[66:81], v[238:241], v[222:225], v[66:81]
	v_mfma_f32_32x32x16_f16 v[50:65], v[234:237], v[226:229], v[50:65]
	v_mfma_f32_32x32x16_f16 v[34:49], v[238:241], v[226:229], v[34:49]
	v_mfma_f32_32x32x16_f16 v[18:33], v[234:237], v[230:233], v[18:33]
	v_mfma_f32_32x32x16_f16 v[2:17], v[238:241], v[230:233], v[2:17]
	ds_read_b128 v[218:221], v179 offset:96
	ds_read_b128 v[222:225], v179 offset:4704
	ds_read_b128 v[226:229], v179 offset:9312
	ds_read_b128 v[230:233], v179 offset:13920
	ds_read_b128 v[234:237], v178 offset:96
	ds_read_b128 v[238:241], v178 offset:4704
	s_waitcnt lgkmcnt(0)
	s_barrier
; DI f16v mfma32(h8v a, h8v b, f16v c) { return __builtin_amdgcn_mfma_f32_32x32x16_f16(a, b, c, 0, 0, 0); }
; template <bool GATHER>
; DI void gemm256_main(const h16* __restrict__ A, int lda, const int* __restrict__ idx, int m0,
;                      const h16* __restrict__ B, int ldb, int n0, int K, h16* lds, f16v (&acc)[4][2]) {
;     ...
;   for (int kt = 0; kt < nk; ++kt) {
;     const h16* As = lds + (kt & 1) * (512 * LDH);
;     const h16* Bs = As + 256 * LDH;
;     h16* Wn = lds + ((kt & 1) ^ 1) * (512 * LDH);
;     if (kt + 1 < nk) {
; #pragma unroll
;       for (int i = 0; i < 4; ++i) { *(u4v*)&Wn[lr * LDH + lc + 8 * i] = ra[i]; *(u4v*)&Wn[(256 + lr) * LDH + lc + 8 * i] = rb[i]; }
;     }
;     if (kt + 2 < nk) {
; #pragma unroll
;       for (int i = 0; i < 4; ++i) { ra[i] = *(const u4v*)(AP_ + 8 * i); rb[i] = *(const u4v*)(BP_ + 8 * i); }
;       ao += 64; bo += 64;
;     }
; #pragma unroll
;     for (int ks = 0; ks < 4; ++ks) {
;       h8v af[4], bf[2];
; #pragma unroll
;       for (int i = 0; i < 4; ++i) af[i] = *(const h8v*)&As[(wm * 128 + i * 32 + (lane & 31)) * LDH + ks * 16 + 8 * (lane >> 5)];
; #pragma unroll
;       for (int j = 0; j < 2; ++j) bf[j] = *(const h8v*)&Bs[(wn * 64 + j * 32 + (lane & 31)) * LDH + ks * 16 + 8 * (lane >> 5)];
; #pragma unroll
;       for (int i = 0; i < 4; ++i)
; #pragma unroll
;         for (int j = 0; j < 2; ++j) acc[i][j] = mfma32(bf[j], af[i], acc[i][j]);
;     }
;     __syncthreads();
	s_waitcnt vmcnt(0)
	ds_write_b128 v177, v[158:161]
	ds_write_b128 v215, v[150:153]
	ds_write_b128 v177, v[154:157] offset:16
	ds_write_b128 v215, v[142:145] offset:16
	ds_write_b128 v177, v[146:149] offset:32
	ds_write_b128 v215, v[134:137] offset:32
	ds_write_b128 v177, v[138:141] offset:48
	ds_write_b128 v215, v[130:133] offset:48
	v_lshl_add_u64 v[138:139], v[162:163], 1, s[16:17]
	global_load_dwordx4 v[130:133], v[138:139], off offset:48
	global_load_dwordx4 v[134:137], v[138:139], off offset:32
	global_load_dwordx4 v[142:145], v[138:139], off offset:16
	global_load_dwordx4 v[150:153], v[138:139], off
	s_nop 0
	global_load_dwordx4 v[138:141], v[174:175], off offset:560
	global_load_dwordx4 v[146:149], v[174:175], off offset:544
	global_load_dwordx4 v[154:157], v[174:175], off offset:528
	global_load_dwordx4 v[158:161], v[174:175], off offset:512
	v_mfma_f32_32x32x16_f16 v[114:129], v[234:237], v[218:221], v[114:129]
	v_or_b32_e32 v162, 0x180, v176
	v_mfma_f32_32x32x16_f16 v[98:113], v[238:241], v[218:221], v[98:113]
	v_mfma_f32_32x32x16_f16 v[82:97], v[234:237], v[222:225], v[82:97]
	v_mfma_f32_32x32x16_f16 v[66:81], v[238:241], v[222:225], v[66:81]
	v_mfma_f32_32x32x16_f16 v[50:65], v[234:237], v[226:229], v[50:65]
	v_mfma_f32_32x32x16_f16 v[34:49], v[238:241], v[226:229], v[34:49]
	v_mfma_f32_32x32x16_f16 v[18:33], v[234:237], v[230:233], v[18:33]
	v_mfma_f32_32x32x16_f16 v[2:17], v[238:241], v[230:233], v[2:17]
	ds_read_b128 v[218:221], v171 offset:4608
	ds_read_b128 v[222:225], v171 offset:9216
	ds_read_b128 v[226:229], v171 offset:13824
	ds_read_b128 v[230:233], v1 offset:41472
	ds_read_b128 v[234:237], v171
	ds_read_b128 v[238:241], v171 offset:32
	ds_read_b128 v[242:245], v1 offset:36864
	ds_read_b128 v[246:249], v1 offset:36896
	s_waitcnt lgkmcnt(1)
	v_mfma_f32_32x32x16_f16 v[114:129], v[242:245], v[234:237], v[114:129]
	v_mfma_f32_32x32x16_f16 v[98:113], v[230:233], v[234:237], v[98:113]
	v_mfma_f32_32x32x16_f16 v[82:97], v[242:245], v[218:221], v[82:97]
	v_mfma_f32_32x32x16_f16 v[66:81], v[230:233], v[218:221], v[66:81]
	v_mfma_f32_32x32x16_f16 v[50:65], v[242:245], v[222:225], v[50:65]
	v_mfma_f32_32x32x16_f16 v[34:49], v[230:233], v[222:225], v[34:49]
	v_mfma_f32_32x32x16_f16 v[18:33], v[242:245], v[226:229], v[18:33]
	v_mfma_f32_32x32x16_f16 v[2:17], v[230:233], v[226:229], v[2:17]
	ds_read_b128 v[218:221], v171 offset:4640
	ds_read_b128 v[222:225], v171 offset:9248
	ds_read_b128 v[226:229], v171 offset:13856
	ds_read_b128 v[230:233], v1 offset:41504
	s_waitcnt lgkmcnt(4)
	v_mfma_f32_32x32x16_f16 v[114:129], v[246:249], v[238:241], v[114:129]
	s_waitcnt lgkmcnt(0)
	v_mfma_f32_32x32x16_f16 v[98:113], v[230:233], v[238:241], v[98:113]
	v_mfma_f32_32x32x16_f16 v[82:97], v[246:249], v[218:221], v[82:97]
	v_mfma_f32_32x32x16_f16 v[66:81], v[230:233], v[218:221], v[66:81]
	v_mfma_f32_32x32x16_f16 v[50:65], v[246:249], v[222:225], v[50:65]
	v_mfma_f32_32x32x16_f16 v[34:49], v[230:233], v[222:225], v[34:49]
	v_mfma_f32_32x32x16_f16 v[18:33], v[246:249], v[226:229], v[18:33]
	v_mfma_f32_32x32x16_f16 v[2:17], v[230:233], v[226:229], v[2:17]
	ds_read_b128 v[218:221], v171 offset:64
	ds_read_b128 v[222:225], v171 offset:4672
	ds_read_b128 v[226:229], v171 offset:9280
	ds_read_b128 v[230:233], v171 offset:13888
	ds_read_b128 v[234:237], v1 offset:36928
	ds_read_b128 v[238:241], v1 offset:41536
	s_waitcnt lgkmcnt(1)
	v_mfma_f32_32x32x16_f16 v[114:129], v[234:237], v[218:221], v[114:129]
	s_waitcnt lgkmcnt(0)
	v_mfma_f32_32x32x16_f16 v[98:113], v[238:241], v[218:221], v[98:113]
	v_mfma_f32_32x32x16_f16 v[82:97], v[234:237], v[222:225], v[82:97]
	v_mfma_f32_32x32x16_f16 v[66:81], v[238:241], v[222:225], v[66:81]
	v_mfma_f32_32x32x16_f16 v[50:65], v[234:237], v[226:229], v[50:65]
	v_mfma_f32_32x32x16_f16 v[34:49], v[238:241], v[226:229], v[34:49]
	v_mfma_f32_32x32x16_f16 v[18:33], v[234:237], v[230:233], v[18:33]
	v_mfma_f32_32x32x16_f16 v[2:17], v[238:241], v[230:233], v[2:17]
	ds_read_b128 v[218:221], v171 offset:96
	ds_read_b128 v[222:225], v171 offset:4704
	ds_read_b128 v[226:229], v171 offset:9312
	ds_read_b128 v[230:233], v171 offset:13920
	ds_read_b128 v[234:237], v1 offset:36960
	ds_read_b128 v[238:241], v1 offset:41568
	s_waitcnt lgkmcnt(0)
	s_barrier
; DI f16v mfma32(h8v a, h8v b, f16v c) { return __builtin_amdgcn_mfma_f32_32x32x16_f16(a, b, c, 0, 0, 0); }
; template <bool GATHER>
; DI void gemm256_main(const h16* __restrict__ A, int lda, const int* __restrict__ idx, int m0,
;                      const h16* __restrict__ B, int ldb, int n0, int K, h16* lds, f16v (&acc)[4][2]) {
;     ...
;   for (int kt = 0; kt < nk; ++kt) {
;     const h16* As = lds + (kt & 1) * (512 * LDH);
;     const h16* Bs = As + 256 * LDH;
;     h16* Wn = lds + ((kt & 1) ^ 1) * (512 * LDH);
;     if (kt + 1 < nk) {
; #pragma unroll
;       for (int i = 0; i < 4; ++i) { *(u4v*)&Wn[lr * LDH + lc + 8 * i] = ra[i]; *(u4v*)&Wn[(256 + lr) * LDH + lc + 8 * i] = rb[i]; }
;     }
;     if (kt + 2 < nk) {
; #pragma unroll
;       for (int i = 0; i < 4; ++i) { ra[i] = *(const u4v*)(AP_ + 8 * i); rb[i] = *(const u4v*)(BP_ + 8 * i); }
;       ao += 64; bo += 64;
;     }
; #pragma unroll
;     for (int ks = 0; ks < 4; ++ks) {
;       h8v af[4], bf[2];
; #pragma unroll
;       for (int i = 0; i < 4; ++i) af[i] = *(const h8v*)&As[(wm * 128 + i * 32 + (lane & 31)) * LDH + ks * 16 + 8 * (lane >> 5)];
; #pragma unroll
;       for (int j = 0; j < 2; ++j) bf[j] = *(const h8v*)&Bs[(wn * 64 + j * 32 + (lane & 31)) * LDH + ks * 16 + 8 * (lane >> 5)];
; #pragma unroll
;       for (int i = 0; i < 4; ++i)
; #pragma unroll
;         for (int j = 0; j < 2; ++j) acc[i][j] = mfma32(bf[j], af[i], acc[i][j]);
;     }
;     __syncthreads();
	s_waitcnt vmcnt(0)
	ds_write_b128 v216, v[158:161]
	ds_write_b128 v216, v[150:153] offset:36864
	ds_write_b128 v216, v[154:157] offset:16
	ds_write_b128 v216, v[142:145] offset:36880
	ds_write_b128 v216, v[146:149] offset:32
	ds_write_b128 v216, v[134:137] offset:36896
	ds_write_b128 v216, v[138:141] offset:48
	ds_write_b128 v216, v[130:133] offset:36912
	v_lshl_add_u64 v[138:139], v[164:165], 1, s[16:17]
	global_load_dwordx4 v[130:133], v[138:139], off offset:48
	global_load_dwordx4 v[134:137], v[138:139], off offset:32
	global_load_dwordx4 v[142:145], v[138:139], off offset:16
	global_load_dwordx4 v[150:153], v[138:139], off
	s_nop 0
	global_load_dwordx4 v[138:141], v[174:175], off offset:688
	global_load_dwordx4 v[146:149], v[174:175], off offset:672
	global_load_dwordx4 v[154:157], v[174:175], off offset:656
	global_load_dwordx4 v[158:161], v[174:175], off offset:640
	v_mfma_f32_32x32x16_f16 v[114:129], v[234:237], v[218:221], v[114:129]
	v_or_b32_e32 v164, 0x1c0, v176
	v_mfma_f32_32x32x16_f16 v[98:113], v[238:241], v[218:221], v[98:113]
	v_mfma_f32_32x32x16_f16 v[82:97], v[234:237], v[222:225], v[82:97]
	v_mfma_f32_32x32x16_f16 v[66:81], v[238:241], v[222:225], v[66:81]
	v_mfma_f32_32x32x16_f16 v[50:65], v[234:237], v[226:229], v[50:65]
	v_mfma_f32_32x32x16_f16 v[34:49], v[238:241], v[226:229], v[34:49]
	v_mfma_f32_32x32x16_f16 v[18:33], v[234:237], v[230:233], v[18:33]
	v_mfma_f32_32x32x16_f16 v[2:17], v[238:241], v[230:233], v[2:17]
	ds_read_b128 v[218:221], v179 offset:4608
	ds_read_b128 v[222:225], v179 offset:9216
	ds_read_b128 v[226:229], v179 offset:13824
	ds_read_b128 v[230:233], v178 offset:4608
	ds_read_b128 v[234:237], v179
	ds_read_b128 v[238:241], v179 offset:32
	ds_read_b128 v[242:245], v178
	ds_read_b128 v[246:249], v178 offset:32
	s_waitcnt lgkmcnt(1)
	v_mfma_f32_32x32x16_f16 v[114:129], v[242:245], v[234:237], v[114:129]
	v_mfma_f32_32x32x16_f16 v[98:113], v[230:233], v[234:237], v[98:113]
	v_mfma_f32_32x32x16_f16 v[82:97], v[242:245], v[218:221], v[82:97]
	v_mfma_f32_32x32x16_f16 v[66:81], v[230:233], v[218:221], v[66:81]
	v_mfma_f32_32x32x16_f16 v[50:65], v[242:245], v[222:225], v[50:65]
	v_mfma_f32_32x32x16_f16 v[34:49], v[230:233], v[222:225], v[34:49]
	v_mfma_f32_32x32x16_f16 v[18:33], v[242:245], v[226:229], v[18:33]
	v_mfma_f32_32x32x16_f16 v[2:17], v[230:233], v[226:229], v[2:17]
	ds_read_b128 v[218:221], v179 offset:4640
	ds_read_b128 v[222:225], v179 offset:9248
	ds_read_b128 v[226:229], v179 offset:13856
	ds_read_b128 v[230:233], v178 offset:4640
	s_waitcnt lgkmcnt(4)
	v_mfma_f32_32x32x16_f16 v[114:129], v[246:249], v[238:241], v[114:129]
	s_waitcnt lgkmcnt(0)
	v_mfma_f32_32x32x16_f16 v[98:113], v[230:233], v[238:241], v[98:113]
	v_mfma_f32_32x32x16_f16 v[82:97], v[246:249], v[218:221], v[82:97]
	v_mfma_f32_32x32x16_f16 v[66:81], v[230:233], v[218:221], v[66:81]
	v_mfma_f32_32x32x16_f16 v[50:65], v[246:249], v[222:225], v[50:65]
	v_mfma_f32_32x32x16_f16 v[34:49], v[230:233], v[222:225], v[34:49]
	v_mfma_f32_32x32x16_f16 v[18:33], v[246:249], v[226:229], v[18:33]
	v_mfma_f32_32x32x16_f16 v[2:17], v[230:233], v[226:229], v[2:17]
	ds_read_b128 v[218:221], v179 offset:64
	ds_read_b128 v[222:225], v179 offset:4672
	ds_read_b128 v[226:229], v179 offset:9280
	ds_read_b128 v[230:233], v179 offset:13888
	ds_read_b128 v[234:237], v178 offset:64
	ds_read_b128 v[238:241], v178 offset:4672
	s_waitcnt lgkmcnt(1)
	v_mfma_f32_32x32x16_f16 v[114:129], v[234:237], v[218:221], v[114:129]
	s_waitcnt lgkmcnt(0)
	v_mfma_f32_32x32x16_f16 v[98:113], v[238:241], v[218:221], v[98:113]
	v_mfma_f32_32x32x16_f16 v[82:97], v[234:237], v[222:225], v[82:97]
	v_mfma_f32_32x32x16_f16 v[66:81], v[238:241], v[222:225], v[66:81]
	v_mfma_f32_32x32x16_f16 v[50:65], v[234:237], v[226:229], v[50:65]
	v_mfma_f32_32x32x16_f16 v[34:49], v[238:241], v[226:229], v[34:49]
	v_mfma_f32_32x32x16_f16 v[18:33], v[234:237], v[230:233], v[18:33]
	v_mfma_f32_32x32x16_f16 v[2:17], v[238:241], v[230:233], v[2:17]
	ds_read_b128 v[218:221], v179 offset:96
	ds_read_b128 v[222:225], v179 offset:4704
	ds_read_b128 v[226:229], v179 offset:9312
	ds_read_b128 v[230:233], v179 offset:13920
	ds_read_b128 v[234:237], v178 offset:96
	ds_read_b128 v[238:241], v178 offset:4704
	s_waitcnt lgkmcnt(0)
	s_barrier
; DI f16v mfma32(h8v a, h8v b, f16v c) { return __builtin_amdgcn_mfma_f32_32x32x16_f16(a, b, c, 0, 0, 0); }
; template <bool GATHER>
; DI void gemm256_main(const h16* __restrict__ A, int lda, const int* __restrict__ idx, int m0,
;                      const h16* __restrict__ B, int ldb, int n0, int K, h16* lds, f16v (&acc)[4][2]) {
;     ...
;   for (int kt = 0; kt < nk; ++kt) {
;     const h16* As = lds + (kt & 1) * (512 * LDH);
;     const h16* Bs = As + 256 * LDH;
;     h16* Wn = lds + ((kt & 1) ^ 1) * (512 * LDH);
;     if (kt + 1 < nk) {
; #pragma unroll
;       for (int i = 0; i < 4; ++i) { *(u4v*)&Wn[lr * LDH + lc + 8 * i] = ra[i]; *(u4v*)&Wn[(256 + lr) * LDH + lc + 8 * i] = rb[i]; }
;     }
;     if (kt + 2 < nk) {
; #pragma unroll
;       for (int i = 0; i < 4; ++i) { ra[i] = *(const u4v*)(AP_ + 8 * i); rb[i] = *(const u4v*)(BP_ + 8 * i); }
;       ao += 64; bo += 64;
;     }
; #pragma unroll
;     for (int ks = 0; ks < 4; ++ks) {
;       h8v af[4], bf[2];
; #pragma unroll
;       for (int i = 0; i < 4; ++i) af[i] = *(const h8v*)&As[(wm * 128 + i * 32 + (lane & 31)) * LDH + ks * 16 + 8 * (lane >> 5)];
; #pragma unroll
;       for (int j = 0; j < 2; ++j) bf[j] = *(const h8v*)&Bs[(wn * 64 + j * 32 + (lane & 31)) * LDH + ks * 16 + 8 * (lane >> 5)];
; #pragma unroll
;       for (int i = 0; i < 4; ++i)
; #pragma unroll
;         for (int j = 0; j < 2; ++j) acc[i][j] = mfma32(bf[j], af[i], acc[i][j]);
;     }
;     __syncthreads();
;   }
	s_waitcnt vmcnt(0)
	ds_write_b128 v177, v[158:161]
	ds_write_b128 v215, v[150:153]
	ds_write_b128 v177, v[154:157] offset:16
	ds_write_b128 v215, v[142:145] offset:16
	ds_write_b128 v177, v[146:149] offset:32
	ds_write_b128 v215, v[134:137] offset:32
	ds_write_b128 v177, v[138:141] offset:48
	ds_write_b128 v215, v[130:133] offset:48
	v_lshl_add_u64 v[138:139], v[162:163], 1, s[16:17]
	global_load_dwordx4 v[130:133], v[138:139], off offset:48
	global_load_dwordx4 v[134:137], v[138:139], off offset:32
	global_load_dwordx4 v[142:145], v[138:139], off offset:16
	global_load_dwordx4 v[150:153], v[138:139], off
	s_nop 0
	global_load_dwordx4 v[138:141], v[174:175], off offset:816
	global_load_dwordx4 v[146:149], v[174:175], off offset:800
	global_load_dwordx4 v[154:157], v[174:175], off offset:784
	global_load_dwordx4 v[158:161], v[174:175], off offset:768
	v_mfma_f32_32x32x16_f16 v[114:129], v[234:237], v[218:221], v[114:129]
	v_or_b32_e32 v162, 0x200, v176
	v_mfma_f32_32x32x16_f16 v[98:113], v[238:241], v[218:221], v[98:113]
	v_mfma_f32_32x32x16_f16 v[82:97], v[234:237], v[222:225], v[82:97]
	v_mfma_f32_32x32x16_f16 v[66:81], v[238:241], v[222:225], v[66:81]
	v_mfma_f32_32x32x16_f16 v[50:65], v[234:237], v[226:229], v[50:65]
	v_mfma_f32_32x32x16_f16 v[34:49], v[238:241], v[226:229], v[34:49]
	v_mfma_f32_32x32x16_f16 v[18:33], v[234:237], v[230:233], v[18:33]
	v_mfma_f32_32x32x16_f16 v[2:17], v[238:241], v[230:233], v[2:17]
	ds_read_b128 v[218:221], v171 offset:4608
	ds_read_b128 v[222:225], v171 offset:9216
	ds_read_b128 v[226:229], v171 offset:13824
	ds_read_b128 v[230:233], v1 offset:41472
	ds_read_b128 v[234:237], v171
	ds_read_b128 v[238:241], v171 offset:32
	ds_read_b128 v[242:245], v1 offset:36864
	ds_read_b128 v[246:249], v1 offset:36896
	s_waitcnt lgkmcnt(1)
	v_mfma_f32_32x32x16_f16 v[114:129], v[242:245], v[234:237], v[114:129]
	v_mfma_f32_32x32x16_f16 v[98:113], v[230:233], v[234:237], v[98:113]
	v_mfma_f32_32x32x16_f16 v[82:97], v[242:245], v[218:221], v[82:97]
	v_mfma_f32_32x32x16_f16 v[66:81], v[230:233], v[218:221], v[66:81]
	v_mfma_f32_32x32x16_f16 v[50:65], v[242:245], v[222:225], v[50:65]
	v_mfma_f32_32x32x16_f16 v[34:49], v[230:233], v[222:225], v[34:49]
	v_mfma_f32_32x32x16_f16 v[18:33], v[242:245], v[226:229], v[18:33]
	v_mfma_f32_32x32x16_f16 v[2:17], v[230:233], v[226:229], v[2:17]
	ds_read_b128 v[218:221], v171 offset:4640
	ds_read_b128 v[222:225], v171 offset:9248
	ds_read_b128 v[226:229], v171 offset:13856
	ds_read_b128 v[230:233], v1 offset:41504
	s_waitcnt lgkmcnt(4)
	v_mfma_f32_32x32x16_f16 v[114:129], v[246:249], v[238:241], v[114:129]
	s_waitcnt lgkmcnt(0)
	v_mfma_f32_32x32x16_f16 v[98:113], v[230:233], v[238:241], v[98:113]
	v_mfma_f32_32x32x16_f16 v[82:97], v[246:249], v[218:221], v[82:97]
	v_mfma_f32_32x32x16_f16 v[66:81], v[230:233], v[218:221], v[66:81]
	v_mfma_f32_32x32x16_f16 v[50:65], v[246:249], v[222:225], v[50:65]
	v_mfma_f32_32x32x16_f16 v[34:49], v[230:233], v[222:225], v[34:49]
	v_mfma_f32_32x32x16_f16 v[18:33], v[246:249], v[226:229], v[18:33]
	v_mfma_f32_32x32x16_f16 v[2:17], v[230:233], v[226:229], v[2:17]
	ds_read_b128 v[218:221], v171 offset:64
	ds_read_b128 v[222:225], v171 offset:4672
	ds_read_b128 v[226:229], v171 offset:9280
	ds_read_b128 v[230:233], v171 offset:13888
	ds_read_b128 v[234:237], v1 offset:36928
	ds_read_b128 v[238:241], v1 offset:41536
	s_waitcnt lgkmcnt(1)
	v_mfma_f32_32x32x16_f16 v[114:129], v[234:237], v[218:221], v[114:129]
	s_waitcnt lgkmcnt(0)
	v_mfma_f32_32x32x16_f16 v[98:113], v[238:241], v[218:221], v[98:113]
	v_mfma_f32_32x32x16_f16 v[82:97], v[234:237], v[222:225], v[82:97]
	v_mfma_f32_32x32x16_f16 v[66:81], v[238:241], v[222:225], v[66:81]
	v_mfma_f32_32x32x16_f16 v[50:65], v[234:237], v[226:229], v[50:65]
	v_mfma_f32_32x32x16_f16 v[34:49], v[238:241], v[226:229], v[34:49]
	v_mfma_f32_32x32x16_f16 v[18:33], v[234:237], v[230:233], v[18:33]
	v_mfma_f32_32x32x16_f16 v[2:17], v[238:241], v[230:233], v[2:17]
	ds_read_b128 v[218:221], v171 offset:96
	ds_read_b128 v[222:225], v171 offset:4704
	ds_read_b128 v[226:229], v171 offset:9312
	ds_read_b128 v[230:233], v171 offset:13920
	ds_read_b128 v[234:237], v1 offset:36960
	ds_read_b128 v[238:241], v1 offset:41568
	s_waitcnt lgkmcnt(0)
	s_barrier
; DI f16v mfma32(h8v a, h8v b, f16v c) { return __builtin_amdgcn_mfma_f32_32x32x16_f16(a, b, c, 0, 0, 0); }
; template <bool GATHER>
; DI void gemm256_main(const h16* __restrict__ A, int lda, const int* __restrict__ idx, int m0,
;                      const h16* __restrict__ B, int ldb, int n0, int K, h16* lds, f16v (&acc)[4][2]) {
;     ...
;   for (int kt = 0; kt < nk; ++kt) {
;     const h16* As = lds + (kt & 1) * (512 * LDH);
;     const h16* Bs = As + 256 * LDH;
;     h16* Wn = lds + ((kt & 1) ^ 1) * (512 * LDH);
;     if (kt + 1 < nk) {
; #pragma unroll
;       for (int i = 0; i < 4; ++i) { *(u4v*)&Wn[lr * LDH + lc + 8 * i] = ra[i]; *(u4v*)&Wn[(256 + lr) * LDH + lc + 8 * i] = rb[i]; }
;     }
;     if (kt + 2 < nk) {
; #pragma unroll
;       for (int i = 0; i < 4; ++i) { ra[i] = *(const u4v*)(AP_ + 8 * i); rb[i] = *(const u4v*)(BP_ + 8 * i); }
;       ao += 64; bo += 64;
;     }
; #pragma unroll
;     for (int ks = 0; ks < 4; ++ks) {
;       h8v af[4], bf[2];
; #pragma unroll
;       for (int i = 0; i < 4; ++i) af[i] = *(const h8v*)&As[(wm * 128 + i * 32 + (lane & 31)) * LDH + ks * 16 + 8 * (lane >> 5)];
; #pragma unroll
;       for (int j = 0; j < 2; ++j) bf[j] = *(const h8v*)&Bs[(wn * 64 + j * 32 + (lane & 31)) * LDH + ks * 16 + 8 * (lane >> 5)];
; #pragma unroll
;       for (int i = 0; i < 4; ++i)
; #pragma unroll
;         for (int j = 0; j < 2; ++j) acc[i][j] = mfma32(bf[j], af[i], acc[i][j]);
;     }
;     __syncthreads();
;   }
	s_waitcnt vmcnt(0)
	ds_write_b128 v216, v[158:161]
	ds_write_b128 v216, v[150:153] offset:36864
	ds_write_b128 v216, v[154:157] offset:16
	ds_write_b128 v216, v[142:145] offset:36880
	ds_write_b128 v216, v[146:149] offset:32
	ds_write_b128 v216, v[134:137] offset:36896
	ds_write_b128 v216, v[138:141] offset:48
	ds_write_b128 v216, v[130:133] offset:36912
	v_lshl_add_u64 v[138:139], v[164:165], 1, s[16:17]
	global_load_dwordx4 v[130:133], v[138:139], off offset:48
	global_load_dwordx4 v[134:137], v[138:139], off offset:32
	global_load_dwordx4 v[142:145], v[138:139], off offset:16
	global_load_dwordx4 v[150:153], v[138:139], off
	s_nop 0
	global_load_dwordx4 v[138:141], v[174:175], off offset:944
	global_load_dwordx4 v[146:149], v[174:175], off offset:928
	global_load_dwordx4 v[154:157], v[174:175], off offset:912
	global_load_dwordx4 v[158:161], v[174:175], off offset:896
	v_mfma_f32_32x32x16_f16 v[114:129], v[234:237], v[218:221], v[114:129]
	v_or_b32_e32 v164, 0x240, v176
	v_mfma_f32_32x32x16_f16 v[98:113], v[238:241], v[218:221], v[98:113]
	v_mfma_f32_32x32x16_f16 v[82:97], v[234:237], v[222:225], v[82:97]
	v_mfma_f32_32x32x16_f16 v[66:81], v[238:241], v[222:225], v[66:81]
	v_mfma_f32_32x32x16_f16 v[50:65], v[234:237], v[226:229], v[50:65]
	v_mfma_f32_32x32x16_f16 v[34:49], v[238:241], v[226:229], v[34:49]
	v_mfma_f32_32x32x16_f16 v[18:33], v[234:237], v[230:233], v[18:33]
	v_mfma_f32_32x32x16_f16 v[2:17], v[238:241], v[230:233], v[2:17]
	ds_read_b128 v[218:221], v179 offset:4608
	ds_read_b128 v[222:225], v179 offset:9216
	ds_read_b128 v[226:229], v179 offset:13824
	ds_read_b128 v[230:233], v178 offset:4608
	ds_read_b128 v[234:237], v179
	ds_read_b128 v[238:241], v179 offset:32
	ds_read_b128 v[242:245], v178
	ds_read_b128 v[246:249], v178 offset:32
	s_waitcnt lgkmcnt(1)
	v_mfma_f32_32x32x16_f16 v[114:129], v[242:245], v[234:237], v[114:129]
	v_mfma_f32_32x32x16_f16 v[98:113], v[230:233], v[234:237], v[98:113]
	v_mfma_f32_32x32x16_f16 v[82:97], v[242:245], v[218:221], v[82:97]
	v_mfma_f32_32x32x16_f16 v[66:81], v[230:233], v[218:221], v[66:81]
	v_mfma_f32_32x32x16_f16 v[50:65], v[242:245], v[222:225], v[50:65]
	v_mfma_f32_32x32x16_f16 v[34:49], v[230:233], v[222:225], v[34:49]
	v_mfma_f32_32x32x16_f16 v[18:33], v[242:245], v[226:229], v[18:33]
	v_mfma_f32_32x32x16_f16 v[2:17], v[230:233], v[226:229], v[2:17]
	ds_read_b128 v[218:221], v179 offset:4640
	ds_read_b128 v[222:225], v179 offset:9248
	ds_read_b128 v[226:229], v179 offset:13856
	ds_read_b128 v[230:233], v178 offset:4640
	s_waitcnt lgkmcnt(4)
	v_mfma_f32_32x32x16_f16 v[114:129], v[246:249], v[238:241], v[114:129]
	s_waitcnt lgkmcnt(0)
	v_mfma_f32_32x32x16_f16 v[98:113], v[230:233], v[238:241], v[98:113]
	v_mfma_f32_32x32x16_f16 v[82:97], v[246:249], v[218:221], v[82:97]
	v_mfma_f32_32x32x16_f16 v[66:81], v[230:233], v[218:221], v[66:81]
	v_mfma_f32_32x32x16_f16 v[50:65], v[246:249], v[222:225], v[50:65]
	v_mfma_f32_32x32x16_f16 v[34:49], v[230:233], v[222:225], v[34:49]
	v_mfma_f32_32x32x16_f16 v[18:33], v[246:249], v[226:229], v[18:33]
	v_mfma_f32_32x32x16_f16 v[2:17], v[230:233], v[226:229], v[2:17]
	ds_read_b128 v[218:221], v179 offset:64
	ds_read_b128 v[222:225], v179 offset:4672
	ds_read_b128 v[226:229], v179 offset:9280
	ds_read_b128 v[230:233], v179 offset:13888
	ds_read_b128 v[234:237], v178 offset:64
	ds_read_b128 v[238:241], v178 offset:4672
	s_waitcnt lgkmcnt(1)
	v_mfma_f32_32x32x16_f16 v[114:129], v[234:237], v[218:221], v[114:129]
	s_waitcnt lgkmcnt(0)
	v_mfma_f32_32x32x16_f16 v[98:113], v[238:241], v[218:221], v[98:113]
	v_mfma_f32_32x32x16_f16 v[82:97], v[234:237], v[222:225], v[82:97]
	v_mfma_f32_32x32x16_f16 v[66:81], v[238:241], v[222:225], v[66:81]
	v_mfma_f32_32x32x16_f16 v[50:65], v[234:237], v[226:229], v[50:65]
	v_mfma_f32_32x32x16_f16 v[34:49], v[238:241], v[226:229], v[34:49]
	v_mfma_f32_32x32x16_f16 v[18:33], v[234:237], v[230:233], v[18:33]
	v_mfma_f32_32x32x16_f16 v[2:17], v[238:241], v[230:233], v[2:17]
	ds_read_b128 v[218:221], v179 offset:96
	ds_read_b128 v[222:225], v179 offset:4704
	ds_read_b128 v[226:229], v179 offset:9312
	ds_read_b128 v[230:233], v179 offset:13920
	ds_read_b128 v[234:237], v178 offset:96
	ds_read_b128 v[238:241], v178 offset:4704
	s_waitcnt lgkmcnt(0)
	s_barrier
; DI f16v mfma32(h8v a, h8v b, f16v c) { return __builtin_amdgcn_mfma_f32_32x32x16_f16(a, b, c, 0, 0, 0); }
; template <bool GATHER>
; DI void gemm256_main(const h16* __restrict__ A, int lda, const int* __restrict__ idx, int m0,
;                      const h16* __restrict__ B, int ldb, int n0, int K, h16* lds, f16v (&acc)[4][2]) {
;     ...
;   for (int kt = 0; kt < nk; ++kt) {
;     const h16* As = lds + (kt & 1) * (512 * LDH);
;     const h16* Bs = As + 256 * LDH;
;     h16* Wn = lds + ((kt & 1) ^ 1) * (512 * LDH);
;     if (kt + 1 < nk) {
; #pragma unroll
;       for (int i = 0; i < 4; ++i) { *(u4v*)&Wn[lr * LDH + lc + 8 * i] = ra[i]; *(u4v*)&Wn[(256 + lr) * LDH + lc + 8 * i] = rb[i]; }
;     }
;     if (kt + 2 < nk) {
; #pragma unroll
;       for (int i = 0; i < 4; ++i) { ra[i] = *(const u4v*)(AP_ + 8 * i); rb[i] = *(const u4v*)(BP_ + 8 * i); }
;       ao += 64; bo += 64;
;     }
; #pragma unroll
;     for (int ks = 0; ks < 4; ++ks) {
;       h8v af[4], bf[2];
; #pragma unroll
;       for (int i = 0; i < 4; ++i) af[i] = *(const h8v*)&As[(wm * 128 + i * 32 + (lane & 31)) * LDH + ks * 16 + 8 * (lane >> 5)];
; #pragma unroll
;       for (int j = 0; j < 2; ++j) bf[j] = *(const h8v*)&Bs[(wn * 64 + j * 32 + (lane & 31)) * LDH + ks * 16 + 8 * (lane >> 5)];
; #pragma unroll
;       for (int i = 0; i < 4; ++i)
; #pragma unroll
;         for (int j = 0; j < 2; ++j) acc[i][j] = mfma32(bf[j], af[i], acc[i][j]);
;     }
;     __syncthreads();
;   }
	s_waitcnt vmcnt(0)
	ds_write_b128 v177, v[158:161]
	ds_write_b128 v215, v[150:153]
	ds_write_b128 v177, v[154:157] offset:16
	ds_write_b128 v215, v[142:145] offset:16
	ds_write_b128 v177, v[146:149] offset:32
	ds_write_b128 v215, v[134:137] offset:32
	ds_write_b128 v177, v[138:141] offset:48
	ds_write_b128 v215, v[130:133] offset:48
	v_lshl_add_u64 v[138:139], v[162:163], 1, s[16:17]
	global_load_dwordx4 v[130:133], v[138:139], off offset:48
	global_load_dwordx4 v[134:137], v[138:139], off offset:32
	global_load_dwordx4 v[142:145], v[138:139], off offset:16
	global_load_dwordx4 v[150:153], v[138:139], off
	s_nop 0
	global_load_dwordx4 v[138:141], v[174:175], off offset:1072
	global_load_dwordx4 v[146:149], v[174:175], off offset:1056
	global_load_dwordx4 v[154:157], v[174:175], off offset:1040
	global_load_dwordx4 v[158:161], v[174:175], off offset:1024
	v_mfma_f32_32x32x16_f16 v[114:129], v[234:237], v[218:221], v[114:129]
	v_or_b32_e32 v162, 0x280, v176
	v_mfma_f32_32x32x16_f16 v[98:113], v[238:241], v[218:221], v[98:113]
	v_mfma_f32_32x32x16_f16 v[82:97], v[234:237], v[222:225], v[82:97]
	v_mfma_f32_32x32x16_f16 v[66:81], v[238:241], v[222:225], v[66:81]
	v_mfma_f32_32x32x16_f16 v[50:65], v[234:237], v[226:229], v[50:65]
	v_mfma_f32_32x32x16_f16 v[34:49], v[238:241], v[226:229], v[34:49]
	v_mfma_f32_32x32x16_f16 v[18:33], v[234:237], v[230:233], v[18:33]
	v_mfma_f32_32x32x16_f16 v[2:17], v[238:241], v[230:233], v[2:17]
	ds_read_b128 v[218:221], v171 offset:4608
	ds_read_b128 v[222:225], v171 offset:9216
	ds_read_b128 v[226:229], v171 offset:13824
	ds_read_b128 v[230:233], v1 offset:41472
	ds_read_b128 v[234:237], v171
	ds_read_b128 v[238:241], v171 offset:32
	ds_read_b128 v[242:245], v1 offset:36864
	ds_read_b128 v[246:249], v1 offset:36896
	s_waitcnt lgkmcnt(1)
	v_mfma_f32_32x32x16_f16 v[114:129], v[242:245], v[234:237], v[114:129]
	v_mfma_f32_32x32x16_f16 v[98:113], v[230:233], v[234:237], v[98:113]
	v_mfma_f32_32x32x16_f16 v[82:97], v[242:245], v[218:221], v[82:97]
	v_mfma_f32_32x32x16_f16 v[66:81], v[230:233], v[218:221], v[66:81]
	v_mfma_f32_32x32x16_f16 v[50:65], v[242:245], v[222:225], v[50:65]
	v_mfma_f32_32x32x16_f16 v[34:49], v[230:233], v[222:225], v[34:49]
	v_mfma_f32_32x32x16_f16 v[18:33], v[242:245], v[226:229], v[18:33]
	v_mfma_f32_32x32x16_f16 v[2:17], v[230:233], v[226:229], v[2:17]
	ds_read_b128 v[218:221], v171 offset:4640
	ds_read_b128 v[222:225], v171 offset:9248
	ds_read_b128 v[226:229], v171 offset:13856
	ds_read_b128 v[230:233], v1 offset:41504
	s_waitcnt lgkmcnt(4)
	v_mfma_f32_32x32x16_f16 v[114:129], v[246:249], v[238:241], v[114:129]
	s_waitcnt lgkmcnt(0)
	v_mfma_f32_32x32x16_f16 v[98:113], v[230:233], v[238:241], v[98:113]
	v_mfma_f32_32x32x16_f16 v[82:97], v[246:249], v[218:221], v[82:97]
	v_mfma_f32_32x32x16_f16 v[66:81], v[230:233], v[218:221], v[66:81]
	v_mfma_f32_32x32x16_f16 v[50:65], v[246:249], v[222:225], v[50:65]
	v_mfma_f32_32x32x16_f16 v[34:49], v[230:233], v[222:225], v[34:49]
	v_mfma_f32_32x32x16_f16 v[18:33], v[246:249], v[226:229], v[18:33]
	v_mfma_f32_32x32x16_f16 v[2:17], v[230:233], v[226:229], v[2:17]
	ds_read_b128 v[218:221], v171 offset:64
	ds_read_b128 v[222:225], v171 offset:4672
	ds_read_b128 v[226:229], v171 offset:9280
	ds_read_b128 v[230:233], v171 offset:13888
	ds_read_b128 v[234:237], v1 offset:36928
	ds_read_b128 v[238:241], v1 offset:41536
	s_waitcnt lgkmcnt(1)
	v_mfma_f32_32x32x16_f16 v[114:129], v[234:237], v[218:221], v[114:129]
	s_waitcnt lgkmcnt(0)
	v_mfma_f32_32x32x16_f16 v[98:113], v[238:241], v[218:221], v[98:113]
	v_mfma_f32_32x32x16_f16 v[82:97], v[234:237], v[222:225], v[82:97]
	v_mfma_f32_32x32x16_f16 v[66:81], v[238:241], v[222:225], v[66:81]
	v_mfma_f32_32x32x16_f16 v[50:65], v[234:237], v[226:229], v[50:65]
	v_mfma_f32_32x32x16_f16 v[34:49], v[238:241], v[226:229], v[34:49]
	v_mfma_f32_32x32x16_f16 v[18:33], v[234:237], v[230:233], v[18:33]
	v_mfma_f32_32x32x16_f16 v[2:17], v[238:241], v[230:233], v[2:17]
	ds_read_b128 v[218:221], v171 offset:96
	ds_read_b128 v[222:225], v171 offset:4704
	ds_read_b128 v[226:229], v171 offset:9312
	ds_read_b128 v[230:233], v171 offset:13920
	ds_read_b128 v[234:237], v1 offset:36960
	ds_read_b128 v[238:241], v1 offset:41568
	s_waitcnt lgkmcnt(0)
	s_barrier
; DI f16v mfma32(h8v a, h8v b, f16v c) { return __builtin_amdgcn_mfma_f32_32x32x16_f16(a, b, c, 0, 0, 0); }
; template <bool GATHER>
; DI void gemm256_main(const h16* __restrict__ A, int lda, const int* __restrict__ idx, int m0,
;                      const h16* __restrict__ B, int ldb, int n0, int K, h16* lds, f16v (&acc)[4][2]) {
;     ...
;   for (int kt = 0; kt < nk; ++kt) {
;     const h16* As = lds + (kt & 1) * (512 * LDH);
;     const h16* Bs = As + 256 * LDH;
;     h16* Wn = lds + ((kt & 1) ^ 1) * (512 * LDH);
;     if (kt + 1 < nk) {
; #pragma unroll
;       for (int i = 0; i < 4; ++i) { *(u4v*)&Wn[lr * LDH + lc + 8 * i] = ra[i]; *(u4v*)&Wn[(256 + lr) * LDH + lc + 8 * i] = rb[i]; }
;     }
;     if (kt + 2 < nk) {
; #pragma unroll
;       for (int i = 0; i < 4; ++i) { ra[i] = *(const u4v*)(AP_ + 8 * i); rb[i] = *(const u4v*)(BP_ + 8 * i); }
;       ao += 64; bo += 64;
;     }
; #pragma unroll
;     for (int ks = 0; ks < 4; ++ks) {
;       h8v af[4], bf[2];
; #pragma unroll
;       for (int i = 0; i < 4; ++i) af[i] = *(const h8v*)&As[(wm * 128 + i * 32 + (lane & 31)) * LDH + ks * 16 + 8 * (lane >> 5)];
; #pragma unroll
;       for (int j = 0; j < 2; ++j) bf[j] = *(const h8v*)&Bs[(wn * 64 + j * 32 + (lane & 31)) * LDH + ks * 16 + 8 * (lane >> 5)];
; #pragma unroll
;       for (int i = 0; i < 4; ++i)
; #pragma unroll
;         for (int j = 0; j < 2; ++j) acc[i][j] = mfma32(bf[j], af[i], acc[i][j]);
;     }
;     __syncthreads();
;   }
	s_waitcnt vmcnt(0)
	ds_write_b128 v216, v[158:161]
	ds_write_b128 v216, v[150:153] offset:36864
	ds_write_b128 v216, v[154:157] offset:16
	ds_write_b128 v216, v[142:145] offset:36880
	ds_write_b128 v216, v[146:149] offset:32
	ds_write_b128 v216, v[134:137] offset:36896
	ds_write_b128 v216, v[138:141] offset:48
	ds_write_b128 v216, v[130:133] offset:36912
	v_lshl_add_u64 v[138:139], v[164:165], 1, s[16:17]
	global_load_dwordx4 v[130:133], v[138:139], off offset:48
	global_load_dwordx4 v[134:137], v[138:139], off offset:32
	global_load_dwordx4 v[142:145], v[138:139], off offset:16
	global_load_dwordx4 v[150:153], v[138:139], off
	s_nop 0
	global_load_dwordx4 v[138:141], v[174:175], off offset:1200
	global_load_dwordx4 v[146:149], v[174:175], off offset:1184
	global_load_dwordx4 v[154:157], v[174:175], off offset:1168
	global_load_dwordx4 v[158:161], v[174:175], off offset:1152
	v_mfma_f32_32x32x16_f16 v[114:129], v[234:237], v[218:221], v[114:129]
	v_or_b32_e32 v164, 0x2c0, v176
	v_mfma_f32_32x32x16_f16 v[98:113], v[238:241], v[218:221], v[98:113]
	v_mfma_f32_32x32x16_f16 v[82:97], v[234:237], v[222:225], v[82:97]
	v_mfma_f32_32x32x16_f16 v[66:81], v[238:241], v[222:225], v[66:81]
	v_mfma_f32_32x32x16_f16 v[50:65], v[234:237], v[226:229], v[50:65]
	v_mfma_f32_32x32x16_f16 v[34:49], v[238:241], v[226:229], v[34:49]
	v_mfma_f32_32x32x16_f16 v[18:33], v[234:237], v[230:233], v[18:33]
	v_mfma_f32_32x32x16_f16 v[2:17], v[238:241], v[230:233], v[2:17]
	ds_read_b128 v[218:221], v179 offset:4608
	ds_read_b128 v[222:225], v179 offset:9216
	ds_read_b128 v[226:229], v179 offset:13824
	ds_read_b128 v[230:233], v178 offset:4608
	ds_read_b128 v[234:237], v179
	ds_read_b128 v[238:241], v179 offset:32
	ds_read_b128 v[242:245], v178
	ds_read_b128 v[246:249], v178 offset:32
	s_waitcnt lgkmcnt(1)
	v_mfma_f32_32x32x16_f16 v[114:129], v[242:245], v[234:237], v[114:129]
	v_mfma_f32_32x32x16_f16 v[98:113], v[230:233], v[234:237], v[98:113]
	v_mfma_f32_32x32x16_f16 v[82:97], v[242:245], v[218:221], v[82:97]
	v_mfma_f32_32x32x16_f16 v[66:81], v[230:233], v[218:221], v[66:81]
	v_mfma_f32_32x32x16_f16 v[50:65], v[242:245], v[222:225], v[50:65]
	v_mfma_f32_32x32x16_f16 v[34:49], v[230:233], v[222:225], v[34:49]
	v_mfma_f32_32x32x16_f16 v[18:33], v[242:245], v[226:229], v[18:33]
	v_mfma_f32_32x32x16_f16 v[2:17], v[230:233], v[226:229], v[2:17]
	ds_read_b128 v[218:221], v179 offset:4640
	ds_read_b128 v[222:225], v179 offset:9248
	ds_read_b128 v[226:229], v179 offset:13856
	ds_read_b128 v[230:233], v178 offset:4640
	s_waitcnt lgkmcnt(4)
	v_mfma_f32_32x32x16_f16 v[114:129], v[246:249], v[238:241], v[114:129]
	s_waitcnt lgkmcnt(0)
	v_mfma_f32_32x32x16_f16 v[98:113], v[230:233], v[238:241], v[98:113]
	v_mfma_f32_32x32x16_f16 v[82:97], v[246:249], v[218:221], v[82:97]
	v_mfma_f32_32x32x16_f16 v[66:81], v[230:233], v[218:221], v[66:81]
	v_mfma_f32_32x32x16_f16 v[50:65], v[246:249], v[222:225], v[50:65]
	v_mfma_f32_32x32x16_f16 v[34:49], v[230:233], v[222:225], v[34:49]
	v_mfma_f32_32x32x16_f16 v[18:33], v[246:249], v[226:229], v[18:33]
	v_mfma_f32_32x32x16_f16 v[2:17], v[230:233], v[226:229], v[2:17]
	ds_read_b128 v[218:221], v179 offset:64
	ds_read_b128 v[222:225], v179 offset:4672
	ds_read_b128 v[226:229], v179 offset:9280
	ds_read_b128 v[230:233], v179 offset:13888
	ds_read_b128 v[234:237], v178 offset:64
	ds_read_b128 v[238:241], v178 offset:4672
	s_waitcnt lgkmcnt(1)
	v_mfma_f32_32x32x16_f16 v[114:129], v[234:237], v[218:221], v[114:129]
	s_waitcnt lgkmcnt(0)
	v_mfma_f32_32x32x16_f16 v[98:113], v[238:241], v[218:221], v[98:113]
	v_mfma_f32_32x32x16_f16 v[82:97], v[234:237], v[222:225], v[82:97]
	v_mfma_f32_32x32x16_f16 v[66:81], v[238:241], v[222:225], v[66:81]
	v_mfma_f32_32x32x16_f16 v[50:65], v[234:237], v[226:229], v[50:65]
	v_mfma_f32_32x32x16_f16 v[34:49], v[238:241], v[226:229], v[34:49]
	v_mfma_f32_32x32x16_f16 v[18:33], v[234:237], v[230:233], v[18:33]
	v_mfma_f32_32x32x16_f16 v[2:17], v[238:241], v[230:233], v[2:17]
	ds_read_b128 v[218:221], v179 offset:96
	ds_read_b128 v[222:225], v179 offset:4704
	ds_read_b128 v[226:229], v179 offset:9312
	ds_read_b128 v[230:233], v179 offset:13920
	ds_read_b128 v[234:237], v178 offset:96
	ds_read_b128 v[238:241], v178 offset:4704
	s_waitcnt lgkmcnt(0)
	s_barrier
; DI f16v mfma32(h8v a, h8v b, f16v c) { return __builtin_amdgcn_mfma_f32_32x32x16_f16(a, b, c, 0, 0, 0); }
; template <bool GATHER>
; DI void gemm256_main(const h16* __restrict__ A, int lda, const int* __restrict__ idx, int m0,
;                      const h16* __restrict__ B, int ldb, int n0, int K, h16* lds, f16v (&acc)[4][2]) {
;     ...
;   for (int kt = 0; kt < nk; ++kt) {
;     const h16* As = lds + (kt & 1) * (512 * LDH);
;     const h16* Bs = As + 256 * LDH;
;     h16* Wn = lds + ((kt & 1) ^ 1) * (512 * LDH);
;     if (kt + 1 < nk) {
; #pragma unroll
;       for (int i = 0; i < 4; ++i) { *(u4v*)&Wn[lr * LDH + lc + 8 * i] = ra[i]; *(u4v*)&Wn[(256 + lr) * LDH + lc + 8 * i] = rb[i]; }
;     }
;     if (kt + 2 < nk) {
; #pragma unroll
;       for (int i = 0; i < 4; ++i) { ra[i] = *(const u4v*)(AP_ + 8 * i); rb[i] = *(const u4v*)(BP_ + 8 * i); }
;       ao += 64; bo += 64;
;     }
; #pragma unroll
;     for (int ks = 0; ks < 4; ++ks) {
;       h8v af[4], bf[2];
; #pragma unroll
;       for (int i = 0; i < 4; ++i) af[i] = *(const h8v*)&As[(wm * 128 + i * 32 + (lane & 31)) * LDH + ks * 16 + 8 * (lane >> 5)];
; #pragma unroll
;       for (int j = 0; j < 2; ++j) bf[j] = *(const h8v*)&Bs[(wn * 64 + j * 32 + (lane & 31)) * LDH + ks * 16 + 8 * (lane >> 5)];
; #pragma unroll
;       for (int i = 0; i < 4; ++i)
; #pragma unroll
;         for (int j = 0; j < 2; ++j) acc[i][j] = mfma32(bf[j], af[i], acc[i][j]);
;     }
;     __syncthreads();
;   }
	s_waitcnt vmcnt(0)
	ds_write_b128 v177, v[158:161]
	ds_write_b128 v215, v[150:153]
	ds_write_b128 v177, v[154:157] offset:16
	ds_write_b128 v215, v[142:145] offset:16
	ds_write_b128 v177, v[146:149] offset:32
	ds_write_b128 v215, v[134:137] offset:32
	ds_write_b128 v177, v[138:141] offset:48
	ds_write_b128 v215, v[130:133] offset:48
	v_lshl_add_u64 v[138:139], v[162:163], 1, s[16:17]
	global_load_dwordx4 v[130:133], v[138:139], off offset:48
	global_load_dwordx4 v[134:137], v[138:139], off offset:32
	global_load_dwordx4 v[142:145], v[138:139], off offset:16
	global_load_dwordx4 v[150:153], v[138:139], off
	s_nop 0
	global_load_dwordx4 v[138:141], v[174:175], off offset:1328
	global_load_dwordx4 v[146:149], v[174:175], off offset:1312
	global_load_dwordx4 v[154:157], v[174:175], off offset:1296
	global_load_dwordx4 v[158:161], v[174:175], off offset:1280
	v_mfma_f32_32x32x16_f16 v[114:129], v[234:237], v[218:221], v[114:129]
	v_or_b32_e32 v162, 0x300, v176
	v_mfma_f32_32x32x16_f16 v[98:113], v[238:241], v[218:221], v[98:113]
	v_mfma_f32_32x32x16_f16 v[82:97], v[234:237], v[222:225], v[82:97]
	v_mfma_f32_32x32x16_f16 v[66:81], v[238:241], v[222:225], v[66:81]
	v_mfma_f32_32x32x16_f16 v[50:65], v[234:237], v[226:229], v[50:65]
	v_mfma_f32_32x32x16_f16 v[34:49], v[238:241], v[226:229], v[34:49]
	v_mfma_f32_32x32x16_f16 v[18:33], v[234:237], v[230:233], v[18:33]
	v_mfma_f32_32x32x16_f16 v[2:17], v[238:241], v[230:233], v[2:17]
	ds_read_b128 v[218:221], v171 offset:4608
	ds_read_b128 v[222:225], v171 offset:9216
	ds_read_b128 v[226:229], v171 offset:13824
	ds_read_b128 v[230:233], v1 offset:41472
	ds_read_b128 v[234:237], v171
	ds_read_b128 v[238:241], v171 offset:32
	ds_read_b128 v[242:245], v1 offset:36864
	ds_read_b128 v[246:249], v1 offset:36896
	s_waitcnt lgkmcnt(1)
	v_mfma_f32_32x32x16_f16 v[114:129], v[242:245], v[234:237], v[114:129]
	v_mfma_f32_32x32x16_f16 v[98:113], v[230:233], v[234:237], v[98:113]
	v_mfma_f32_32x32x16_f16 v[82:97], v[242:245], v[218:221], v[82:97]
	v_mfma_f32_32x32x16_f16 v[66:81], v[230:233], v[218:221], v[66:81]
	v_mfma_f32_32x32x16_f16 v[50:65], v[242:245], v[222:225], v[50:65]
	v_mfma_f32_32x32x16_f16 v[34:49], v[230:233], v[222:225], v[34:49]
	v_mfma_f32_32x32x16_f16 v[18:33], v[242:245], v[226:229], v[18:33]
	v_mfma_f32_32x32x16_f16 v[2:17], v[230:233], v[226:229], v[2:17]
	ds_read_b128 v[218:221], v171 offset:4640
	ds_read_b128 v[222:225], v171 offset:9248
	ds_read_b128 v[226:229], v171 offset:13856
	ds_read_b128 v[230:233], v1 offset:41504
	s_waitcnt lgkmcnt(4)
	v_mfma_f32_32x32x16_f16 v[114:129], v[246:249], v[238:241], v[114:129]
	s_waitcnt lgkmcnt(0)
	v_mfma_f32_32x32x16_f16 v[98:113], v[230:233], v[238:241], v[98:113]
	v_mfma_f32_32x32x16_f16 v[82:97], v[246:249], v[218:221], v[82:97]
	v_mfma_f32_32x32x16_f16 v[66:81], v[230:233], v[218:221], v[66:81]
	v_mfma_f32_32x32x16_f16 v[50:65], v[246:249], v[222:225], v[50:65]
	v_mfma_f32_32x32x16_f16 v[34:49], v[230:233], v[222:225], v[34:49]
	v_mfma_f32_32x32x16_f16 v[18:33], v[246:249], v[226:229], v[18:33]
	v_mfma_f32_32x32x16_f16 v[2:17], v[230:233], v[226:229], v[2:17]
	ds_read_b128 v[218:221], v171 offset:64
	ds_read_b128 v[222:225], v171 offset:4672
	ds_read_b128 v[226:229], v171 offset:9280
	ds_read_b128 v[230:233], v171 offset:13888
	ds_read_b128 v[234:237], v1 offset:36928
	ds_read_b128 v[238:241], v1 offset:41536
	s_waitcnt lgkmcnt(1)
	v_mfma_f32_32x32x16_f16 v[114:129], v[234:237], v[218:221], v[114:129]
	s_waitcnt lgkmcnt(0)
	v_mfma_f32_32x32x16_f16 v[98:113], v[238:241], v[218:221], v[98:113]
	v_mfma_f32_32x32x16_f16 v[82:97], v[234:237], v[222:225], v[82:97]
	v_mfma_f32_32x32x16_f16 v[66:81], v[238:241], v[222:225], v[66:81]
	v_mfma_f32_32x32x16_f16 v[50:65], v[234:237], v[226:229], v[50:65]
	v_mfma_f32_32x32x16_f16 v[34:49], v[238:241], v[226:229], v[34:49]
	v_mfma_f32_32x32x16_f16 v[18:33], v[234:237], v[230:233], v[18:33]
	v_mfma_f32_32x32x16_f16 v[2:17], v[238:241], v[230:233], v[2:17]
	ds_read_b128 v[218:221], v171 offset:96
	ds_read_b128 v[222:225], v171 offset:4704
	ds_read_b128 v[226:229], v171 offset:9312
	ds_read_b128 v[230:233], v171 offset:13920
	ds_read_b128 v[234:237], v1 offset:36960
	ds_read_b128 v[238:241], v1 offset:41568
	s_waitcnt lgkmcnt(0)
	s_barrier
; DI f16v mfma32(h8v a, h8v b, f16v c) { return __builtin_amdgcn_mfma_f32_32x32x16_f16(a, b, c, 0, 0, 0); }
; template <bool GATHER>
; DI void gemm256_main(const h16* __restrict__ A, int lda, const int* __restrict__ idx, int m0,
;                      const h16* __restrict__ B, int ldb, int n0, int K, h16* lds, f16v (&acc)[4][2]) {
;     ...
;   for (int kt = 0; kt < nk; ++kt) {
;     const h16* As = lds + (kt & 1) * (512 * LDH);
;     const h16* Bs = As + 256 * LDH;
;     h16* Wn = lds + ((kt & 1) ^ 1) * (512 * LDH);
;     if (kt + 1 < nk) {
; #pragma unroll
;       for (int i = 0; i < 4; ++i) { *(u4v*)&Wn[lr * LDH + lc + 8 * i] = ra[i]; *(u4v*)&Wn[(256 + lr) * LDH + lc + 8 * i] = rb[i]; }
;     }
;     if (kt + 2 < nk) {
; #pragma unroll
;       for (int i = 0; i < 4; ++i) { ra[i] = *(const u4v*)(AP_ + 8 * i); rb[i] = *(const u4v*)(BP_ + 8 * i); }
;       ao += 64; bo += 64;
;     }
; #pragma unroll
;     for (int ks = 0; ks < 4; ++ks) {
;       h8v af[4], bf[2];
; #pragma unroll
;       for (int i = 0; i < 4; ++i) af[i] = *(const h8v*)&As[(wm * 128 + i * 32 + (lane & 31)) * LDH + ks * 16 + 8 * (lane >> 5)];
; #pragma unroll
;       for (int j = 0; j < 2; ++j) bf[j] = *(const h8v*)&Bs[(wn * 64 + j * 32 + (lane & 31)) * LDH + ks * 16 + 8 * (lane >> 5)];
; #pragma unroll
;       for (int i = 0; i < 4; ++i)
; #pragma unroll
;         for (int j = 0; j < 2; ++j) acc[i][j] = mfma32(bf[j], af[i], acc[i][j]);
;     }
;     __syncthreads();
;   }
	s_waitcnt vmcnt(0)
	ds_write_b128 v216, v[158:161]
	ds_write_b128 v216, v[150:153] offset:36864
	ds_write_b128 v216, v[154:157] offset:16
	ds_write_b128 v216, v[142:145] offset:36880
	ds_write_b128 v216, v[146:149] offset:32
	ds_write_b128 v216, v[134:137] offset:36896
	ds_write_b128 v216, v[138:141] offset:48
	ds_write_b128 v216, v[130:133] offset:36912
	v_lshl_add_u64 v[138:139], v[164:165], 1, s[16:17]
	global_load_dwordx4 v[130:133], v[138:139], off offset:48
	global_load_dwordx4 v[134:137], v[138:139], off offset:32
	global_load_dwordx4 v[142:145], v[138:139], off offset:16
	global_load_dwordx4 v[150:153], v[138:139], off
	s_nop 0
	global_load_dwordx4 v[138:141], v[174:175], off offset:1456
	global_load_dwordx4 v[146:149], v[174:175], off offset:1440
	global_load_dwordx4 v[154:157], v[174:175], off offset:1424
	global_load_dwordx4 v[158:161], v[174:175], off offset:1408
	v_mfma_f32_32x32x16_f16 v[114:129], v[234:237], v[218:221], v[114:129]
	v_or_b32_e32 v164, 0x340, v176
	v_mfma_f32_32x32x16_f16 v[98:113], v[238:241], v[218:221], v[98:113]
	v_mfma_f32_32x32x16_f16 v[82:97], v[234:237], v[222:225], v[82:97]
	v_mfma_f32_32x32x16_f16 v[66:81], v[238:241], v[222:225], v[66:81]
	v_mfma_f32_32x32x16_f16 v[50:65], v[234:237], v[226:229], v[50:65]
	v_mfma_f32_32x32x16_f16 v[34:49], v[238:241], v[226:229], v[34:49]
	v_mfma_f32_32x32x16_f16 v[18:33], v[234:237], v[230:233], v[18:33]
	v_mfma_f32_32x32x16_f16 v[2:17], v[238:241], v[230:233], v[2:17]
	ds_read_b128 v[218:221], v179 offset:4608
	ds_read_b128 v[222:225], v179 offset:9216
	ds_read_b128 v[226:229], v179 offset:13824
	ds_read_b128 v[230:233], v178 offset:4608
	ds_read_b128 v[234:237], v179
	ds_read_b128 v[238:241], v179 offset:32
	ds_read_b128 v[242:245], v178
	ds_read_b128 v[246:249], v178 offset:32
	s_waitcnt lgkmcnt(1)
	v_mfma_f32_32x32x16_f16 v[114:129], v[242:245], v[234:237], v[114:129]
	v_mfma_f32_32x32x16_f16 v[98:113], v[230:233], v[234:237], v[98:113]
	v_mfma_f32_32x32x16_f16 v[82:97], v[242:245], v[218:221], v[82:97]
	v_mfma_f32_32x32x16_f16 v[66:81], v[230:233], v[218:221], v[66:81]
	v_mfma_f32_32x32x16_f16 v[50:65], v[242:245], v[222:225], v[50:65]
	v_mfma_f32_32x32x16_f16 v[34:49], v[230:233], v[222:225], v[34:49]
	v_mfma_f32_32x32x16_f16 v[18:33], v[242:245], v[226:229], v[18:33]
	v_mfma_f32_32x32x16_f16 v[2:17], v[230:233], v[226:229], v[2:17]
	ds_read_b128 v[218:221], v179 offset:4640
	ds_read_b128 v[222:225], v179 offset:9248
	ds_read_b128 v[226:229], v179 offset:13856
	ds_read_b128 v[230:233], v178 offset:4640
	s_waitcnt lgkmcnt(4)
	v_mfma_f32_32x32x16_f16 v[114:129], v[246:249], v[238:241], v[114:129]
	s_waitcnt lgkmcnt(0)
	v_mfma_f32_32x32x16_f16 v[98:113], v[230:233], v[238:241], v[98:113]
	v_mfma_f32_32x32x16_f16 v[82:97], v[246:249], v[218:221], v[82:97]
	v_mfma_f32_32x32x16_f16 v[66:81], v[230:233], v[218:221], v[66:81]
	v_mfma_f32_32x32x16_f16 v[50:65], v[246:249], v[222:225], v[50:65]
	v_mfma_f32_32x32x16_f16 v[34:49], v[230:233], v[222:225], v[34:49]
	v_mfma_f32_32x32x16_f16 v[18:33], v[246:249], v[226:229], v[18:33]
	v_mfma_f32_32x32x16_f16 v[2:17], v[230:233], v[226:229], v[2:17]
	ds_read_b128 v[218:221], v179 offset:64
	ds_read_b128 v[222:225], v179 offset:4672
	ds_read_b128 v[226:229], v179 offset:9280
	ds_read_b128 v[230:233], v179 offset:13888
	ds_read_b128 v[234:237], v178 offset:64
	ds_read_b128 v[238:241], v178 offset:4672
	s_waitcnt lgkmcnt(1)
	v_mfma_f32_32x32x16_f16 v[114:129], v[234:237], v[218:221], v[114:129]
	s_waitcnt lgkmcnt(0)
	v_mfma_f32_32x32x16_f16 v[98:113], v[238:241], v[218:221], v[98:113]
	v_mfma_f32_32x32x16_f16 v[82:97], v[234:237], v[222:225], v[82:97]
	v_mfma_f32_32x32x16_f16 v[66:81], v[238:241], v[222:225], v[66:81]
	v_mfma_f32_32x32x16_f16 v[50:65], v[234:237], v[226:229], v[50:65]
	v_mfma_f32_32x32x16_f16 v[34:49], v[238:241], v[226:229], v[34:49]
	v_mfma_f32_32x32x16_f16 v[18:33], v[234:237], v[230:233], v[18:33]
	v_mfma_f32_32x32x16_f16 v[2:17], v[238:241], v[230:233], v[2:17]
	ds_read_b128 v[218:221], v179 offset:96
	ds_read_b128 v[222:225], v179 offset:4704
	ds_read_b128 v[226:229], v179 offset:9312
	ds_read_b128 v[230:233], v179 offset:13920
	ds_read_b128 v[234:237], v178 offset:96
	ds_read_b128 v[238:241], v178 offset:4704
	s_waitcnt lgkmcnt(0)
	s_barrier
; DI f16v mfma32(h8v a, h8v b, f16v c) { return __builtin_amdgcn_mfma_f32_32x32x16_f16(a, b, c, 0, 0, 0); }
; template <bool GATHER>
; DI void gemm256_main(const h16* __restrict__ A, int lda, const int* __restrict__ idx, int m0,
;                      const h16* __restrict__ B, int ldb, int n0, int K, h16* lds, f16v (&acc)[4][2]) {
;     ...
;   for (int kt = 0; kt < nk; ++kt) {
;     const h16* As = lds + (kt & 1) * (512 * LDH);
;     const h16* Bs = As + 256 * LDH;
;     h16* Wn = lds + ((kt & 1) ^ 1) * (512 * LDH);
;     if (kt + 1 < nk) {
; #pragma unroll
;       for (int i = 0; i < 4; ++i) { *(u4v*)&Wn[lr * LDH + lc + 8 * i] = ra[i]; *(u4v*)&Wn[(256 + lr) * LDH + lc + 8 * i] = rb[i]; }
;     }
;     if (kt + 2 < nk) {
; #pragma unroll
;       for (int i = 0; i < 4; ++i) { ra[i] = *(const u4v*)(AP_ + 8 * i); rb[i] = *(const u4v*)(BP_ + 8 * i); }
;       ao += 64; bo += 64;
;     }
; #pragma unroll
;     for (int ks = 0; ks < 4; ++ks) {
;       h8v af[4], bf[2];
; #pragma unroll
;       for (int i = 0; i < 4; ++i) af[i] = *(const h8v*)&As[(wm * 128 + i * 32 + (lane & 31)) * LDH + ks * 16 + 8 * (lane >> 5)];
; #pragma unroll
;       for (int j = 0; j < 2; ++j) bf[j] = *(const h8v*)&Bs[(wn * 64 + j * 32 + (lane & 31)) * LDH + ks * 16 + 8 * (lane >> 5)];
; #pragma unroll
;       for (int i = 0; i < 4; ++i)
; #pragma unroll
;         for (int j = 0; j < 2; ++j) acc[i][j] = mfma32(bf[j], af[i], acc[i][j]);
;     }
;     __syncthreads();
;   }
	s_waitcnt vmcnt(0)
	ds_write_b128 v177, v[158:161]
	ds_write_b128 v215, v[150:153]
	ds_write_b128 v177, v[154:157] offset:16
	ds_write_b128 v215, v[142:145] offset:16
	ds_write_b128 v177, v[146:149] offset:32
	ds_write_b128 v215, v[134:137] offset:32
	ds_write_b128 v177, v[138:141] offset:48
	ds_write_b128 v215, v[130:133] offset:48
	v_lshl_add_u64 v[138:139], v[162:163], 1, s[16:17]
	global_load_dwordx4 v[130:133], v[138:139], off offset:48
	global_load_dwordx4 v[134:137], v[138:139], off offset:32
	global_load_dwordx4 v[142:145], v[138:139], off offset:16
	global_load_dwordx4 v[150:153], v[138:139], off
	s_nop 0
	global_load_dwordx4 v[138:141], v[174:175], off offset:1584
	global_load_dwordx4 v[146:149], v[174:175], off offset:1568
	global_load_dwordx4 v[154:157], v[174:175], off offset:1552
	global_load_dwordx4 v[158:161], v[174:175], off offset:1536
	v_mfma_f32_32x32x16_f16 v[114:129], v[234:237], v[218:221], v[114:129]
	v_or_b32_e32 v162, 0x380, v176
	v_mfma_f32_32x32x16_f16 v[98:113], v[238:241], v[218:221], v[98:113]
	v_mfma_f32_32x32x16_f16 v[82:97], v[234:237], v[222:225], v[82:97]
	v_mfma_f32_32x32x16_f16 v[66:81], v[238:241], v[222:225], v[66:81]
	v_mfma_f32_32x32x16_f16 v[50:65], v[234:237], v[226:229], v[50:65]
	v_mfma_f32_32x32x16_f16 v[34:49], v[238:241], v[226:229], v[34:49]
	v_mfma_f32_32x32x16_f16 v[18:33], v[234:237], v[230:233], v[18:33]
	v_mfma_f32_32x32x16_f16 v[2:17], v[238:241], v[230:233], v[2:17]
	ds_read_b128 v[218:221], v171 offset:4608
	ds_read_b128 v[222:225], v171 offset:9216
	ds_read_b128 v[226:229], v171 offset:13824
	ds_read_b128 v[230:233], v1 offset:41472
	ds_read_b128 v[234:237], v171
	ds_read_b128 v[238:241], v171 offset:32
	ds_read_b128 v[242:245], v1 offset:36864
	ds_read_b128 v[246:249], v1 offset:36896
	s_waitcnt lgkmcnt(1)
	v_mfma_f32_32x32x16_f16 v[114:129], v[242:245], v[234:237], v[114:129]
	v_mfma_f32_32x32x16_f16 v[98:113], v[230:233], v[234:237], v[98:113]
	v_mfma_f32_32x32x16_f16 v[82:97], v[242:245], v[218:221], v[82:97]
	v_mfma_f32_32x32x16_f16 v[66:81], v[230:233], v[218:221], v[66:81]
	v_mfma_f32_32x32x16_f16 v[50:65], v[242:245], v[222:225], v[50:65]
	v_mfma_f32_32x32x16_f16 v[34:49], v[230:233], v[222:225], v[34:49]
	v_mfma_f32_32x32x16_f16 v[18:33], v[242:245], v[226:229], v[18:33]
	v_mfma_f32_32x32x16_f16 v[2:17], v[230:233], v[226:229], v[2:17]
	ds_read_b128 v[218:221], v171 offset:4640
	ds_read_b128 v[222:225], v171 offset:9248
	ds_read_b128 v[226:229], v171 offset:13856
	ds_read_b128 v[230:233], v1 offset:41504
	s_waitcnt lgkmcnt(4)
	v_mfma_f32_32x32x16_f16 v[114:129], v[246:249], v[238:241], v[114:129]
	s_waitcnt lgkmcnt(0)
	v_mfma_f32_32x32x16_f16 v[98:113], v[230:233], v[238:241], v[98:113]
	v_mfma_f32_32x32x16_f16 v[82:97], v[246:249], v[218:221], v[82:97]
	v_mfma_f32_32x32x16_f16 v[66:81], v[230:233], v[218:221], v[66:81]
	v_mfma_f32_32x32x16_f16 v[50:65], v[246:249], v[222:225], v[50:65]
	v_mfma_f32_32x32x16_f16 v[34:49], v[230:233], v[222:225], v[34:49]
	v_mfma_f32_32x32x16_f16 v[18:33], v[246:249], v[226:229], v[18:33]
	v_mfma_f32_32x32x16_f16 v[2:17], v[230:233], v[226:229], v[2:17]
	ds_read_b128 v[218:221], v171 offset:64
	ds_read_b128 v[222:225], v171 offset:4672
	ds_read_b128 v[226:229], v171 offset:9280
	ds_read_b128 v[230:233], v171 offset:13888
	ds_read_b128 v[234:237], v1 offset:36928
	ds_read_b128 v[238:241], v1 offset:41536
	s_waitcnt lgkmcnt(1)
	v_mfma_f32_32x32x16_f16 v[114:129], v[234:237], v[218:221], v[114:129]
	s_waitcnt lgkmcnt(0)
	v_mfma_f32_32x32x16_f16 v[98:113], v[238:241], v[218:221], v[98:113]
	v_mfma_f32_32x32x16_f16 v[82:97], v[234:237], v[222:225], v[82:97]
	v_mfma_f32_32x32x16_f16 v[66:81], v[238:241], v[222:225], v[66:81]
	v_mfma_f32_32x32x16_f16 v[50:65], v[234:237], v[226:229], v[50:65]
	v_mfma_f32_32x32x16_f16 v[34:49], v[238:241], v[226:229], v[34:49]
	v_mfma_f32_32x32x16_f16 v[18:33], v[234:237], v[230:233], v[18:33]
	v_mfma_f32_32x32x16_f16 v[2:17], v[238:241], v[230:233], v[2:17]
	ds_read_b128 v[218:221], v171 offset:96
	ds_read_b128 v[222:225], v171 offset:4704
	ds_read_b128 v[226:229], v171 offset:9312
	ds_read_b128 v[230:233], v171 offset:13920
	ds_read_b128 v[234:237], v1 offset:36960
	ds_read_b128 v[238:241], v1 offset:41568
	s_waitcnt lgkmcnt(0)
	s_barrier
; DI f16v mfma32(h8v a, h8v b, f16v c) { return __builtin_amdgcn_mfma_f32_32x32x16_f16(a, b, c, 0, 0, 0); }
; template <bool GATHER>
; DI void gemm256_main(const h16* __restrict__ A, int lda, const int* __restrict__ idx, int m0,
;                      const h16* __restrict__ B, int ldb, int n0, int K, h16* lds, f16v (&acc)[4][2]) {
;     ...
;   for (int kt = 0; kt < nk; ++kt) {
;     const h16* As = lds + (kt & 1) * (512 * LDH);
;     const h16* Bs = As + 256 * LDH;
;     h16* Wn = lds + ((kt & 1) ^ 1) * (512 * LDH);
;     if (kt + 1 < nk) {
; #pragma unroll
;       for (int i = 0; i < 4; ++i) { *(u4v*)&Wn[lr * LDH + lc + 8 * i] = ra[i]; *(u4v*)&Wn[(256 + lr) * LDH + lc + 8 * i] = rb[i]; }
;     }
;     if (kt + 2 < nk) {
; #pragma unroll
;       for (int i = 0; i < 4; ++i) { ra[i] = *(const u4v*)(AP_ + 8 * i); rb[i] = *(const u4v*)(BP_ + 8 * i); }
;       ao += 64; bo += 64;
;     }
; #pragma unroll
;     for (int ks = 0; ks < 4; ++ks) {
;       h8v af[4], bf[2];
; #pragma unroll
;       for (int i = 0; i < 4; ++i) af[i] = *(const h8v*)&As[(wm * 128 + i * 32 + (lane & 31)) * LDH + ks * 16 + 8 * (lane >> 5)];
; #pragma unroll
;       for (int j = 0; j < 2; ++j) bf[j] = *(const h8v*)&Bs[(wn * 64 + j * 32 + (lane & 31)) * LDH + ks * 16 + 8 * (lane >> 5)];
; #pragma unroll
;       for (int i = 0; i < 4; ++i)
; #pragma unroll
;         for (int j = 0; j < 2; ++j) acc[i][j] = mfma32(bf[j], af[i], acc[i][j]);
;     }
;     __syncthreads();
;   }
	s_waitcnt vmcnt(0)
	ds_write_b128 v216, v[158:161]
	ds_write_b128 v216, v[150:153] offset:36864
	ds_write_b128 v216, v[154:157] offset:16
	ds_write_b128 v216, v[142:145] offset:36880
	ds_write_b128 v216, v[146:149] offset:32
	ds_write_b128 v216, v[134:137] offset:36896
	ds_write_b128 v216, v[138:141] offset:48
	ds_write_b128 v216, v[130:133] offset:36912
	v_lshl_add_u64 v[138:139], v[164:165], 1, s[16:17]
	global_load_dwordx4 v[130:133], v[138:139], off offset:48
	global_load_dwordx4 v[134:137], v[138:139], off offset:32
	global_load_dwordx4 v[142:145], v[138:139], off offset:16
	global_load_dwordx4 v[150:153], v[138:139], off
	s_nop 0
	global_load_dwordx4 v[138:141], v[174:175], off offset:1712
	global_load_dwordx4 v[146:149], v[174:175], off offset:1696
	global_load_dwordx4 v[154:157], v[174:175], off offset:1680
	global_load_dwordx4 v[158:161], v[174:175], off offset:1664
	v_mfma_f32_32x32x16_f16 v[114:129], v[234:237], v[218:221], v[114:129]
	v_or_b32_e32 v164, 0x3c0, v176
	v_mfma_f32_32x32x16_f16 v[98:113], v[238:241], v[218:221], v[98:113]
	v_mfma_f32_32x32x16_f16 v[82:97], v[234:237], v[222:225], v[82:97]
	v_mfma_f32_32x32x16_f16 v[66:81], v[238:241], v[222:225], v[66:81]
	v_mfma_f32_32x32x16_f16 v[50:65], v[234:237], v[226:229], v[50:65]
	v_mfma_f32_32x32x16_f16 v[34:49], v[238:241], v[226:229], v[34:49]
	v_mfma_f32_32x32x16_f16 v[18:33], v[234:237], v[230:233], v[18:33]
	v_mfma_f32_32x32x16_f16 v[2:17], v[238:241], v[230:233], v[2:17]
	ds_read_b128 v[218:221], v179 offset:4608
	ds_read_b128 v[222:225], v179 offset:9216
	ds_read_b128 v[226:229], v179 offset:13824
	ds_read_b128 v[230:233], v178 offset:4608
	ds_read_b128 v[234:237], v179
	ds_read_b128 v[238:241], v179 offset:32
	ds_read_b128 v[242:245], v178
	ds_read_b128 v[246:249], v178 offset:32
	s_waitcnt lgkmcnt(1)
	v_mfma_f32_32x32x16_f16 v[114:129], v[242:245], v[234:237], v[114:129]
	v_mfma_f32_32x32x16_f16 v[98:113], v[230:233], v[234:237], v[98:113]
	v_mfma_f32_32x32x16_f16 v[82:97], v[242:245], v[218:221], v[82:97]
	v_mfma_f32_32x32x16_f16 v[66:81], v[230:233], v[218:221], v[66:81]
	v_mfma_f32_32x32x16_f16 v[50:65], v[242:245], v[222:225], v[50:65]
	v_mfma_f32_32x32x16_f16 v[34:49], v[230:233], v[222:225], v[34:49]
	v_mfma_f32_32x32x16_f16 v[18:33], v[242:245], v[226:229], v[18:33]
	v_mfma_f32_32x32x16_f16 v[2:17], v[230:233], v[226:229], v[2:17]
	ds_read_b128 v[218:221], v179 offset:4640
	ds_read_b128 v[222:225], v179 offset:9248
	ds_read_b128 v[226:229], v179 offset:13856
	ds_read_b128 v[230:233], v178 offset:4640
	s_waitcnt lgkmcnt(4)
	v_mfma_f32_32x32x16_f16 v[114:129], v[246:249], v[238:241], v[114:129]
	s_waitcnt lgkmcnt(0)
	v_mfma_f32_32x32x16_f16 v[98:113], v[230:233], v[238:241], v[98:113]
	v_mfma_f32_32x32x16_f16 v[82:97], v[246:249], v[218:221], v[82:97]
	v_mfma_f32_32x32x16_f16 v[66:81], v[230:233], v[218:221], v[66:81]
	v_mfma_f32_32x32x16_f16 v[50:65], v[246:249], v[222:225], v[50:65]
	v_mfma_f32_32x32x16_f16 v[34:49], v[230:233], v[222:225], v[34:49]
	v_mfma_f32_32x32x16_f16 v[18:33], v[246:249], v[226:229], v[18:33]
	v_mfma_f32_32x32x16_f16 v[2:17], v[230:233], v[226:229], v[2:17]
	ds_read_b128 v[218:221], v179 offset:64
	ds_read_b128 v[222:225], v179 offset:4672
	ds_read_b128 v[226:229], v179 offset:9280
	ds_read_b128 v[230:233], v179 offset:13888
	ds_read_b128 v[234:237], v178 offset:64
	ds_read_b128 v[238:241], v178 offset:4672
	s_waitcnt lgkmcnt(1)
	v_mfma_f32_32x32x16_f16 v[114:129], v[234:237], v[218:221], v[114:129]
	s_waitcnt lgkmcnt(0)
	v_mfma_f32_32x32x16_f16 v[98:113], v[238:241], v[218:221], v[98:113]
	v_mfma_f32_32x32x16_f16 v[82:97], v[234:237], v[222:225], v[82:97]
	v_mfma_f32_32x32x16_f16 v[66:81], v[238:241], v[222:225], v[66:81]
	v_mfma_f32_32x32x16_f16 v[50:65], v[234:237], v[226:229], v[50:65]
	v_mfma_f32_32x32x16_f16 v[34:49], v[238:241], v[226:229], v[34:49]
	v_mfma_f32_32x32x16_f16 v[18:33], v[234:237], v[230:233], v[18:33]
	v_mfma_f32_32x32x16_f16 v[2:17], v[238:241], v[230:233], v[2:17]
	ds_read_b128 v[218:221], v179 offset:96
	ds_read_b128 v[222:225], v179 offset:4704
	ds_read_b128 v[226:229], v179 offset:9312
	ds_read_b128 v[230:233], v179 offset:13920
	ds_read_b128 v[234:237], v178 offset:96
	ds_read_b128 v[238:241], v178 offset:4704
	s_waitcnt lgkmcnt(0)
	s_barrier
; DI f16v mfma32(h8v a, h8v b, f16v c) { return __builtin_amdgcn_mfma_f32_32x32x16_f16(a, b, c, 0, 0, 0); }
; template <bool GATHER>
; DI void gemm256_main(const h16* __restrict__ A, int lda, const int* __restrict__ idx, int m0,
;                      const h16* __restrict__ B, int ldb, int n0, int K, h16* lds, f16v (&acc)[4][2]) {
;     ...
;   for (int kt = 0; kt < nk; ++kt) {
;     const h16* As = lds + (kt & 1) * (512 * LDH);
;     const h16* Bs = As + 256 * LDH;
;     h16* Wn = lds + ((kt & 1) ^ 1) * (512 * LDH);
;     if (kt + 1 < nk) {
; #pragma unroll
;       for (int i = 0; i < 4; ++i) { *(u4v*)&Wn[lr * LDH + lc + 8 * i] = ra[i]; *(u4v*)&Wn[(256 + lr) * LDH + lc + 8 * i] = rb[i]; }
;     }
;     if (kt + 2 < nk) {
; #pragma unroll
;       for (int i = 0; i < 4; ++i) { ra[i] = *(const u4v*)(AP_ + 8 * i); rb[i] = *(const u4v*)(BP_ + 8 * i); }
;       ao += 64; bo += 64;
;     }
; #pragma unroll
;     for (int ks = 0; ks < 4; ++ks) {
;       h8v af[4], bf[2];
; #pragma unroll
;       for (int i = 0; i < 4; ++i) af[i] = *(const h8v*)&As[(wm * 128 + i * 32 + (lane & 31)) * LDH + ks * 16 + 8 * (lane >> 5)];
; #pragma unroll
;       for (int j = 0; j < 2; ++j) bf[j] = *(const h8v*)&Bs[(wn * 64 + j * 32 + (lane & 31)) * LDH + ks * 16 + 8 * (lane >> 5)];
; #pragma unroll
;       for (int i = 0; i < 4; ++i)
; #pragma unroll
;         for (int j = 0; j < 2; ++j) acc[i][j] = mfma32(bf[j], af[i], acc[i][j]);
;     }
;     __syncthreads();
;   }
	s_waitcnt vmcnt(0)
	ds_write_b128 v177, v[158:161]
	ds_write_b128 v215, v[150:153]
	ds_write_b128 v177, v[154:157] offset:16
	ds_write_b128 v215, v[142:145] offset:16
	ds_write_b128 v177, v[146:149] offset:32
	ds_write_b128 v215, v[134:137] offset:32
	ds_write_b128 v177, v[138:141] offset:48
	ds_write_b128 v215, v[130:133] offset:48
	v_lshl_add_u64 v[138:139], v[162:163], 1, s[16:17]
	global_load_dwordx4 v[130:133], v[138:139], off offset:48
	global_load_dwordx4 v[134:137], v[138:139], off offset:32
	global_load_dwordx4 v[142:145], v[138:139], off offset:16
	global_load_dwordx4 v[150:153], v[138:139], off
	s_nop 0
	global_load_dwordx4 v[138:141], v[174:175], off offset:1840
	global_load_dwordx4 v[146:149], v[174:175], off offset:1824
	global_load_dwordx4 v[154:157], v[174:175], off offset:1808
	global_load_dwordx4 v[158:161], v[174:175], off offset:1792
	v_mfma_f32_32x32x16_f16 v[114:129], v[234:237], v[218:221], v[114:129]
	v_mfma_f32_32x32x16_f16 v[98:113], v[238:241], v[218:221], v[98:113]
	v_mfma_f32_32x32x16_f16 v[82:97], v[234:237], v[222:225], v[82:97]
	v_mfma_f32_32x32x16_f16 v[66:81], v[238:241], v[222:225], v[66:81]
	v_mfma_f32_32x32x16_f16 v[50:65], v[234:237], v[226:229], v[50:65]
	v_mfma_f32_32x32x16_f16 v[34:49], v[238:241], v[226:229], v[34:49]
	v_mfma_f32_32x32x16_f16 v[18:33], v[234:237], v[230:233], v[18:33]
	v_mfma_f32_32x32x16_f16 v[2:17], v[238:241], v[230:233], v[2:17]
	ds_read_b128 v[218:221], v171 offset:4608
	ds_read_b128 v[222:225], v171 offset:9216
	ds_read_b128 v[226:229], v171 offset:13824
	ds_read_b128 v[230:233], v1 offset:41472
	ds_read_b128 v[234:237], v171
	ds_read_b128 v[238:241], v171 offset:32
	ds_read_b128 v[242:245], v1 offset:36864
	ds_read_b128 v[246:249], v1 offset:36896
	s_waitcnt lgkmcnt(1)
	v_mfma_f32_32x32x16_f16 v[114:129], v[242:245], v[234:237], v[114:129]
	v_mfma_f32_32x32x16_f16 v[98:113], v[230:233], v[234:237], v[98:113]
	v_mfma_f32_32x32x16_f16 v[82:97], v[242:245], v[218:221], v[82:97]
	v_mfma_f32_32x32x16_f16 v[66:81], v[230:233], v[218:221], v[66:81]
	v_mfma_f32_32x32x16_f16 v[50:65], v[242:245], v[222:225], v[50:65]
	v_mfma_f32_32x32x16_f16 v[34:49], v[230:233], v[222:225], v[34:49]
	v_mfma_f32_32x32x16_f16 v[18:33], v[242:245], v[226:229], v[18:33]
	v_mfma_f32_32x32x16_f16 v[2:17], v[230:233], v[226:229], v[2:17]
	ds_read_b128 v[218:221], v171 offset:4640
	ds_read_b128 v[222:225], v171 offset:9248
	ds_read_b128 v[226:229], v171 offset:13856
	ds_read_b128 v[230:233], v1 offset:41504
	s_waitcnt lgkmcnt(4)
	v_mfma_f32_32x32x16_f16 v[114:129], v[246:249], v[238:241], v[114:129]
	s_waitcnt lgkmcnt(0)
	v_mfma_f32_32x32x16_f16 v[98:113], v[230:233], v[238:241], v[98:113]
	v_mfma_f32_32x32x16_f16 v[82:97], v[246:249], v[218:221], v[82:97]
	v_mfma_f32_32x32x16_f16 v[66:81], v[230:233], v[218:221], v[66:81]
	v_mfma_f32_32x32x16_f16 v[50:65], v[246:249], v[222:225], v[50:65]
	v_mfma_f32_32x32x16_f16 v[34:49], v[230:233], v[222:225], v[34:49]
	v_mfma_f32_32x32x16_f16 v[18:33], v[246:249], v[226:229], v[18:33]
	v_mfma_f32_32x32x16_f16 v[2:17], v[230:233], v[226:229], v[2:17]
	ds_read_b128 v[218:221], v171 offset:64
	ds_read_b128 v[222:225], v171 offset:4672
	ds_read_b128 v[226:229], v171 offset:9280
	ds_read_b128 v[230:233], v171 offset:13888
	ds_read_b128 v[234:237], v1 offset:36928
	ds_read_b128 v[238:241], v1 offset:41536
	s_waitcnt lgkmcnt(1)
	v_mfma_f32_32x32x16_f16 v[114:129], v[234:237], v[218:221], v[114:129]
	s_waitcnt lgkmcnt(0)
	v_mfma_f32_32x32x16_f16 v[98:113], v[238:241], v[218:221], v[98:113]
	v_mfma_f32_32x32x16_f16 v[82:97], v[234:237], v[222:225], v[82:97]
	v_mfma_f32_32x32x16_f16 v[66:81], v[238:241], v[222:225], v[66:81]
	v_mfma_f32_32x32x16_f16 v[50:65], v[234:237], v[226:229], v[50:65]
	v_mfma_f32_32x32x16_f16 v[34:49], v[238:241], v[226:229], v[34:49]
	v_mfma_f32_32x32x16_f16 v[18:33], v[234:237], v[230:233], v[18:33]
	v_mfma_f32_32x32x16_f16 v[2:17], v[238:241], v[230:233], v[2:17]
	ds_read_b128 v[218:221], v171 offset:96
	ds_read_b128 v[222:225], v171 offset:4704
	ds_read_b128 v[226:229], v171 offset:9312
	ds_read_b128 v[230:233], v171 offset:13920
	ds_read_b128 v[234:237], v1 offset:36960
	ds_read_b128 v[238:241], v1 offset:41568
	s_waitcnt lgkmcnt(0)
	s_barrier
	s_waitcnt vmcnt(0)
	ds_write_b128 v216, v[158:161]
	ds_write_b128 v216, v[150:153] offset:36864
	ds_write_b128 v216, v[154:157] offset:16
	ds_write_b128 v216, v[142:145] offset:36880
	ds_write_b128 v216, v[146:149] offset:32
	ds_write_b128 v216, v[134:137] offset:36896
	ds_write_b128 v216, v[138:141] offset:48
	ds_write_b128 v216, v[130:133] offset:36912
	v_lshl_add_u64 v[138:139], v[164:165], 1, s[16:17]
	global_load_dwordx4 v[130:133], v[138:139], off offset:48
	global_load_dwordx4 v[134:137], v[138:139], off offset:32
	global_load_dwordx4 v[142:145], v[138:139], off offset:16
	global_load_dwordx4 v[150:153], v[138:139], off
	s_nop 0
	global_load_dwordx4 v[138:141], v[174:175], off offset:1968
	global_load_dwordx4 v[146:149], v[174:175], off offset:1952
	global_load_dwordx4 v[154:157], v[174:175], off offset:1936
	global_load_dwordx4 v[158:161], v[174:175], off offset:1920
	v_mfma_f32_32x32x16_f16 v[114:129], v[234:237], v[218:221], v[114:129]
	v_mfma_f32_32x32x16_f16 v[98:113], v[238:241], v[218:221], v[98:113]
	v_mfma_f32_32x32x16_f16 v[82:97], v[234:237], v[222:225], v[82:97]
	v_mfma_f32_32x32x16_f16 v[66:81], v[238:241], v[222:225], v[66:81]
	v_mfma_f32_32x32x16_f16 v[50:65], v[234:237], v[226:229], v[50:65]
	v_mfma_f32_32x32x16_f16 v[34:49], v[238:241], v[226:229], v[34:49]
	v_mfma_f32_32x32x16_f16 v[18:33], v[234:237], v[230:233], v[18:33]
	v_mfma_f32_32x32x16_f16 v[2:17], v[238:241], v[230:233], v[2:17]
	ds_read_b128 v[162:165], v179 offset:4608
	ds_read_b128 v[216:219], v179 offset:9216
	ds_read_b128 v[220:223], v179 offset:13824
	ds_read_b128 v[224:227], v178 offset:4608
	ds_read_b128 v[228:231], v179
	ds_read_b128 v[232:235], v179 offset:32
	ds_read_b128 v[236:239], v178
	ds_read_b128 v[240:243], v178 offset:32
	s_waitcnt lgkmcnt(1)
; DI f16v mfma32(h8v a, h8v b, f16v c) { return __builtin_amdgcn_mfma_f32_32x32x16_f16(a, b, c, 0, 0, 0); }
; template <bool GATHER>
; DI void gemm256_main(const h16* __restrict__ A, int lda, const int* __restrict__ idx, int m0,
;                      const h16* __restrict__ B, int ldb, int n0, int K, h16* lds, f16v (&acc)[4][2]) {
;     ...
;   for (int kt = 0; kt < nk; ++kt) {
;     const h16* As = lds + (kt & 1) * (512 * LDH);
;     const h16* Bs = As + 256 * LDH;
;     h16* Wn = lds + ((kt & 1) ^ 1) * (512 * LDH);
;     if (kt + 1 < nk) {
; #pragma unroll
;       for (int i = 0; i < 4; ++i) { *(u4v*)&Wn[lr * LDH + lc + 8 * i] = ra[i]; *(u4v*)&Wn[(256 + lr) * LDH + lc + 8 * i] = rb[i]; }
;     }
;     if (kt + 2 < nk) {
; #pragma unroll
;       for (int i = 0; i < 4; ++i) { ra[i] = *(const u4v*)(AP_ + 8 * i); rb[i] = *(const u4v*)(BP_ + 8 * i); }
;       ao += 64; bo += 64;
;     }
; #pragma unroll
;     for (int ks = 0; ks < 4; ++ks) {
;       h8v af[4], bf[2];
; #pragma unroll
;       for (int i = 0; i < 4; ++i) af[i] = *(const h8v*)&As[(wm * 128 + i * 32 + (lane & 31)) * LDH + ks * 16 + 8 * (lane >> 5)];
; #pragma unroll
;       for (int j = 0; j < 2; ++j) bf[j] = *(const h8v*)&Bs[(wn * 64 + j * 32 + (lane & 31)) * LDH + ks * 16 + 8 * (lane >> 5)];
; #pragma unroll
;       for (int i = 0; i < 4; ++i)
; #pragma unroll
;         for (int j = 0; j < 2; ++j) acc[i][j] = mfma32(bf[j], af[i], acc[i][j]);
;     }
;     __syncthreads();
;   }
	v_mfma_f32_32x32x16_f16 v[114:129], v[236:239], v[228:231], v[114:129]
	v_mfma_f32_32x32x16_f16 v[98:113], v[224:227], v[228:231], v[98:113]
	v_mfma_f32_32x32x16_f16 v[82:97], v[236:239], v[162:165], v[82:97]
	v_mfma_f32_32x32x16_f16 v[66:81], v[224:227], v[162:165], v[66:81]
	v_mfma_f32_32x32x16_f16 v[50:65], v[236:239], v[216:219], v[50:65]
	v_mfma_f32_32x32x16_f16 v[34:49], v[224:227], v[216:219], v[34:49]
	v_mfma_f32_32x32x16_f16 v[18:33], v[236:239], v[220:223], v[18:33]
	v_mfma_f32_32x32x16_f16 v[2:17], v[224:227], v[220:223], v[2:17]
	ds_read_b128 v[162:165], v179 offset:4640
	ds_read_b128 v[216:219], v179 offset:9248
	ds_read_b128 v[220:223], v179 offset:13856
	ds_read_b128 v[224:227], v178 offset:4640
	s_waitcnt lgkmcnt(4)
	v_mfma_f32_32x32x16_f16 v[114:129], v[240:243], v[232:235], v[114:129]
	s_waitcnt lgkmcnt(0)
	v_mfma_f32_32x32x16_f16 v[98:113], v[224:227], v[232:235], v[98:113]
	v_mfma_f32_32x32x16_f16 v[82:97], v[240:243], v[162:165], v[82:97]
	v_mfma_f32_32x32x16_f16 v[66:81], v[224:227], v[162:165], v[66:81]
	v_mfma_f32_32x32x16_f16 v[50:65], v[240:243], v[216:219], v[50:65]
	v_mfma_f32_32x32x16_f16 v[34:49], v[224:227], v[216:219], v[34:49]
	v_mfma_f32_32x32x16_f16 v[18:33], v[240:243], v[220:223], v[18:33]
	v_mfma_f32_32x32x16_f16 v[2:17], v[224:227], v[220:223], v[2:17]
	ds_read_b128 v[162:165], v179 offset:64
	ds_read_b128 v[216:219], v179 offset:4672
	ds_read_b128 v[220:223], v179 offset:9280
	ds_read_b128 v[224:227], v179 offset:13888
	ds_read_b128 v[228:231], v178 offset:64
	ds_read_b128 v[232:235], v178 offset:4672
	s_waitcnt lgkmcnt(1)
	v_mfma_f32_32x32x16_f16 v[114:129], v[228:231], v[162:165], v[114:129]
	s_waitcnt lgkmcnt(0)
	v_mfma_f32_32x32x16_f16 v[98:113], v[232:235], v[162:165], v[98:113]
	v_mfma_f32_32x32x16_f16 v[82:97], v[228:231], v[216:219], v[82:97]
	v_mfma_f32_32x32x16_f16 v[66:81], v[232:235], v[216:219], v[66:81]
	v_mfma_f32_32x32x16_f16 v[50:65], v[228:231], v[220:223], v[50:65]
	v_mfma_f32_32x32x16_f16 v[34:49], v[232:235], v[220:223], v[34:49]
	v_mfma_f32_32x32x16_f16 v[18:33], v[228:231], v[224:227], v[18:33]
	v_mfma_f32_32x32x16_f16 v[2:17], v[232:235], v[224:227], v[2:17]
	ds_read_b128 v[162:165], v179 offset:96
	ds_read_b128 v[216:219], v179 offset:4704
	ds_read_b128 v[220:223], v179 offset:9312
	ds_read_b128 v[224:227], v179 offset:13920
	ds_read_b128 v[228:231], v178 offset:96
	ds_read_b128 v[232:235], v178 offset:4704
	s_waitcnt lgkmcnt(0)
	s_barrier
	s_waitcnt vmcnt(0)
	ds_write_b128 v177, v[158:161]
	ds_write_b128 v215, v[150:153]
	ds_write_b128 v177, v[154:157] offset:16
	ds_write_b128 v215, v[142:145] offset:16
	ds_write_b128 v177, v[146:149] offset:32
	ds_write_b128 v215, v[134:137] offset:32
	ds_write_b128 v177, v[138:141] offset:48
	ds_write_b128 v215, v[130:133] offset:48
	ds_read_b128 v[130:133], v171 offset:4608
	ds_read_b128 v[134:137], v171 offset:9216
	ds_read_b128 v[138:141], v171 offset:13824
	ds_read_b128 v[142:145], v1 offset:41472
	ds_read_b128 v[146:149], v171
	ds_read_b128 v[150:153], v171 offset:32
	ds_read_b128 v[154:157], v1 offset:36864
	ds_read_b128 v[158:161], v1 offset:36896
	v_mfma_f32_32x32x16_f16 v[114:129], v[228:231], v[162:165], v[114:129]
	v_mfma_f32_32x32x16_f16 v[98:113], v[232:235], v[162:165], v[98:113]
	v_mfma_f32_32x32x16_f16 v[82:97], v[228:231], v[216:219], v[82:97]
	v_mfma_f32_32x32x16_f16 v[66:81], v[232:235], v[216:219], v[66:81]
	v_mfma_f32_32x32x16_f16 v[50:65], v[228:231], v[220:223], v[50:65]
	v_mfma_f32_32x32x16_f16 v[34:49], v[232:235], v[220:223], v[34:49]
	v_mfma_f32_32x32x16_f16 v[18:33], v[228:231], v[224:227], v[18:33]
	v_mfma_f32_32x32x16_f16 v[2:17], v[232:235], v[224:227], v[2:17]
	s_waitcnt lgkmcnt(1)
	v_mfma_f32_32x32x16_f16 v[114:129], v[154:157], v[146:149], v[114:129]
	v_mfma_f32_32x32x16_f16 v[98:113], v[142:145], v[146:149], v[98:113]
	v_mfma_f32_32x32x16_f16 v[82:97], v[154:157], v[130:133], v[82:97]
	v_mfma_f32_32x32x16_f16 v[66:81], v[142:145], v[130:133], v[66:81]
	v_mfma_f32_32x32x16_f16 v[50:65], v[154:157], v[134:137], v[50:65]
	v_mfma_f32_32x32x16_f16 v[34:49], v[142:145], v[134:137], v[34:49]
	v_mfma_f32_32x32x16_f16 v[18:33], v[154:157], v[138:141], v[18:33]
	v_mfma_f32_32x32x16_f16 v[2:17], v[142:145], v[138:141], v[2:17]
	ds_read_b128 v[130:133], v171 offset:4640
	ds_read_b128 v[134:137], v171 offset:9248
	ds_read_b128 v[138:141], v171 offset:13856
	ds_read_b128 v[142:145], v1 offset:41504
	s_waitcnt lgkmcnt(4)
	v_mfma_f32_32x32x16_f16 v[114:129], v[158:161], v[150:153], v[114:129]
	s_waitcnt lgkmcnt(0)
	v_mfma_f32_32x32x16_f16 v[98:113], v[142:145], v[150:153], v[98:113]
	v_mfma_f32_32x32x16_f16 v[82:97], v[158:161], v[130:133], v[82:97]
	v_mfma_f32_32x32x16_f16 v[66:81], v[142:145], v[130:133], v[66:81]
	v_mfma_f32_32x32x16_f16 v[50:65], v[158:161], v[134:137], v[50:65]
	v_mfma_f32_32x32x16_f16 v[34:49], v[142:145], v[134:137], v[34:49]
	v_mfma_f32_32x32x16_f16 v[18:33], v[158:161], v[138:141], v[18:33]
	v_mfma_f32_32x32x16_f16 v[2:17], v[142:145], v[138:141], v[2:17]
	ds_read_b128 v[130:133], v171 offset:64
	ds_read_b128 v[134:137], v171 offset:4672
	ds_read_b128 v[138:141], v171 offset:9280
	ds_read_b128 v[142:145], v171 offset:13888
	ds_read_b128 v[146:149], v1 offset:36928
	ds_read_b128 v[150:153], v1 offset:41536
	s_waitcnt lgkmcnt(1)
	v_mfma_f32_32x32x16_f16 v[114:129], v[146:149], v[130:133], v[114:129]
	s_waitcnt lgkmcnt(0)
	v_mfma_f32_32x32x16_f16 v[98:113], v[150:153], v[130:133], v[98:113]
	v_mfma_f32_32x32x16_f16 v[82:97], v[146:149], v[134:137], v[82:97]
	v_mfma_f32_32x32x16_f16 v[66:81], v[150:153], v[134:137], v[66:81]
	v_mfma_f32_32x32x16_f16 v[50:65], v[146:149], v[138:141], v[50:65]
	v_mfma_f32_32x32x16_f16 v[34:49], v[150:153], v[138:141], v[34:49]
	v_mfma_f32_32x32x16_f16 v[18:33], v[146:149], v[142:145], v[18:33]
	v_mfma_f32_32x32x16_f16 v[2:17], v[150:153], v[142:145], v[2:17]
	ds_read_b128 v[130:133], v171 offset:96
	ds_read_b128 v[134:137], v171 offset:4704
	ds_read_b128 v[138:141], v171 offset:9312
	ds_read_b128 v[142:145], v171 offset:13920
	ds_read_b128 v[146:149], v1 offset:36960
	ds_read_b128 v[150:153], v1 offset:41568
	s_waitcnt lgkmcnt(0)
	s_barrier
; DI float sigmoid_(float x) { return 1.f / (1.f + __expf(-x)); }
; DI f16v mfma32(h8v a, h8v b, f16v c) { return __builtin_amdgcn_mfma_f32_32x32x16_f16(a, b, c, 0, 0, 0); }
; template <bool GATHER>
; DI void gemm256_main(const h16* __restrict__ A, int lda, const int* __restrict__ idx, int m0,
;                      const h16* __restrict__ B, int ldb, int n0, int K, h16* lds, f16v (&acc)[4][2]) {
;     ...
; #pragma unroll
;     for (int ks = 0; ks < 4; ++ks) {
;       h8v af[4], bf[2];
; #pragma unroll
;       for (int i = 0; i < 4; ++i) af[i] = *(const h8v*)&As[(wm * 128 + i * 32 + (lane & 31)) * LDH + ks * 16 + 8 * (lane >> 5)];
; #pragma unroll
;       for (int j = 0; j < 2; ++j) bf[j] = *(const h8v*)&Bs[(wn * 64 + j * 32 + (lane & 31)) * LDH + ks * 16 + 8 * (lane >> 5)];
; #pragma unroll
;       for (int i = 0; i < 4; ++i)
; #pragma unroll
;         for (int j = 0; j < 2; ++j) acc[i][j] = mfma32(bf[j], af[i], acc[i][j]);
;     }
;     __syncthreads();
;   }
; DI void phase_gates(const Params& p, int bid, int nb, h16* lds) {
;     ...
;     gemm256_epilogue(acc, m0, n0, [&](int m, int n, f4v v0, f4v v1) {
;       f4v a, b;
; #pragma unroll
;       for (int i = 0; i < 4; ++i) { a[i] = sigmoid_(v0[i]); b[i] = sigmoid_(v1[i]); }
;       st_h4(&G[(size_t)m * 4096 + n], a); st_h4(&G[(size_t)m * 4096 + n + 32], b);
;     });
	v_mov_b32_e32 v1, v180
	v_mfma_f32_32x32x16_f16 v[114:129], v[146:149], v[130:133], v[114:129]
	v_mfma_f32_32x32x16_f16 v[98:113], v[150:153], v[130:133], v[98:113]
	v_mfma_f32_32x32x16_f16 v[82:97], v[146:149], v[134:137], v[82:97]
	v_mfma_f32_32x32x16_f16 v[66:81], v[150:153], v[134:137], v[66:81]
	v_mfma_f32_32x32x16_f16 v[50:65], v[146:149], v[138:141], v[50:65]
	v_mfma_f32_32x32x16_f16 v[34:49], v[150:153], v[138:141], v[34:49]
	v_mfma_f32_32x32x16_f16 v[18:33], v[146:149], v[142:145], v[18:33]
	v_mfma_f32_32x32x16_f16 v[2:17], v[150:153], v[142:145], v[2:17]
	ds_read_b128 v[130:133], v179 offset:4608
	ds_read_b128 v[134:137], v179 offset:9216
	ds_read_b128 v[138:141], v179 offset:13824
	ds_read_b128 v[142:145], v178 offset:4608
	ds_read_b128 v[146:149], v179
	ds_read_b128 v[150:153], v179 offset:32
	ds_read_b128 v[154:157], v178
	ds_read_b128 v[158:161], v178 offset:32
	s_waitcnt lgkmcnt(1)
	v_mfma_f32_32x32x16_f16 v[114:129], v[154:157], v[146:149], v[114:129]
	v_mfma_f32_32x32x16_f16 v[98:113], v[142:145], v[146:149], v[98:113]
	v_mfma_f32_32x32x16_f16 v[82:97], v[154:157], v[130:133], v[82:97]
	v_mfma_f32_32x32x16_f16 v[66:81], v[142:145], v[130:133], v[66:81]
	v_mfma_f32_32x32x16_f16 v[50:65], v[154:157], v[134:137], v[50:65]
	v_mfma_f32_32x32x16_f16 v[34:49], v[142:145], v[134:137], v[34:49]
	v_mfma_f32_32x32x16_f16 v[18:33], v[154:157], v[138:141], v[18:33]
	v_mfma_f32_32x32x16_f16 v[2:17], v[142:145], v[138:141], v[2:17]
	ds_read_b128 v[130:133], v179 offset:4640
	ds_read_b128 v[134:137], v179 offset:9248
	ds_read_b128 v[138:141], v179 offset:13856
	ds_read_b128 v[142:145], v178 offset:4640
	s_waitcnt lgkmcnt(4)
	v_mfma_f32_32x32x16_f16 v[114:129], v[158:161], v[150:153], v[114:129]
	s_waitcnt lgkmcnt(0)
	v_mfma_f32_32x32x16_f16 v[98:113], v[142:145], v[150:153], v[98:113]
	v_mfma_f32_32x32x16_f16 v[82:97], v[158:161], v[130:133], v[82:97]
	v_mfma_f32_32x32x16_f16 v[66:81], v[142:145], v[130:133], v[66:81]
	v_mfma_f32_32x32x16_f16 v[50:65], v[158:161], v[134:137], v[50:65]
	v_mfma_f32_32x32x16_f16 v[34:49], v[142:145], v[134:137], v[34:49]
	v_mfma_f32_32x32x16_f16 v[18:33], v[158:161], v[138:141], v[18:33]
	v_mfma_f32_32x32x16_f16 v[2:17], v[142:145], v[138:141], v[2:17]
	ds_read_b128 v[130:133], v179 offset:64
	ds_read_b128 v[134:137], v179 offset:4672
	ds_read_b128 v[138:141], v179 offset:9280
	ds_read_b128 v[142:145], v179 offset:13888
	ds_read_b128 v[146:149], v178 offset:64
	ds_read_b128 v[150:153], v178 offset:4672
	s_waitcnt lgkmcnt(1)
	v_mfma_f32_32x32x16_f16 v[114:129], v[146:149], v[130:133], v[114:129]
	s_waitcnt lgkmcnt(0)
	v_mfma_f32_32x32x16_f16 v[98:113], v[150:153], v[130:133], v[98:113]
	v_mfma_f32_32x32x16_f16 v[82:97], v[146:149], v[134:137], v[82:97]
	v_mfma_f32_32x32x16_f16 v[66:81], v[150:153], v[134:137], v[66:81]
	v_mfma_f32_32x32x16_f16 v[50:65], v[146:149], v[138:141], v[50:65]
	v_mfma_f32_32x32x16_f16 v[34:49], v[150:153], v[138:141], v[34:49]
	v_mfma_f32_32x32x16_f16 v[18:33], v[146:149], v[142:145], v[18:33]
	v_mfma_f32_32x32x16_f16 v[2:17], v[150:153], v[142:145], v[2:17]
	ds_read_b128 v[130:133], v179 offset:96
	ds_read_b128 v[134:137], v179 offset:4704
	ds_read_b128 v[138:141], v179 offset:9312
	ds_read_b128 v[142:145], v179 offset:13920
	ds_read_b128 v[146:149], v178 offset:96
	ds_read_b128 v[150:153], v178 offset:4704
	s_waitcnt lgkmcnt(0)
	s_barrier
	v_mfma_f32_32x32x16_f16 v[114:129], v[146:149], v[130:133], v[114:129]
	v_mfma_f32_32x32x16_f16 v[98:113], v[150:153], v[130:133], v[98:113]
	v_mfma_f32_32x32x16_f16 v[82:97], v[146:149], v[134:137], v[82:97]
	v_mfma_f32_32x32x16_f16 v[66:81], v[150:153], v[134:137], v[66:81]
	v_mfma_f32_32x32x16_f16 v[50:65], v[146:149], v[138:141], v[50:65]
	v_mfma_f32_32x32x16_f16 v[34:49], v[150:153], v[138:141], v[34:49]
	v_mfma_f32_32x32x16_f16 v[18:33], v[146:149], v[142:145], v[18:33]
	v_mfma_f32_32x32x16_f16 v[2:17], v[150:153], v[142:145], v[2:17]
	s_nop 15
	s_cselect_b32 s60, 1, 0
	s_barrier
	v_readfirstlane_b32 s66, v180
	s_mov_b32 s69, s5
	s_mov_b32 s65, s6
	s_lshr_b32 s66, s66, 6
	s_and_b32 s67, s66, 3
	s_lshr_b32 s68, s66, 2
	s_lshl_b32 s70, s67, 6
	s_add_i32 s70, s70, s69
	s_lshl_b32 s71, s68, 7
	s_add_i32 s71, s71, s65
	s_mul_i32 s72, s66, 0x4800
	s_add_i32 s72, s72, 16
	s_mov_b32 s73, 0x2000
	v_and_b32_e32 v146, 63, v180
	v_and_b32_e32 v148, 31, v146
	v_lshrrev_b32_e32 v147, 5, v146
	v_mul_u32_u24_e32 v130, 0x90, v148
	v_lshl_add_u32 v130, v147, 3, v130
	v_add_u32_e32 v130, s72, v130
	v_lshrrev_b32_e32 v149, 3, v146
	v_and_b32_e32 v138, 7, v146
	v_mul_u32_u24_e32 v131, 0x90, v149
	v_lshl_add_u32 v131, v138, 4, v131
	v_add_u32_e32 v131, s72, v131
	v_add_u32_e32 v140, s71, v149
	v_lshl_add_u32 v138, v138, 3, s70
	v_mov_b64_e32 v[132:133], s[0:1]
	v_mad_u64_u32 v[132:133], s[74:75], v140, s73, v[132:133]
	v_lshlrev_b32_e32 v138, 1, v138
	v_mov_b32_e32 v139, v0
	v_lshl_add_u64 v[132:133], v[132:133], 0, v[138:139]
	s_mov_b32 s76, 0x10000
	s_mov_b32 s77, 0
	v_mul_f32_e32 v114, 0xbfb8aa3b, v114
	v_mul_f32_e32 v115, 0xbfb8aa3b, v115
	v_mul_f32_e32 v116, 0xbfb8aa3b, v116
	v_mul_f32_e32 v117, 0xbfb8aa3b, v117
	v_exp_f32_e32 v114, v114
	v_exp_f32_e32 v115, v115
	v_exp_f32_e32 v116, v116
	v_exp_f32_e32 v117, v117
	v_add_f32_e32 v114, 1.0, v114
	v_add_f32_e32 v115, 1.0, v115
	v_add_f32_e32 v116, 1.0, v116
	v_add_f32_e32 v117, 1.0, v117
	v_rcp_f32_e32 v114, v114
	v_rcp_f32_e32 v115, v115
	v_rcp_f32_e32 v116, v116
	v_rcp_f32_e32 v117, v117
	v_cvt_pk_f16_f32 v138, v114, v115
	v_cvt_pk_f16_f32 v139, v116, v117
	ds_write_b64 v130, v[138:139] offset:0
	v_mul_f32_e32 v98, 0xbfb8aa3b, v98
	v_mul_f32_e32 v99, 0xbfb8aa3b, v99
	v_mul_f32_e32 v100, 0xbfb8aa3b, v100
; DI int otid512() { int t = threadIdx.x; asm volatile("" : "+v"(t)); return t; }
; DI float sigmoid_(float x) { return 1.f / (1.f + __expf(-x)); }
; template <class Epi>
; DI void gemm256_epilogue(f16v (&acc)[4][2], int m0, int n0, Epi epi) {
;   const int tid = otid512(), lane = tid & 63, wv = tid >> 6, wm = wv >> 2, wn = wv & 3, h = lane >> 5;
; #pragma unroll
;   for (int i = 0; i < 4; ++i) {
;     const int m = m0 + wm * 128 + i * 32 + (lane & 31);
; #pragma unroll
;     for (int g = 0; g < 4; ++g) {
;       const int n = n0 + wn * 64 + 8 * g + 4 * h;
;       f4v v0 = {acc[i][0][4 * g], acc[i][0][4 * g + 1], acc[i][0][4 * g + 2], acc[i][0][4 * g + 3]};
;       f4v v1 = {acc[i][1][4 * g], acc[i][1][4 * g + 1], acc[i][1][4 * g + 2], acc[i][1][4 * g + 3]};
;       epi(m, n, v0, v1);
;     }
;   }
; }
; DI void phase_gates(const Params& p, int bid, int nb, h16* lds) {
;     ...
;     gemm256_epilogue(acc, m0, n0, [&](int m, int n, f4v v0, f4v v1) {
;       f4v a, b;
; #pragma unroll
;       for (int i = 0; i < 4; ++i) { a[i] = sigmoid_(v0[i]); b[i] = sigmoid_(v1[i]); }
;       st_h4(&G[(size_t)m * 4096 + n], a); st_h4(&G[(size_t)m * 4096 + n + 32], b);
;     });
	v_mul_f32_e32 v101, 0xbfb8aa3b, v101
	v_exp_f32_e32 v98, v98
	v_exp_f32_e32 v99, v99
	v_exp_f32_e32 v100, v100
	v_exp_f32_e32 v101, v101
	v_add_f32_e32 v98, 1.0, v98
	v_add_f32_e32 v99, 1.0, v99
	v_add_f32_e32 v100, 1.0, v100
	v_add_f32_e32 v101, 1.0, v101
	v_rcp_f32_e32 v98, v98
	v_rcp_f32_e32 v99, v99
	v_rcp_f32_e32 v100, v100
	v_rcp_f32_e32 v101, v101
	v_cvt_pk_f16_f32 v140, v98, v99
	v_cvt_pk_f16_f32 v141, v100, v101
	ds_write_b64 v130, v[140:141] offset:64
	v_mul_f32_e32 v118, 0xbfb8aa3b, v118
	v_mul_f32_e32 v119, 0xbfb8aa3b, v119
	v_mul_f32_e32 v120, 0xbfb8aa3b, v120
	v_mul_f32_e32 v121, 0xbfb8aa3b, v121
	v_exp_f32_e32 v118, v118
	v_exp_f32_e32 v119, v119
	v_exp_f32_e32 v120, v120
	v_exp_f32_e32 v121, v121
	v_add_f32_e32 v118, 1.0, v118
	v_add_f32_e32 v119, 1.0, v119
	v_add_f32_e32 v120, 1.0, v120
	v_add_f32_e32 v121, 1.0, v121
	v_rcp_f32_e32 v118, v118
	v_rcp_f32_e32 v119, v119
	v_rcp_f32_e32 v120, v120
	v_rcp_f32_e32 v121, v121
	v_cvt_pk_f16_f32 v142, v118, v119
	v_cvt_pk_f16_f32 v143, v120, v121
	ds_write_b64 v130, v[142:143] offset:16
	v_mul_f32_e32 v102, 0xbfb8aa3b, v102
	v_mul_f32_e32 v103, 0xbfb8aa3b, v103
	v_mul_f32_e32 v104, 0xbfb8aa3b, v104
	v_mul_f32_e32 v105, 0xbfb8aa3b, v105
	v_exp_f32_e32 v102, v102
	v_exp_f32_e32 v103, v103
	v_exp_f32_e32 v104, v104
	v_exp_f32_e32 v105, v105
	v_add_f32_e32 v102, 1.0, v102
	v_add_f32_e32 v103, 1.0, v103
	v_add_f32_e32 v104, 1.0, v104
	v_add_f32_e32 v105, 1.0, v105
	v_rcp_f32_e32 v102, v102
	v_rcp_f32_e32 v103, v103
	v_rcp_f32_e32 v104, v104
	v_rcp_f32_e32 v105, v105
	v_cvt_pk_f16_f32 v144, v102, v103
	v_cvt_pk_f16_f32 v145, v104, v105
	ds_write_b64 v130, v[144:145] offset:80
	v_mul_f32_e32 v122, 0xbfb8aa3b, v122
	v_mul_f32_e32 v123, 0xbfb8aa3b, v123
	v_mul_f32_e32 v124, 0xbfb8aa3b, v124
	v_mul_f32_e32 v125, 0xbfb8aa3b, v125
	v_exp_f32_e32 v122, v122
	v_exp_f32_e32 v123, v123
	v_exp_f32_e32 v124, v124
	v_exp_f32_e32 v125, v125
	v_add_f32_e32 v122, 1.0, v122
	v_add_f32_e32 v123, 1.0, v123
	v_add_f32_e32 v124, 1.0, v124
	v_add_f32_e32 v125, 1.0, v125
	v_rcp_f32_e32 v122, v122
	v_rcp_f32_e32 v123, v123
	v_rcp_f32_e32 v124, v124
	v_rcp_f32_e32 v125, v125
	v_cvt_pk_f16_f32 v138, v122, v123
	v_cvt_pk_f16_f32 v139, v124, v125
	ds_write_b64 v130, v[138:139] offset:32
	v_mul_f32_e32 v106, 0xbfb8aa3b, v106
	v_mul_f32_e32 v107, 0xbfb8aa3b, v107
	v_mul_f32_e32 v108, 0xbfb8aa3b, v108
	v_mul_f32_e32 v109, 0xbfb8aa3b, v109
	v_exp_f32_e32 v106, v106
	v_exp_f32_e32 v107, v107
	v_exp_f32_e32 v108, v108
	v_exp_f32_e32 v109, v109
	v_add_f32_e32 v106, 1.0, v106
	v_add_f32_e32 v107, 1.0, v107
	v_add_f32_e32 v108, 1.0, v108
	v_add_f32_e32 v109, 1.0, v109
	v_rcp_f32_e32 v106, v106
	v_rcp_f32_e32 v107, v107
	v_rcp_f32_e32 v108, v108
	v_rcp_f32_e32 v109, v109
	v_cvt_pk_f16_f32 v140, v106, v107
	v_cvt_pk_f16_f32 v141, v108, v109
	ds_write_b64 v130, v[140:141] offset:96
	v_mul_f32_e32 v126, 0xbfb8aa3b, v126
	v_mul_f32_e32 v127, 0xbfb8aa3b, v127
	v_mul_f32_e32 v128, 0xbfb8aa3b, v128
	v_mul_f32_e32 v129, 0xbfb8aa3b, v129
	v_exp_f32_e32 v126, v126
	v_exp_f32_e32 v127, v127
	v_exp_f32_e32 v128, v128
	v_exp_f32_e32 v129, v129
	v_add_f32_e32 v126, 1.0, v126
	v_add_f32_e32 v127, 1.0, v127
	v_add_f32_e32 v128, 1.0, v128
	v_add_f32_e32 v129, 1.0, v129
	v_rcp_f32_e32 v126, v126
	v_rcp_f32_e32 v127, v127
	v_rcp_f32_e32 v128, v128
	v_rcp_f32_e32 v129, v129
	v_cvt_pk_f16_f32 v142, v126, v127
	v_cvt_pk_f16_f32 v143, v128, v129
	ds_write_b64 v130, v[142:143] offset:48
	v_mul_f32_e32 v110, 0xbfb8aa3b, v110
	v_mul_f32_e32 v111, 0xbfb8aa3b, v111
	v_mul_f32_e32 v112, 0xbfb8aa3b, v112
	v_mul_f32_e32 v113, 0xbfb8aa3b, v113
	v_exp_f32_e32 v110, v110
	v_exp_f32_e32 v111, v111
	v_exp_f32_e32 v112, v112
	v_exp_f32_e32 v113, v113
	v_add_f32_e32 v110, 1.0, v110
	v_add_f32_e32 v111, 1.0, v111
	v_add_f32_e32 v112, 1.0, v112
	v_add_f32_e32 v113, 1.0, v113
	v_rcp_f32_e32 v110, v110
	v_rcp_f32_e32 v111, v111
	v_rcp_f32_e32 v112, v112
	v_rcp_f32_e32 v113, v113
	v_cvt_pk_f16_f32 v144, v110, v111
	v_cvt_pk_f16_f32 v145, v112, v113
	ds_write_b64 v130, v[144:145] offset:112
	v_mul_f32_e32 v82, 0xbfb8aa3b, v82
	v_mul_f32_e32 v83, 0xbfb8aa3b, v83
	v_mul_f32_e32 v84, 0xbfb8aa3b, v84
	v_mul_f32_e32 v85, 0xbfb8aa3b, v85
	v_exp_f32_e32 v82, v82
	v_exp_f32_e32 v83, v83
	v_exp_f32_e32 v84, v84
	v_exp_f32_e32 v85, v85
	v_add_f32_e32 v82, 1.0, v82
	v_add_f32_e32 v83, 1.0, v83
	v_add_f32_e32 v84, 1.0, v84
	v_add_f32_e32 v85, 1.0, v85
	v_rcp_f32_e32 v82, v82
	v_rcp_f32_e32 v83, v83
	v_rcp_f32_e32 v84, v84
	v_rcp_f32_e32 v85, v85
	v_cvt_pk_f16_f32 v138, v82, v83
	v_cvt_pk_f16_f32 v139, v84, v85
	ds_write_b64 v130, v[138:139] offset:4608
	v_mul_f32_e32 v66, 0xbfb8aa3b, v66
	v_mul_f32_e32 v67, 0xbfb8aa3b, v67
	v_mul_f32_e32 v68, 0xbfb8aa3b, v68
	v_mul_f32_e32 v69, 0xbfb8aa3b, v69
	v_exp_f32_e32 v66, v66
	v_exp_f32_e32 v67, v67
	v_exp_f32_e32 v68, v68
	v_exp_f32_e32 v69, v69
	v_add_f32_e32 v66, 1.0, v66
	v_add_f32_e32 v67, 1.0, v67
	v_add_f32_e32 v68, 1.0, v68
	v_add_f32_e32 v69, 1.0, v69
	v_rcp_f32_e32 v66, v66
	v_rcp_f32_e32 v67, v67
	v_rcp_f32_e32 v68, v68
	v_rcp_f32_e32 v69, v69
	v_cvt_pk_f16_f32 v140, v66, v67
	v_cvt_pk_f16_f32 v141, v68, v69
	ds_write_b64 v130, v[140:141] offset:4672
	v_mul_f32_e32 v86, 0xbfb8aa3b, v86
	v_mul_f32_e32 v87, 0xbfb8aa3b, v87
	v_mul_f32_e32 v88, 0xbfb8aa3b, v88
	v_mul_f32_e32 v89, 0xbfb8aa3b, v89
	v_exp_f32_e32 v86, v86
	v_exp_f32_e32 v87, v87
	v_exp_f32_e32 v88, v88
	v_exp_f32_e32 v89, v89
	v_add_f32_e32 v86, 1.0, v86
	v_add_f32_e32 v87, 1.0, v87
	v_add_f32_e32 v88, 1.0, v88
	v_add_f32_e32 v89, 1.0, v89
	v_rcp_f32_e32 v86, v86
	v_rcp_f32_e32 v87, v87
	v_rcp_f32_e32 v88, v88
	v_rcp_f32_e32 v89, v89
	v_cvt_pk_f16_f32 v142, v86, v87
; DI int otid512() { int t = threadIdx.x; asm volatile("" : "+v"(t)); return t; }
; DI float sigmoid_(float x) { return 1.f / (1.f + __expf(-x)); }
; template <class Epi>
; DI void gemm256_epilogue(f16v (&acc)[4][2], int m0, int n0, Epi epi) {
;   const int tid = otid512(), lane = tid & 63, wv = tid >> 6, wm = wv >> 2, wn = wv & 3, h = lane >> 5;
; #pragma unroll
;   for (int i = 0; i < 4; ++i) {
;     const int m = m0 + wm * 128 + i * 32 + (lane & 31);
; #pragma unroll
;     for (int g = 0; g < 4; ++g) {
;       const int n = n0 + wn * 64 + 8 * g + 4 * h;
;       f4v v0 = {acc[i][0][4 * g], acc[i][0][4 * g + 1], acc[i][0][4 * g + 2], acc[i][0][4 * g + 3]};
;       f4v v1 = {acc[i][1][4 * g], acc[i][1][4 * g + 1], acc[i][1][4 * g + 2], acc[i][1][4 * g + 3]};
;       epi(m, n, v0, v1);
;     }
;   }
; }
; DI void phase_gates(const Params& p, int bid, int nb, h16* lds) {
;     ...
;     gemm256_epilogue(acc, m0, n0, [&](int m, int n, f4v v0, f4v v1) {
;       f4v a, b;
; #pragma unroll
;       for (int i = 0; i < 4; ++i) { a[i] = sigmoid_(v0[i]); b[i] = sigmoid_(v1[i]); }
;       st_h4(&G[(size_t)m * 4096 + n], a); st_h4(&G[(size_t)m * 4096 + n + 32], b);
;     });
	v_cvt_pk_f16_f32 v143, v88, v89
	ds_write_b64 v130, v[142:143] offset:4624
	v_mul_f32_e32 v70, 0xbfb8aa3b, v70
	v_mul_f32_e32 v71, 0xbfb8aa3b, v71
	v_mul_f32_e32 v72, 0xbfb8aa3b, v72
	v_mul_f32_e32 v73, 0xbfb8aa3b, v73
	v_exp_f32_e32 v70, v70
	v_exp_f32_e32 v71, v71
	v_exp_f32_e32 v72, v72
	v_exp_f32_e32 v73, v73
	v_add_f32_e32 v70, 1.0, v70
	v_add_f32_e32 v71, 1.0, v71
	v_add_f32_e32 v72, 1.0, v72
	v_add_f32_e32 v73, 1.0, v73
	v_rcp_f32_e32 v70, v70
	v_rcp_f32_e32 v71, v71
	v_rcp_f32_e32 v72, v72
	v_rcp_f32_e32 v73, v73
	v_cvt_pk_f16_f32 v144, v70, v71
	v_cvt_pk_f16_f32 v145, v72, v73
	ds_write_b64 v130, v[144:145] offset:4688
	v_mul_f32_e32 v90, 0xbfb8aa3b, v90
	v_mul_f32_e32 v91, 0xbfb8aa3b, v91
	v_mul_f32_e32 v92, 0xbfb8aa3b, v92
	v_mul_f32_e32 v93, 0xbfb8aa3b, v93
	v_exp_f32_e32 v90, v90
	v_exp_f32_e32 v91, v91
	v_exp_f32_e32 v92, v92
	v_exp_f32_e32 v93, v93
	v_add_f32_e32 v90, 1.0, v90
	v_add_f32_e32 v91, 1.0, v91
	v_add_f32_e32 v92, 1.0, v92
	v_add_f32_e32 v93, 1.0, v93
	v_rcp_f32_e32 v90, v90
	v_rcp_f32_e32 v91, v91
	v_rcp_f32_e32 v92, v92
	v_rcp_f32_e32 v93, v93
	v_cvt_pk_f16_f32 v138, v90, v91
	v_cvt_pk_f16_f32 v139, v92, v93
	ds_write_b64 v130, v[138:139] offset:4640
	v_mul_f32_e32 v74, 0xbfb8aa3b, v74
	v_mul_f32_e32 v75, 0xbfb8aa3b, v75
	v_mul_f32_e32 v76, 0xbfb8aa3b, v76
	v_mul_f32_e32 v77, 0xbfb8aa3b, v77
	v_exp_f32_e32 v74, v74
	v_exp_f32_e32 v75, v75
	v_exp_f32_e32 v76, v76
	v_exp_f32_e32 v77, v77
	v_add_f32_e32 v74, 1.0, v74
	v_add_f32_e32 v75, 1.0, v75
	v_add_f32_e32 v76, 1.0, v76
	v_add_f32_e32 v77, 1.0, v77
	v_rcp_f32_e32 v74, v74
	v_rcp_f32_e32 v75, v75
	v_rcp_f32_e32 v76, v76
	v_rcp_f32_e32 v77, v77
	v_cvt_pk_f16_f32 v140, v74, v75
	v_cvt_pk_f16_f32 v141, v76, v77
	ds_write_b64 v130, v[140:141] offset:4704
	v_mul_f32_e32 v94, 0xbfb8aa3b, v94
	v_mul_f32_e32 v95, 0xbfb8aa3b, v95
	v_mul_f32_e32 v96, 0xbfb8aa3b, v96
	v_mul_f32_e32 v97, 0xbfb8aa3b, v97
	v_exp_f32_e32 v94, v94
	v_exp_f32_e32 v95, v95
	v_exp_f32_e32 v96, v96
	v_exp_f32_e32 v97, v97
	v_add_f32_e32 v94, 1.0, v94
	v_add_f32_e32 v95, 1.0, v95
	v_add_f32_e32 v96, 1.0, v96
	v_add_f32_e32 v97, 1.0, v97
	v_rcp_f32_e32 v94, v94
	v_rcp_f32_e32 v95, v95
	v_rcp_f32_e32 v96, v96
	v_rcp_f32_e32 v97, v97
	v_cvt_pk_f16_f32 v142, v94, v95
	v_cvt_pk_f16_f32 v143, v96, v97
	ds_write_b64 v130, v[142:143] offset:4656
	v_mul_f32_e32 v78, 0xbfb8aa3b, v78
	v_mul_f32_e32 v79, 0xbfb8aa3b, v79
	v_mul_f32_e32 v80, 0xbfb8aa3b, v80
	v_mul_f32_e32 v81, 0xbfb8aa3b, v81
	v_exp_f32_e32 v78, v78
	v_exp_f32_e32 v79, v79
	v_exp_f32_e32 v80, v80
	v_exp_f32_e32 v81, v81
	v_add_f32_e32 v78, 1.0, v78
	v_add_f32_e32 v79, 1.0, v79
	v_add_f32_e32 v80, 1.0, v80
	v_add_f32_e32 v81, 1.0, v81
	v_rcp_f32_e32 v78, v78
	v_rcp_f32_e32 v79, v79
	v_rcp_f32_e32 v80, v80
	v_rcp_f32_e32 v81, v81
	v_cvt_pk_f16_f32 v144, v78, v79
	v_cvt_pk_f16_f32 v145, v80, v81
	ds_write_b64 v130, v[144:145] offset:4720
	v_mul_f32_e32 v50, 0xbfb8aa3b, v50
	v_mul_f32_e32 v51, 0xbfb8aa3b, v51
	v_mul_f32_e32 v52, 0xbfb8aa3b, v52
	v_mul_f32_e32 v53, 0xbfb8aa3b, v53
	v_exp_f32_e32 v50, v50
	v_exp_f32_e32 v51, v51
	v_exp_f32_e32 v52, v52
	v_exp_f32_e32 v53, v53
	v_add_f32_e32 v50, 1.0, v50
	v_add_f32_e32 v51, 1.0, v51
	v_add_f32_e32 v52, 1.0, v52
	v_add_f32_e32 v53, 1.0, v53
	v_rcp_f32_e32 v50, v50
	v_rcp_f32_e32 v51, v51
	v_rcp_f32_e32 v52, v52
	v_rcp_f32_e32 v53, v53
	v_cvt_pk_f16_f32 v138, v50, v51
	v_cvt_pk_f16_f32 v139, v52, v53
	ds_write_b64 v130, v[138:139] offset:9216
	v_mul_f32_e32 v34, 0xbfb8aa3b, v34
	v_mul_f32_e32 v35, 0xbfb8aa3b, v35
	v_mul_f32_e32 v36, 0xbfb8aa3b, v36
	v_mul_f32_e32 v37, 0xbfb8aa3b, v37
	v_exp_f32_e32 v34, v34
	v_exp_f32_e32 v35, v35
	v_exp_f32_e32 v36, v36
	v_exp_f32_e32 v37, v37
	v_add_f32_e32 v34, 1.0, v34
	v_add_f32_e32 v35, 1.0, v35
	v_add_f32_e32 v36, 1.0, v36
	v_add_f32_e32 v37, 1.0, v37
	v_rcp_f32_e32 v34, v34
	v_rcp_f32_e32 v35, v35
	v_rcp_f32_e32 v36, v36
	v_rcp_f32_e32 v37, v37
	v_cvt_pk_f16_f32 v140, v34, v35
	v_cvt_pk_f16_f32 v141, v36, v37
	ds_write_b64 v130, v[140:141] offset:9280
	v_mul_f32_e32 v54, 0xbfb8aa3b, v54
	v_mul_f32_e32 v55, 0xbfb8aa3b, v55
	v_mul_f32_e32 v56, 0xbfb8aa3b, v56
	v_mul_f32_e32 v57, 0xbfb8aa3b, v57
	v_exp_f32_e32 v54, v54
	v_exp_f32_e32 v55, v55
	v_exp_f32_e32 v56, v56
	v_exp_f32_e32 v57, v57
	v_add_f32_e32 v54, 1.0, v54
	v_add_f32_e32 v55, 1.0, v55
	v_add_f32_e32 v56, 1.0, v56
	v_add_f32_e32 v57, 1.0, v57
	v_rcp_f32_e32 v54, v54
	v_rcp_f32_e32 v55, v55
	v_rcp_f32_e32 v56, v56
	v_rcp_f32_e32 v57, v57
	v_cvt_pk_f16_f32 v142, v54, v55
	v_cvt_pk_f16_f32 v143, v56, v57
	ds_write_b64 v130, v[142:143] offset:9232
	v_mul_f32_e32 v38, 0xbfb8aa3b, v38
	v_mul_f32_e32 v39, 0xbfb8aa3b, v39
	v_mul_f32_e32 v40, 0xbfb8aa3b, v40
	v_mul_f32_e32 v41, 0xbfb8aa3b, v41
	v_exp_f32_e32 v38, v38
	v_exp_f32_e32 v39, v39
	v_exp_f32_e32 v40, v40
	v_exp_f32_e32 v41, v41
	v_add_f32_e32 v38, 1.0, v38
	v_add_f32_e32 v39, 1.0, v39
	v_add_f32_e32 v40, 1.0, v40
	v_add_f32_e32 v41, 1.0, v41
	v_rcp_f32_e32 v38, v38
	v_rcp_f32_e32 v39, v39
	v_rcp_f32_e32 v40, v40
	v_rcp_f32_e32 v41, v41
	v_cvt_pk_f16_f32 v144, v38, v39
	v_cvt_pk_f16_f32 v145, v40, v41
	ds_write_b64 v130, v[144:145] offset:9296
	v_mul_f32_e32 v58, 0xbfb8aa3b, v58
	v_mul_f32_e32 v59, 0xbfb8aa3b, v59
	v_mul_f32_e32 v60, 0xbfb8aa3b, v60
	v_mul_f32_e32 v61, 0xbfb8aa3b, v61
	v_exp_f32_e32 v58, v58
	v_exp_f32_e32 v59, v59
	v_exp_f32_e32 v60, v60
	v_exp_f32_e32 v61, v61
	v_add_f32_e32 v58, 1.0, v58
	v_add_f32_e32 v59, 1.0, v59
	v_add_f32_e32 v60, 1.0, v60
	v_add_f32_e32 v61, 1.0, v61
	v_rcp_f32_e32 v58, v58
	v_rcp_f32_e32 v59, v59
	v_rcp_f32_e32 v60, v60
	v_rcp_f32_e32 v61, v61
	v_cvt_pk_f16_f32 v138, v58, v59
	v_cvt_pk_f16_f32 v139, v60, v61
; DI int otid512() { int t = threadIdx.x; asm volatile("" : "+v"(t)); return t; }
; DI float sigmoid_(float x) { return 1.f / (1.f + __expf(-x)); }
; template <class Epi>
; DI void gemm256_epilogue(f16v (&acc)[4][2], int m0, int n0, Epi epi) {
;   const int tid = otid512(), lane = tid & 63, wv = tid >> 6, wm = wv >> 2, wn = wv & 3, h = lane >> 5;
; #pragma unroll
;   for (int i = 0; i < 4; ++i) {
;     const int m = m0 + wm * 128 + i * 32 + (lane & 31);
; #pragma unroll
;     for (int g = 0; g < 4; ++g) {
;       const int n = n0 + wn * 64 + 8 * g + 4 * h;
;       f4v v0 = {acc[i][0][4 * g], acc[i][0][4 * g + 1], acc[i][0][4 * g + 2], acc[i][0][4 * g + 3]};
;       f4v v1 = {acc[i][1][4 * g], acc[i][1][4 * g + 1], acc[i][1][4 * g + 2], acc[i][1][4 * g + 3]};
;       epi(m, n, v0, v1);
;     }
;   }
; }
; DI void phase_gates(const Params& p, int bid, int nb, h16* lds) {
;     ...
;     gemm256_epilogue(acc, m0, n0, [&](int m, int n, f4v v0, f4v v1) {
;       f4v a, b;
; #pragma unroll
;       for (int i = 0; i < 4; ++i) { a[i] = sigmoid_(v0[i]); b[i] = sigmoid_(v1[i]); }
;       st_h4(&G[(size_t)m * 4096 + n], a); st_h4(&G[(size_t)m * 4096 + n + 32], b);
;     });
	ds_write_b64 v130, v[138:139] offset:9248
	v_mul_f32_e32 v42, 0xbfb8aa3b, v42
	v_mul_f32_e32 v43, 0xbfb8aa3b, v43
	v_mul_f32_e32 v44, 0xbfb8aa3b, v44
	v_mul_f32_e32 v45, 0xbfb8aa3b, v45
	v_exp_f32_e32 v42, v42
	v_exp_f32_e32 v43, v43
	v_exp_f32_e32 v44, v44
	v_exp_f32_e32 v45, v45
	v_add_f32_e32 v42, 1.0, v42
	v_add_f32_e32 v43, 1.0, v43
	v_add_f32_e32 v44, 1.0, v44
	v_add_f32_e32 v45, 1.0, v45
	v_rcp_f32_e32 v42, v42
	v_rcp_f32_e32 v43, v43
	v_rcp_f32_e32 v44, v44
	v_rcp_f32_e32 v45, v45
	v_cvt_pk_f16_f32 v140, v42, v43
	v_cvt_pk_f16_f32 v141, v44, v45
	ds_write_b64 v130, v[140:141] offset:9312
	v_mul_f32_e32 v62, 0xbfb8aa3b, v62
	v_mul_f32_e32 v63, 0xbfb8aa3b, v63
	v_mul_f32_e32 v64, 0xbfb8aa3b, v64
	v_mul_f32_e32 v65, 0xbfb8aa3b, v65
	v_exp_f32_e32 v62, v62
	v_exp_f32_e32 v63, v63
	v_exp_f32_e32 v64, v64
	v_exp_f32_e32 v65, v65
	v_add_f32_e32 v62, 1.0, v62
	v_add_f32_e32 v63, 1.0, v63
	v_add_f32_e32 v64, 1.0, v64
	v_add_f32_e32 v65, 1.0, v65
	v_rcp_f32_e32 v62, v62
	v_rcp_f32_e32 v63, v63
	v_rcp_f32_e32 v64, v64
	v_rcp_f32_e32 v65, v65
	v_cvt_pk_f16_f32 v142, v62, v63
	v_cvt_pk_f16_f32 v143, v64, v65
	ds_write_b64 v130, v[142:143] offset:9264
	v_mul_f32_e32 v46, 0xbfb8aa3b, v46
	v_mul_f32_e32 v47, 0xbfb8aa3b, v47
	v_mul_f32_e32 v48, 0xbfb8aa3b, v48
	v_mul_f32_e32 v49, 0xbfb8aa3b, v49
	v_exp_f32_e32 v46, v46
	v_exp_f32_e32 v47, v47
	v_exp_f32_e32 v48, v48
	v_exp_f32_e32 v49, v49
	v_add_f32_e32 v46, 1.0, v46
	v_add_f32_e32 v47, 1.0, v47
	v_add_f32_e32 v48, 1.0, v48
	v_add_f32_e32 v49, 1.0, v49
	v_rcp_f32_e32 v46, v46
	v_rcp_f32_e32 v47, v47
	v_rcp_f32_e32 v48, v48
	v_rcp_f32_e32 v49, v49
	v_cvt_pk_f16_f32 v144, v46, v47
	v_cvt_pk_f16_f32 v145, v48, v49
	ds_write_b64 v130, v[144:145] offset:9328
	v_mul_f32_e32 v18, 0xbfb8aa3b, v18
	v_mul_f32_e32 v19, 0xbfb8aa3b, v19
	v_mul_f32_e32 v20, 0xbfb8aa3b, v20
	v_mul_f32_e32 v21, 0xbfb8aa3b, v21
	v_exp_f32_e32 v18, v18
	v_exp_f32_e32 v19, v19
	v_exp_f32_e32 v20, v20
	v_exp_f32_e32 v21, v21
	v_add_f32_e32 v18, 1.0, v18
	v_add_f32_e32 v19, 1.0, v19
	v_add_f32_e32 v20, 1.0, v20
	v_add_f32_e32 v21, 1.0, v21
	v_rcp_f32_e32 v18, v18
	v_rcp_f32_e32 v19, v19
	v_rcp_f32_e32 v20, v20
	v_rcp_f32_e32 v21, v21
	v_cvt_pk_f16_f32 v138, v18, v19
	v_cvt_pk_f16_f32 v139, v20, v21
	ds_write_b64 v130, v[138:139] offset:13824
	v_mul_f32_e32 v2, 0xbfb8aa3b, v2
	v_mul_f32_e32 v3, 0xbfb8aa3b, v3
	v_mul_f32_e32 v4, 0xbfb8aa3b, v4
	v_mul_f32_e32 v5, 0xbfb8aa3b, v5
	v_exp_f32_e32 v2, v2
	v_exp_f32_e32 v3, v3
	v_exp_f32_e32 v4, v4
	v_exp_f32_e32 v5, v5
	v_add_f32_e32 v2, 1.0, v2
	v_add_f32_e32 v3, 1.0, v3
	v_add_f32_e32 v4, 1.0, v4
	v_add_f32_e32 v5, 1.0, v5
	v_rcp_f32_e32 v2, v2
	v_rcp_f32_e32 v3, v3
	v_rcp_f32_e32 v4, v4
	v_rcp_f32_e32 v5, v5
	v_cvt_pk_f16_f32 v140, v2, v3
	v_cvt_pk_f16_f32 v141, v4, v5
	ds_write_b64 v130, v[140:141] offset:13888
	v_mul_f32_e32 v22, 0xbfb8aa3b, v22
	v_mul_f32_e32 v23, 0xbfb8aa3b, v23
	v_mul_f32_e32 v24, 0xbfb8aa3b, v24
	v_mul_f32_e32 v25, 0xbfb8aa3b, v25
	v_exp_f32_e32 v22, v22
	v_exp_f32_e32 v23, v23
	v_exp_f32_e32 v24, v24
	v_exp_f32_e32 v25, v25
	v_add_f32_e32 v22, 1.0, v22
	v_add_f32_e32 v23, 1.0, v23
	v_add_f32_e32 v24, 1.0, v24
	v_add_f32_e32 v25, 1.0, v25
	v_rcp_f32_e32 v22, v22
	v_rcp_f32_e32 v23, v23
	v_rcp_f32_e32 v24, v24
	v_rcp_f32_e32 v25, v25
	v_cvt_pk_f16_f32 v142, v22, v23
	v_cvt_pk_f16_f32 v143, v24, v25
	ds_write_b64 v130, v[142:143] offset:13840
	v_mul_f32_e32 v6, 0xbfb8aa3b, v6
	v_mul_f32_e32 v7, 0xbfb8aa3b, v7
	v_mul_f32_e32 v8, 0xbfb8aa3b, v8
	v_mul_f32_e32 v9, 0xbfb8aa3b, v9
	v_exp_f32_e32 v6, v6
	v_exp_f32_e32 v7, v7
	v_exp_f32_e32 v8, v8
	v_exp_f32_e32 v9, v9
	v_add_f32_e32 v6, 1.0, v6
	v_add_f32_e32 v7, 1.0, v7
	v_add_f32_e32 v8, 1.0, v8
	v_add_f32_e32 v9, 1.0, v9
	v_rcp_f32_e32 v6, v6
	v_rcp_f32_e32 v7, v7
	v_rcp_f32_e32 v8, v8
	v_rcp_f32_e32 v9, v9
	v_cvt_pk_f16_f32 v144, v6, v7
	v_cvt_pk_f16_f32 v145, v8, v9
	ds_write_b64 v130, v[144:145] offset:13904
	v_mul_f32_e32 v26, 0xbfb8aa3b, v26
	v_mul_f32_e32 v27, 0xbfb8aa3b, v27
	v_mul_f32_e32 v28, 0xbfb8aa3b, v28
	v_mul_f32_e32 v29, 0xbfb8aa3b, v29
	v_exp_f32_e32 v26, v26
	v_exp_f32_e32 v27, v27
	v_exp_f32_e32 v28, v28
	v_exp_f32_e32 v29, v29
	v_add_f32_e32 v26, 1.0, v26
	v_add_f32_e32 v27, 1.0, v27
	v_add_f32_e32 v28, 1.0, v28
	v_add_f32_e32 v29, 1.0, v29
	v_rcp_f32_e32 v26, v26
	v_rcp_f32_e32 v27, v27
	v_rcp_f32_e32 v28, v28
	v_rcp_f32_e32 v29, v29
	v_cvt_pk_f16_f32 v138, v26, v27
	v_cvt_pk_f16_f32 v139, v28, v29
	ds_write_b64 v130, v[138:139] offset:13856
	v_mul_f32_e32 v10, 0xbfb8aa3b, v10
	v_mul_f32_e32 v11, 0xbfb8aa3b, v11
	v_mul_f32_e32 v12, 0xbfb8aa3b, v12
	v_mul_f32_e32 v13, 0xbfb8aa3b, v13
	v_exp_f32_e32 v10, v10
	v_exp_f32_e32 v11, v11
	v_exp_f32_e32 v12, v12
	v_exp_f32_e32 v13, v13
	v_add_f32_e32 v10, 1.0, v10
	v_add_f32_e32 v11, 1.0, v11
	v_add_f32_e32 v12, 1.0, v12
	v_add_f32_e32 v13, 1.0, v13
	v_rcp_f32_e32 v10, v10
	v_rcp_f32_e32 v11, v11
	v_rcp_f32_e32 v12, v12
	v_rcp_f32_e32 v13, v13
	v_cvt_pk_f16_f32 v140, v10, v11
	v_cvt_pk_f16_f32 v141, v12, v13
	ds_write_b64 v130, v[140:141] offset:13920
	v_mul_f32_e32 v30, 0xbfb8aa3b, v30
	v_mul_f32_e32 v31, 0xbfb8aa3b, v31
	v_mul_f32_e32 v32, 0xbfb8aa3b, v32
	v_mul_f32_e32 v33, 0xbfb8aa3b, v33
	v_exp_f32_e32 v30, v30
	v_exp_f32_e32 v31, v31
	v_exp_f32_e32 v32, v32
	v_exp_f32_e32 v33, v33
	v_add_f32_e32 v30, 1.0, v30
	v_add_f32_e32 v31, 1.0, v31
	v_add_f32_e32 v32, 1.0, v32
	v_add_f32_e32 v33, 1.0, v33
	v_rcp_f32_e32 v30, v30
	v_rcp_f32_e32 v31, v31
	v_rcp_f32_e32 v32, v32
	v_rcp_f32_e32 v33, v33
	v_cvt_pk_f16_f32 v142, v30, v31
	v_cvt_pk_f16_f32 v143, v32, v33
	ds_write_b64 v130, v[142:143] offset:13872
	v_mul_f32_e32 v14, 0xbfb8aa3b, v14
	v_mul_f32_e32 v15, 0xbfb8aa3b, v15
	v_mul_f32_e32 v16, 0xbfb8aa3b, v16
	v_mul_f32_e32 v17, 0xbfb8aa3b, v17
	v_exp_f32_e32 v14, v14
	v_exp_f32_e32 v15, v15
	v_exp_f32_e32 v16, v16
	v_exp_f32_e32 v17, v17
	v_add_f32_e32 v14, 1.0, v14
	v_add_f32_e32 v15, 1.0, v15
	v_add_f32_e32 v16, 1.0, v16
	v_add_f32_e32 v17, 1.0, v17
	v_rcp_f32_e32 v14, v14
	v_rcp_f32_e32 v15, v15
	v_rcp_f32_e32 v16, v16
	v_rcp_f32_e32 v17, v17
	v_cvt_pk_f16_f32 v144, v14, v15
	v_cvt_pk_f16_f32 v145, v16, v17
	ds_write_b64 v130, v[144:145] offset:13936
	ds_read_b128 v[150:153], v131 offset:0
	ds_read_b128 v[154:157], v131 offset:1152
	ds_read_b128 v[158:161], v131 offset:2304
	ds_read_b128 v[162:165], v131 offset:3456
	ds_read_b128 v[216:219], v131 offset:4608
	ds_read_b128 v[220:223], v131 offset:5760
	ds_read_b128 v[224:227], v131 offset:6912
	ds_read_b128 v[228:231], v131 offset:8064
	s_waitcnt lgkmcnt(7)
; DI float sigmoid_(float x) { return 1.f / (1.f + __expf(-x)); }
; DI void phase_gates(const Params& p, int bid, int nb, h16* lds) {
;     ...
;   for (int u = bid; u < 64 * 16; u += nb) {
;     const int m0 = (u >> 4) * 256, n0 = (u & 15) * 256;
;     f16v acc[4][2]; acc256_zero(acc);
;     gemm256_main<false>(x16, DM, nullptr, m0, wg, 1024, n0, 1024, lds, acc);
;     gemm256_epilogue(acc, m0, n0, [&](int m, int n, f4v v0, f4v v1) {
;       f4v a, b;
; #pragma unroll
;       for (int i = 0; i < 4; ++i) { a[i] = sigmoid_(v0[i]); b[i] = sigmoid_(v1[i]); }
;       st_h4(&G[(size_t)m * 4096 + n], a); st_h4(&G[(size_t)m * 4096 + n + 32], b);
;     });
	global_store_dwordx4 v[132:133], v[150:153], off
	v_lshl_add_u64 v[132:133], v[132:133], 0, s[76:77]
	s_waitcnt lgkmcnt(6)
	global_store_dwordx4 v[132:133], v[154:157], off
	v_lshl_add_u64 v[132:133], v[132:133], 0, s[76:77]
	s_waitcnt lgkmcnt(5)
	global_store_dwordx4 v[132:133], v[158:161], off
	v_lshl_add_u64 v[132:133], v[132:133], 0, s[76:77]
	s_waitcnt lgkmcnt(4)
	global_store_dwordx4 v[132:133], v[162:165], off
	v_lshl_add_u64 v[132:133], v[132:133], 0, s[76:77]
	s_waitcnt lgkmcnt(3)
	global_store_dwordx4 v[132:133], v[216:219], off
	v_lshl_add_u64 v[132:133], v[132:133], 0, s[76:77]
	s_waitcnt lgkmcnt(2)
	global_store_dwordx4 v[132:133], v[220:223], off
	v_lshl_add_u64 v[132:133], v[132:133], 0, s[76:77]
	s_waitcnt lgkmcnt(1)
	global_store_dwordx4 v[132:133], v[224:227], off
	v_lshl_add_u64 v[132:133], v[132:133], 0, s[76:77]
	s_waitcnt lgkmcnt(0)
	global_store_dwordx4 v[132:133], v[228:231], off
	v_lshl_add_u64 v[132:133], v[132:133], 0, s[76:77]
	s_nop 1
	ds_read_b128 v[150:153], v131 offset:9216
	ds_read_b128 v[154:157], v131 offset:10368
	ds_read_b128 v[158:161], v131 offset:11520
	ds_read_b128 v[162:165], v131 offset:12672
	ds_read_b128 v[216:219], v131 offset:13824
	ds_read_b128 v[220:223], v131 offset:14976
	ds_read_b128 v[224:227], v131 offset:16128
	ds_read_b128 v[228:231], v131 offset:17280
	s_waitcnt lgkmcnt(7)
	global_store_dwordx4 v[132:133], v[150:153], off
	v_lshl_add_u64 v[132:133], v[132:133], 0, s[76:77]
	s_waitcnt lgkmcnt(6)
	global_store_dwordx4 v[132:133], v[154:157], off
	v_lshl_add_u64 v[132:133], v[132:133], 0, s[76:77]
	s_waitcnt lgkmcnt(5)
	global_store_dwordx4 v[132:133], v[158:161], off
	v_lshl_add_u64 v[132:133], v[132:133], 0, s[76:77]
	s_waitcnt lgkmcnt(4)
	global_store_dwordx4 v[132:133], v[162:165], off
	v_lshl_add_u64 v[132:133], v[132:133], 0, s[76:77]
	s_waitcnt lgkmcnt(3)
	global_store_dwordx4 v[132:133], v[216:219], off
	v_lshl_add_u64 v[132:133], v[132:133], 0, s[76:77]
	s_waitcnt lgkmcnt(2)
	global_store_dwordx4 v[132:133], v[220:223], off
	v_lshl_add_u64 v[132:133], v[132:133], 0, s[76:77]
	s_waitcnt lgkmcnt(1)
	global_store_dwordx4 v[132:133], v[224:227], off
	v_lshl_add_u64 v[132:133], v[132:133], 0, s[76:77]
	s_waitcnt lgkmcnt(0)
	global_store_dwordx4 v[132:133], v[228:231], off
	v_lshl_add_u64 v[132:133], v[132:133], 0, s[76:77]
	s_cmp_eq_u32 s60, 1
	s_cbranch_scc1 .LBB0_1246
